# 16x16x32 MFMA k-loop (swizzled LDS, coalesced loader) also for the full 128x128 tiles of phase 4b and phase 5b GEMMs
# speedup vs baseline: 1.0691x; 1.0117x over previous
.LBB0_765:
	s_and_b64 vcc, exec, s[24:25]
	s_cbranch_vccz .LBB0_724
	s_ashr_i32 s14, s51, 31
	s_lshr_b32 s14, s14, 29
	s_add_i32 s14, s51, s14
	s_lshl_b32 s15, s14, 4
	s_and_b32 s14, s14, 0x1fffff8
	s_sub_i32 s14, s51, s14
	s_and_b32 s24, s15, 0xffffff80
	s_lshl_b32 s25, s14, 7
	v_add_u32_e32 v0, s24, v105
	v_add_u32_e32 v16, s25, v105
	v_ashrrev_i32_e32 v1, 31, v0
	v_ashrrev_i32_e32 v17, 31, v16
	v_lshlrev_b64 v[0:1], 11, v[0:1]
	v_lshlrev_b64 v[16:17], 11, v[16:17]
	v_lshl_add_u64 v[70:71], v[66:67], 0, v[0:1]
	v_lshl_add_u64 v[72:73], v[68:69], 0, v[16:17]
	v_readfirstlane_b32 s98, v66
	v_readfirstlane_b32 s99, v67
	v_readfirstlane_b32 s100, v68
	v_readfirstlane_b32 s101, v69
	s_lshl_b32 s15, s24, 11
	s_add_u32 s98, s98, s15
	s_addc_u32 s99, s99, 0
	s_lshl_b32 s15, s25, 11
	s_add_u32 s100, s100, s15
	s_addc_u32 s101, s101, 0
	v_lshrrev_b32_e32 v246, 3, v100
	v_and_b32_e32 v247, 7, v100
	v_bfe_u32 v244, v100, 4, 3
	v_xor_b32_e32 v244, v244, v247
	v_lshlrev_b32_e32 v244, 4, v244
	v_lshl_or_b32 v110, v246, 7, v244
	v_lshlrev_b32_e32 v245, 4, v247
	v_lshl_or_b32 v93, v246, 11, v245
	v_add_u32_e32 v94, 0x10000, v93
	v_add_u32_e32 v95, 0x20000, v93
	v_add_u32_e32 v109, 0x30000, v93
	v_and_b32_e32 v244, 15, v100
	v_bfe_u32 v245, v100, 4, 2
	v_bfe_u32 v246, v100, 1, 3
	v_xor_b32_e32 v247, v245, v246
	v_lshlrev_b32_e32 v247, 4, v247
	v_lshl_or_b32 v247, v244, 7, v247
	v_bfe_u32 v246, v100, 7, 1
	v_lshl_add_u32 v239, v246, 13, v247
	v_xor_b32_e32 v240, 64, v239
	v_bfe_u32 v246, v100, 6, 1
	v_lshl_add_u32 v241, v246, 13, v247
	v_add_u32_e32 v241, 0x4000, v241
	v_xor_b32_e32 v242, 64, v241
	v_bfe_u32 v247, v100, 7, 1
	v_lshlrev_b32_e32 v247, 6, v247
	v_lshl_add_u32 v247, v245, 2, v247
	v_mul_u32_u24_e32 v247, 0x84, v247
	v_lshl_add_u32 v247, v246, 6, v247
	v_add_u32_e32 v247, v247, v244
	v_lshlrev_b32_e32 v243, 2, v247
	global_load_dwordx4 v[178:181], v93, s[98:99]
	global_load_dwordx4 v[182:185], v94, s[98:99]
	global_load_dwordx4 v[186:189], v95, s[98:99]
	global_load_dwordx4 v[190:193], v109, s[98:99]
	global_load_dwordx4 v[220:223], v93, s[100:101]
	global_load_dwordx4 v[224:227], v94, s[100:101]
	global_load_dwordx4 v[228:231], v95, s[100:101]
	global_load_dwordx4 v[232:235], v109, s[100:101]
	v_readlane_b32 s52, v238, 32
	v_readlane_b32 s54, v238, 34
	v_readlane_b32 s55, v238, 35
	s_mov_b32 s14, 0
	v_readlane_b32 s53, v238, 33
	v_readlane_b32 s56, v238, 36
	v_readlane_b32 s57, v238, 37
	v_readlane_b32 s58, v238, 38
	v_readlane_b32 s59, v238, 39
	v_readlane_b32 s60, v238, 40
	v_readlane_b32 s61, v238, 41
	v_readlane_b32 s62, v238, 42
	v_readlane_b32 s63, v238, 43
	v_readlane_b32 s64, v238, 44
	v_readlane_b32 s65, v238, 45
	v_readlane_b32 s66, v238, 46
	v_readlane_b32 s67, v238, 47
	s_barrier
	s_waitcnt vmcnt(0)
	ds_write_b128 v110, v[178:181]
	ds_write_b128 v110, v[182:185] offset:4096
	ds_write_b128 v110, v[186:189] offset:8192
	ds_write_b128 v110, v[190:193] offset:12288
	ds_write_b128 v110, v[220:223] offset:16384
	ds_write_b128 v110, v[224:227] offset:20480
	ds_write_b128 v110, v[228:231] offset:24576
	ds_write_b128 v110, v[232:235] offset:28672
	global_load_dwordx4 v[178:181], v93, s[98:99] offset:128
	global_load_dwordx4 v[182:185], v94, s[98:99] offset:128
	global_load_dwordx4 v[186:189], v95, s[98:99] offset:128
	global_load_dwordx4 v[190:193], v109, s[98:99] offset:128
	global_load_dwordx4 v[220:223], v93, s[100:101] offset:128
	global_load_dwordx4 v[224:227], v94, s[100:101] offset:128
	global_load_dwordx4 v[228:231], v95, s[100:101] offset:128
	global_load_dwordx4 v[232:235], v109, s[100:101] offset:128
	s_waitcnt lgkmcnt(0)
	s_barrier
	ds_read_b128 v[112:115], v239
	ds_read_b128 v[134:137], v241
	ds_read_b128 v[138:141], v241 offset:2048
	ds_read_b128 v[142:145], v241 offset:4096
	ds_read_b128 v[154:157], v241 offset:6144
	ds_read_b128 v[118:121], v239 offset:2048
	ds_read_b128 v[126:129], v239 offset:4096
	ds_read_b128 v[130:133], v239 offset:6144
	s_waitcnt lgkmcnt(6)
	v_mfma_f32_16x16x32_bf16 v[0:3], v[112:115], v[134:137], 0
	ds_read_b128 v[158:161], v240
	s_waitcnt lgkmcnt(6)
	v_mfma_f32_16x16x32_bf16 v[4:7], v[112:115], v[138:141], 0
	ds_read_b128 v[166:169], v242
	s_waitcnt lgkmcnt(6)
	v_mfma_f32_16x16x32_bf16 v[8:11], v[112:115], v[142:145], 0
	ds_read_b128 v[170:173], v242 offset:2048
	s_waitcnt lgkmcnt(6)
	v_mfma_f32_16x16x32_bf16 v[12:15], v[112:115], v[154:157], 0
	ds_read_b128 v[174:177], v242 offset:4096
	s_waitcnt lgkmcnt(6)
	v_mfma_f32_16x16x32_bf16 v[16:19], v[118:121], v[134:137], 0
	ds_read_b128 v[252:255], v242 offset:6144
	v_mfma_f32_16x16x32_bf16 v[20:23], v[118:121], v[138:141], 0
	ds_read_b128 v[162:165], v240 offset:2048
	v_mfma_f32_16x16x32_bf16 v[24:27], v[118:121], v[142:145], 0
	ds_read_b128 v[244:247], v240 offset:4096
	v_mfma_f32_16x16x32_bf16 v[28:31], v[118:121], v[154:157], 0
	ds_read_b128 v[248:251], v240 offset:6144
	s_waitcnt lgkmcnt(9)
	v_mfma_f32_16x16x32_bf16 v[32:35], v[126:129], v[134:137], 0
	v_mfma_f32_16x16x32_bf16 v[36:39], v[126:129], v[138:141], 0
	v_mfma_f32_16x16x32_bf16 v[40:43], v[126:129], v[142:145], 0
	v_mfma_f32_16x16x32_bf16 v[44:47], v[126:129], v[154:157], 0
	s_waitcnt lgkmcnt(8)
	v_mfma_f32_16x16x32_bf16 v[48:51], v[130:133], v[134:137], 0
	v_mfma_f32_16x16x32_bf16 v[52:55], v[130:133], v[138:141], 0
	v_mfma_f32_16x16x32_bf16 v[56:59], v[130:133], v[142:145], 0
	v_mfma_f32_16x16x32_bf16 v[60:63], v[130:133], v[154:157], 0
	s_waitcnt lgkmcnt(6)
	v_mfma_f32_16x16x32_bf16 v[0:3], v[158:161], v[166:169], v[0:3]
	s_waitcnt vmcnt(0)
	ds_write_b128 v110, v[178:181] offset:32768
	s_waitcnt lgkmcnt(6)
	v_mfma_f32_16x16x32_bf16 v[4:7], v[158:161], v[170:173], v[4:7]
	ds_write_b128 v110, v[182:185] offset:36864
	s_waitcnt lgkmcnt(6)
	v_mfma_f32_16x16x32_bf16 v[8:11], v[158:161], v[174:177], v[8:11]
	ds_write_b128 v110, v[186:189] offset:40960
	s_waitcnt lgkmcnt(6)
	v_mfma_f32_16x16x32_bf16 v[12:15], v[158:161], v[252:255], v[12:15]
	ds_write_b128 v110, v[190:193] offset:45056
	s_waitcnt lgkmcnt(6)
	v_mfma_f32_16x16x32_bf16 v[16:19], v[162:165], v[166:169], v[16:19]
	ds_write_b128 v110, v[220:223] offset:49152
	v_mfma_f32_16x16x32_bf16 v[20:23], v[162:165], v[170:173], v[20:23]
	ds_write_b128 v110, v[224:227] offset:53248
	v_mfma_f32_16x16x32_bf16 v[24:27], v[162:165], v[174:177], v[24:27]
	ds_write_b128 v110, v[228:231] offset:57344
	v_mfma_f32_16x16x32_bf16 v[28:31], v[162:165], v[252:255], v[28:31]
	ds_write_b128 v110, v[232:235] offset:61440
	s_waitcnt lgkmcnt(9)
	v_mfma_f32_16x16x32_bf16 v[32:35], v[244:247], v[166:169], v[32:35]
	global_load_dwordx4 v[178:181], v93, s[98:99] offset:256
	v_mfma_f32_16x16x32_bf16 v[36:39], v[244:247], v[170:173], v[36:39]
	global_load_dwordx4 v[182:185], v94, s[98:99] offset:256
	v_mfma_f32_16x16x32_bf16 v[40:43], v[244:247], v[174:177], v[40:43]
	global_load_dwordx4 v[186:189], v95, s[98:99] offset:256
	v_mfma_f32_16x16x32_bf16 v[44:47], v[244:247], v[252:255], v[44:47]
	global_load_dwordx4 v[190:193], v109, s[98:99] offset:256
	s_waitcnt lgkmcnt(8)
	v_mfma_f32_16x16x32_bf16 v[48:51], v[248:251], v[166:169], v[48:51]
	global_load_dwordx4 v[220:223], v93, s[100:101] offset:256
	v_mfma_f32_16x16x32_bf16 v[52:55], v[248:251], v[170:173], v[52:55]
	global_load_dwordx4 v[224:227], v94, s[100:101] offset:256
	v_mfma_f32_16x16x32_bf16 v[56:59], v[248:251], v[174:177], v[56:59]
	global_load_dwordx4 v[228:231], v95, s[100:101] offset:256
	v_mfma_f32_16x16x32_bf16 v[60:63], v[248:251], v[252:255], v[60:63]
	global_load_dwordx4 v[232:235], v109, s[100:101] offset:256
	s_waitcnt lgkmcnt(0)
	s_barrier
	ds_read_b128 v[112:115], v239 offset:32768
	ds_read_b128 v[134:137], v241 offset:32768
	ds_read_b128 v[138:141], v241 offset:34816
	ds_read_b128 v[142:145], v241 offset:36864
	ds_read_b128 v[154:157], v241 offset:38912
	ds_read_b128 v[118:121], v239 offset:34816
	ds_read_b128 v[126:129], v239 offset:36864
	ds_read_b128 v[130:133], v239 offset:38912
	s_waitcnt lgkmcnt(6)
	v_mfma_f32_16x16x32_bf16 v[0:3], v[112:115], v[134:137], v[0:3]
	ds_read_b128 v[158:161], v240 offset:32768
	s_waitcnt lgkmcnt(6)
	v_mfma_f32_16x16x32_bf16 v[4:7], v[112:115], v[138:141], v[4:7]
	ds_read_b128 v[166:169], v242 offset:32768
	s_waitcnt lgkmcnt(6)
	v_mfma_f32_16x16x32_bf16 v[8:11], v[112:115], v[142:145], v[8:11]
	ds_read_b128 v[170:173], v242 offset:34816
	s_waitcnt lgkmcnt(6)
	v_mfma_f32_16x16x32_bf16 v[12:15], v[112:115], v[154:157], v[12:15]
	ds_read_b128 v[174:177], v242 offset:36864
	s_waitcnt lgkmcnt(6)
	v_mfma_f32_16x16x32_bf16 v[16:19], v[118:121], v[134:137], v[16:19]
	ds_read_b128 v[252:255], v242 offset:38912
	v_mfma_f32_16x16x32_bf16 v[20:23], v[118:121], v[138:141], v[20:23]
	ds_read_b128 v[162:165], v240 offset:34816
	v_mfma_f32_16x16x32_bf16 v[24:27], v[118:121], v[142:145], v[24:27]
	ds_read_b128 v[244:247], v240 offset:36864
	v_mfma_f32_16x16x32_bf16 v[28:31], v[118:121], v[154:157], v[28:31]
	ds_read_b128 v[248:251], v240 offset:38912
	s_waitcnt lgkmcnt(9)
	v_mfma_f32_16x16x32_bf16 v[32:35], v[126:129], v[134:137], v[32:35]
	v_mfma_f32_16x16x32_bf16 v[36:39], v[126:129], v[138:141], v[36:39]
	v_mfma_f32_16x16x32_bf16 v[40:43], v[126:129], v[142:145], v[40:43]
	v_mfma_f32_16x16x32_bf16 v[44:47], v[126:129], v[154:157], v[44:47]
	s_waitcnt lgkmcnt(8)
	v_mfma_f32_16x16x32_bf16 v[48:51], v[130:133], v[134:137], v[48:51]
	v_mfma_f32_16x16x32_bf16 v[52:55], v[130:133], v[138:141], v[52:55]
	v_mfma_f32_16x16x32_bf16 v[56:59], v[130:133], v[142:145], v[56:59]
	v_mfma_f32_16x16x32_bf16 v[60:63], v[130:133], v[154:157], v[60:63]
	s_waitcnt lgkmcnt(6)
	v_mfma_f32_16x16x32_bf16 v[0:3], v[158:161], v[166:169], v[0:3]
	s_waitcnt vmcnt(0)
	ds_write_b128 v110, v[178:181]
	s_waitcnt lgkmcnt(6)
	v_mfma_f32_16x16x32_bf16 v[4:7], v[158:161], v[170:173], v[4:7]
	ds_write_b128 v110, v[182:185] offset:4096
	s_waitcnt lgkmcnt(6)
	v_mfma_f32_16x16x32_bf16 v[8:11], v[158:161], v[174:177], v[8:11]
	ds_write_b128 v110, v[186:189] offset:8192
	s_waitcnt lgkmcnt(6)
	v_mfma_f32_16x16x32_bf16 v[12:15], v[158:161], v[252:255], v[12:15]
	ds_write_b128 v110, v[190:193] offset:12288
	s_waitcnt lgkmcnt(6)
	v_mfma_f32_16x16x32_bf16 v[16:19], v[162:165], v[166:169], v[16:19]
	ds_write_b128 v110, v[220:223] offset:16384
	v_mfma_f32_16x16x32_bf16 v[20:23], v[162:165], v[170:173], v[20:23]
	ds_write_b128 v110, v[224:227] offset:20480
	v_mfma_f32_16x16x32_bf16 v[24:27], v[162:165], v[174:177], v[24:27]
	ds_write_b128 v110, v[228:231] offset:24576
	v_mfma_f32_16x16x32_bf16 v[28:31], v[162:165], v[252:255], v[28:31]
	ds_write_b128 v110, v[232:235] offset:28672
	s_waitcnt lgkmcnt(9)
	v_mfma_f32_16x16x32_bf16 v[32:35], v[244:247], v[166:169], v[32:35]
	global_load_dwordx4 v[178:181], v93, s[98:99] offset:384
	v_mfma_f32_16x16x32_bf16 v[36:39], v[244:247], v[170:173], v[36:39]
	global_load_dwordx4 v[182:185], v94, s[98:99] offset:384
	v_mfma_f32_16x16x32_bf16 v[40:43], v[244:247], v[174:177], v[40:43]
	global_load_dwordx4 v[186:189], v95, s[98:99] offset:384
	v_mfma_f32_16x16x32_bf16 v[44:47], v[244:247], v[252:255], v[44:47]
	global_load_dwordx4 v[190:193], v109, s[98:99] offset:384
	s_waitcnt lgkmcnt(8)
	v_mfma_f32_16x16x32_bf16 v[48:51], v[248:251], v[166:169], v[48:51]
	global_load_dwordx4 v[220:223], v93, s[100:101] offset:384
	v_mfma_f32_16x16x32_bf16 v[52:55], v[248:251], v[170:173], v[52:55]
	global_load_dwordx4 v[224:227], v94, s[100:101] offset:384
	v_mfma_f32_16x16x32_bf16 v[56:59], v[248:251], v[174:177], v[56:59]
	global_load_dwordx4 v[228:231], v95, s[100:101] offset:384
	v_mfma_f32_16x16x32_bf16 v[60:63], v[248:251], v[252:255], v[60:63]
	global_load_dwordx4 v[232:235], v109, s[100:101] offset:384
	s_waitcnt lgkmcnt(0)
	s_barrier
	ds_read_b128 v[112:115], v239
	ds_read_b128 v[134:137], v241
	ds_read_b128 v[138:141], v241 offset:2048
	ds_read_b128 v[142:145], v241 offset:4096
	ds_read_b128 v[154:157], v241 offset:6144
	ds_read_b128 v[118:121], v239 offset:2048
	ds_read_b128 v[126:129], v239 offset:4096
	ds_read_b128 v[130:133], v239 offset:6144
	s_waitcnt lgkmcnt(6)
	v_mfma_f32_16x16x32_bf16 v[0:3], v[112:115], v[134:137], v[0:3]
	ds_read_b128 v[158:161], v240
	s_waitcnt lgkmcnt(6)
	v_mfma_f32_16x16x32_bf16 v[4:7], v[112:115], v[138:141], v[4:7]
	ds_read_b128 v[166:169], v242
	s_waitcnt lgkmcnt(6)
	v_mfma_f32_16x16x32_bf16 v[8:11], v[112:115], v[142:145], v[8:11]
	ds_read_b128 v[170:173], v242 offset:2048
	s_waitcnt lgkmcnt(6)
	v_mfma_f32_16x16x32_bf16 v[12:15], v[112:115], v[154:157], v[12:15]
	ds_read_b128 v[174:177], v242 offset:4096
	s_waitcnt lgkmcnt(6)
	v_mfma_f32_16x16x32_bf16 v[16:19], v[118:121], v[134:137], v[16:19]
	ds_read_b128 v[252:255], v242 offset:6144
	v_mfma_f32_16x16x32_bf16 v[20:23], v[118:121], v[138:141], v[20:23]
	ds_read_b128 v[162:165], v240 offset:2048
	v_mfma_f32_16x16x32_bf16 v[24:27], v[118:121], v[142:145], v[24:27]
	ds_read_b128 v[244:247], v240 offset:4096
	v_mfma_f32_16x16x32_bf16 v[28:31], v[118:121], v[154:157], v[28:31]
	ds_read_b128 v[248:251], v240 offset:6144
	s_waitcnt lgkmcnt(9)
	v_mfma_f32_16x16x32_bf16 v[32:35], v[126:129], v[134:137], v[32:35]
	v_mfma_f32_16x16x32_bf16 v[36:39], v[126:129], v[138:141], v[36:39]
	v_mfma_f32_16x16x32_bf16 v[40:43], v[126:129], v[142:145], v[40:43]
	v_mfma_f32_16x16x32_bf16 v[44:47], v[126:129], v[154:157], v[44:47]
	s_waitcnt lgkmcnt(8)
	v_mfma_f32_16x16x32_bf16 v[48:51], v[130:133], v[134:137], v[48:51]
	v_mfma_f32_16x16x32_bf16 v[52:55], v[130:133], v[138:141], v[52:55]
	v_mfma_f32_16x16x32_bf16 v[56:59], v[130:133], v[142:145], v[56:59]
	v_mfma_f32_16x16x32_bf16 v[60:63], v[130:133], v[154:157], v[60:63]
	s_waitcnt lgkmcnt(6)
	v_mfma_f32_16x16x32_bf16 v[0:3], v[158:161], v[166:169], v[0:3]
	s_waitcnt vmcnt(0)
	ds_write_b128 v110, v[178:181] offset:32768
	s_waitcnt lgkmcnt(6)
	v_mfma_f32_16x16x32_bf16 v[4:7], v[158:161], v[170:173], v[4:7]
	ds_write_b128 v110, v[182:185] offset:36864
	s_waitcnt lgkmcnt(6)
	v_mfma_f32_16x16x32_bf16 v[8:11], v[158:161], v[174:177], v[8:11]
	ds_write_b128 v110, v[186:189] offset:40960
	s_waitcnt lgkmcnt(6)
	v_mfma_f32_16x16x32_bf16 v[12:15], v[158:161], v[252:255], v[12:15]
	ds_write_b128 v110, v[190:193] offset:45056
	s_waitcnt lgkmcnt(6)
	v_mfma_f32_16x16x32_bf16 v[16:19], v[162:165], v[166:169], v[16:19]
	ds_write_b128 v110, v[220:223] offset:49152
	v_mfma_f32_16x16x32_bf16 v[20:23], v[162:165], v[170:173], v[20:23]
	ds_write_b128 v110, v[224:227] offset:53248
	v_mfma_f32_16x16x32_bf16 v[24:27], v[162:165], v[174:177], v[24:27]
	ds_write_b128 v110, v[228:231] offset:57344
	v_mfma_f32_16x16x32_bf16 v[28:31], v[162:165], v[252:255], v[28:31]
	ds_write_b128 v110, v[232:235] offset:61440
	s_waitcnt lgkmcnt(9)
	v_mfma_f32_16x16x32_bf16 v[32:35], v[244:247], v[166:169], v[32:35]
	global_load_dwordx4 v[178:181], v93, s[98:99] offset:512
	v_mfma_f32_16x16x32_bf16 v[36:39], v[244:247], v[170:173], v[36:39]
	global_load_dwordx4 v[182:185], v94, s[98:99] offset:512
	v_mfma_f32_16x16x32_bf16 v[40:43], v[244:247], v[174:177], v[40:43]
	global_load_dwordx4 v[186:189], v95, s[98:99] offset:512
	v_mfma_f32_16x16x32_bf16 v[44:47], v[244:247], v[252:255], v[44:47]
	global_load_dwordx4 v[190:193], v109, s[98:99] offset:512
	s_waitcnt lgkmcnt(8)
	v_mfma_f32_16x16x32_bf16 v[48:51], v[248:251], v[166:169], v[48:51]
	global_load_dwordx4 v[220:223], v93, s[100:101] offset:512
	v_mfma_f32_16x16x32_bf16 v[52:55], v[248:251], v[170:173], v[52:55]
	global_load_dwordx4 v[224:227], v94, s[100:101] offset:512
	v_mfma_f32_16x16x32_bf16 v[56:59], v[248:251], v[174:177], v[56:59]
	global_load_dwordx4 v[228:231], v95, s[100:101] offset:512
	v_mfma_f32_16x16x32_bf16 v[60:63], v[248:251], v[252:255], v[60:63]
	global_load_dwordx4 v[232:235], v109, s[100:101] offset:512
	s_waitcnt lgkmcnt(0)
	s_barrier
	ds_read_b128 v[112:115], v239 offset:32768
	ds_read_b128 v[134:137], v241 offset:32768
	ds_read_b128 v[138:141], v241 offset:34816
	ds_read_b128 v[142:145], v241 offset:36864
	ds_read_b128 v[154:157], v241 offset:38912
	ds_read_b128 v[118:121], v239 offset:34816
	ds_read_b128 v[126:129], v239 offset:36864
	ds_read_b128 v[130:133], v239 offset:38912
	s_waitcnt lgkmcnt(6)
	v_mfma_f32_16x16x32_bf16 v[0:3], v[112:115], v[134:137], v[0:3]
	ds_read_b128 v[158:161], v240 offset:32768
	s_waitcnt lgkmcnt(6)
	v_mfma_f32_16x16x32_bf16 v[4:7], v[112:115], v[138:141], v[4:7]
	ds_read_b128 v[166:169], v242 offset:32768
	s_waitcnt lgkmcnt(6)
	v_mfma_f32_16x16x32_bf16 v[8:11], v[112:115], v[142:145], v[8:11]
	ds_read_b128 v[170:173], v242 offset:34816
	s_waitcnt lgkmcnt(6)
	v_mfma_f32_16x16x32_bf16 v[12:15], v[112:115], v[154:157], v[12:15]
	ds_read_b128 v[174:177], v242 offset:36864
	s_waitcnt lgkmcnt(6)
	v_mfma_f32_16x16x32_bf16 v[16:19], v[118:121], v[134:137], v[16:19]
	ds_read_b128 v[252:255], v242 offset:38912
	v_mfma_f32_16x16x32_bf16 v[20:23], v[118:121], v[138:141], v[20:23]
	ds_read_b128 v[162:165], v240 offset:34816
	v_mfma_f32_16x16x32_bf16 v[24:27], v[118:121], v[142:145], v[24:27]
	ds_read_b128 v[244:247], v240 offset:36864
	v_mfma_f32_16x16x32_bf16 v[28:31], v[118:121], v[154:157], v[28:31]
	ds_read_b128 v[248:251], v240 offset:38912
	s_waitcnt lgkmcnt(9)
	v_mfma_f32_16x16x32_bf16 v[32:35], v[126:129], v[134:137], v[32:35]
	v_mfma_f32_16x16x32_bf16 v[36:39], v[126:129], v[138:141], v[36:39]
	v_mfma_f32_16x16x32_bf16 v[40:43], v[126:129], v[142:145], v[40:43]
	v_mfma_f32_16x16x32_bf16 v[44:47], v[126:129], v[154:157], v[44:47]
	s_waitcnt lgkmcnt(8)
	v_mfma_f32_16x16x32_bf16 v[48:51], v[130:133], v[134:137], v[48:51]
	v_mfma_f32_16x16x32_bf16 v[52:55], v[130:133], v[138:141], v[52:55]
	v_mfma_f32_16x16x32_bf16 v[56:59], v[130:133], v[142:145], v[56:59]
	v_mfma_f32_16x16x32_bf16 v[60:63], v[130:133], v[154:157], v[60:63]
	s_waitcnt lgkmcnt(6)
	v_mfma_f32_16x16x32_bf16 v[0:3], v[158:161], v[166:169], v[0:3]
	s_waitcnt vmcnt(0)
	ds_write_b128 v110, v[178:181]
	s_waitcnt lgkmcnt(6)
	v_mfma_f32_16x16x32_bf16 v[4:7], v[158:161], v[170:173], v[4:7]
	ds_write_b128 v110, v[182:185] offset:4096
	s_waitcnt lgkmcnt(6)
	v_mfma_f32_16x16x32_bf16 v[8:11], v[158:161], v[174:177], v[8:11]
	ds_write_b128 v110, v[186:189] offset:8192
	s_waitcnt lgkmcnt(6)
	v_mfma_f32_16x16x32_bf16 v[12:15], v[158:161], v[252:255], v[12:15]
	ds_write_b128 v110, v[190:193] offset:12288
	s_waitcnt lgkmcnt(6)
	v_mfma_f32_16x16x32_bf16 v[16:19], v[162:165], v[166:169], v[16:19]
	ds_write_b128 v110, v[220:223] offset:16384
	v_mfma_f32_16x16x32_bf16 v[20:23], v[162:165], v[170:173], v[20:23]
	ds_write_b128 v110, v[224:227] offset:20480
	v_mfma_f32_16x16x32_bf16 v[24:27], v[162:165], v[174:177], v[24:27]
	ds_write_b128 v110, v[228:231] offset:24576
	v_mfma_f32_16x16x32_bf16 v[28:31], v[162:165], v[252:255], v[28:31]
	ds_write_b128 v110, v[232:235] offset:28672
	s_waitcnt lgkmcnt(9)
	v_mfma_f32_16x16x32_bf16 v[32:35], v[244:247], v[166:169], v[32:35]
	global_load_dwordx4 v[178:181], v93, s[98:99] offset:640
	v_mfma_f32_16x16x32_bf16 v[36:39], v[244:247], v[170:173], v[36:39]
	global_load_dwordx4 v[182:185], v94, s[98:99] offset:640
	v_mfma_f32_16x16x32_bf16 v[40:43], v[244:247], v[174:177], v[40:43]
	global_load_dwordx4 v[186:189], v95, s[98:99] offset:640
	v_mfma_f32_16x16x32_bf16 v[44:47], v[244:247], v[252:255], v[44:47]
	global_load_dwordx4 v[190:193], v109, s[98:99] offset:640
	s_waitcnt lgkmcnt(8)
	v_mfma_f32_16x16x32_bf16 v[48:51], v[248:251], v[166:169], v[48:51]
	global_load_dwordx4 v[220:223], v93, s[100:101] offset:640
	v_mfma_f32_16x16x32_bf16 v[52:55], v[248:251], v[170:173], v[52:55]
	global_load_dwordx4 v[224:227], v94, s[100:101] offset:640
	v_mfma_f32_16x16x32_bf16 v[56:59], v[248:251], v[174:177], v[56:59]
	global_load_dwordx4 v[228:231], v95, s[100:101] offset:640
	v_mfma_f32_16x16x32_bf16 v[60:63], v[248:251], v[252:255], v[60:63]
	global_load_dwordx4 v[232:235], v109, s[100:101] offset:640
	s_waitcnt lgkmcnt(0)
	s_barrier
	ds_read_b128 v[112:115], v239
	ds_read_b128 v[134:137], v241
	ds_read_b128 v[138:141], v241 offset:2048
	ds_read_b128 v[142:145], v241 offset:4096
	ds_read_b128 v[154:157], v241 offset:6144
	ds_read_b128 v[118:121], v239 offset:2048
	ds_read_b128 v[126:129], v239 offset:4096
	ds_read_b128 v[130:133], v239 offset:6144
	s_waitcnt lgkmcnt(6)
	v_mfma_f32_16x16x32_bf16 v[0:3], v[112:115], v[134:137], v[0:3]
	ds_read_b128 v[158:161], v240
	s_waitcnt lgkmcnt(6)
	v_mfma_f32_16x16x32_bf16 v[4:7], v[112:115], v[138:141], v[4:7]
	ds_read_b128 v[166:169], v242
	s_waitcnt lgkmcnt(6)
	v_mfma_f32_16x16x32_bf16 v[8:11], v[112:115], v[142:145], v[8:11]
	ds_read_b128 v[170:173], v242 offset:2048
	s_waitcnt lgkmcnt(6)
	v_mfma_f32_16x16x32_bf16 v[12:15], v[112:115], v[154:157], v[12:15]
	ds_read_b128 v[174:177], v242 offset:4096
	s_waitcnt lgkmcnt(6)
	v_mfma_f32_16x16x32_bf16 v[16:19], v[118:121], v[134:137], v[16:19]
	ds_read_b128 v[252:255], v242 offset:6144
	v_mfma_f32_16x16x32_bf16 v[20:23], v[118:121], v[138:141], v[20:23]
	ds_read_b128 v[162:165], v240 offset:2048
	v_mfma_f32_16x16x32_bf16 v[24:27], v[118:121], v[142:145], v[24:27]
	ds_read_b128 v[244:247], v240 offset:4096
	v_mfma_f32_16x16x32_bf16 v[28:31], v[118:121], v[154:157], v[28:31]
	ds_read_b128 v[248:251], v240 offset:6144
	s_waitcnt lgkmcnt(9)
	v_mfma_f32_16x16x32_bf16 v[32:35], v[126:129], v[134:137], v[32:35]
	v_mfma_f32_16x16x32_bf16 v[36:39], v[126:129], v[138:141], v[36:39]
	v_mfma_f32_16x16x32_bf16 v[40:43], v[126:129], v[142:145], v[40:43]
	v_mfma_f32_16x16x32_bf16 v[44:47], v[126:129], v[154:157], v[44:47]
	s_waitcnt lgkmcnt(8)
	v_mfma_f32_16x16x32_bf16 v[48:51], v[130:133], v[134:137], v[48:51]
	v_mfma_f32_16x16x32_bf16 v[52:55], v[130:133], v[138:141], v[52:55]
	v_mfma_f32_16x16x32_bf16 v[56:59], v[130:133], v[142:145], v[56:59]
	v_mfma_f32_16x16x32_bf16 v[60:63], v[130:133], v[154:157], v[60:63]
	s_waitcnt lgkmcnt(6)
	v_mfma_f32_16x16x32_bf16 v[0:3], v[158:161], v[166:169], v[0:3]
	s_waitcnt vmcnt(0)
	ds_write_b128 v110, v[178:181] offset:32768
	s_waitcnt lgkmcnt(6)
	v_mfma_f32_16x16x32_bf16 v[4:7], v[158:161], v[170:173], v[4:7]
	ds_write_b128 v110, v[182:185] offset:36864
	s_waitcnt lgkmcnt(6)
	v_mfma_f32_16x16x32_bf16 v[8:11], v[158:161], v[174:177], v[8:11]
	ds_write_b128 v110, v[186:189] offset:40960
	s_waitcnt lgkmcnt(6)
	v_mfma_f32_16x16x32_bf16 v[12:15], v[158:161], v[252:255], v[12:15]
	ds_write_b128 v110, v[190:193] offset:45056
	s_waitcnt lgkmcnt(6)
	v_mfma_f32_16x16x32_bf16 v[16:19], v[162:165], v[166:169], v[16:19]
	ds_write_b128 v110, v[220:223] offset:49152
	v_mfma_f32_16x16x32_bf16 v[20:23], v[162:165], v[170:173], v[20:23]
	ds_write_b128 v110, v[224:227] offset:53248
	v_mfma_f32_16x16x32_bf16 v[24:27], v[162:165], v[174:177], v[24:27]
	ds_write_b128 v110, v[228:231] offset:57344
	v_mfma_f32_16x16x32_bf16 v[28:31], v[162:165], v[252:255], v[28:31]
	ds_write_b128 v110, v[232:235] offset:61440
	s_waitcnt lgkmcnt(9)
	v_mfma_f32_16x16x32_bf16 v[32:35], v[244:247], v[166:169], v[32:35]
	global_load_dwordx4 v[178:181], v93, s[98:99] offset:768
	v_mfma_f32_16x16x32_bf16 v[36:39], v[244:247], v[170:173], v[36:39]
	global_load_dwordx4 v[182:185], v94, s[98:99] offset:768
	v_mfma_f32_16x16x32_bf16 v[40:43], v[244:247], v[174:177], v[40:43]
	global_load_dwordx4 v[186:189], v95, s[98:99] offset:768
	v_mfma_f32_16x16x32_bf16 v[44:47], v[244:247], v[252:255], v[44:47]
	global_load_dwordx4 v[190:193], v109, s[98:99] offset:768
	s_waitcnt lgkmcnt(8)
	v_mfma_f32_16x16x32_bf16 v[48:51], v[248:251], v[166:169], v[48:51]
	global_load_dwordx4 v[220:223], v93, s[100:101] offset:768
	v_mfma_f32_16x16x32_bf16 v[52:55], v[248:251], v[170:173], v[52:55]
	global_load_dwordx4 v[224:227], v94, s[100:101] offset:768
	v_mfma_f32_16x16x32_bf16 v[56:59], v[248:251], v[174:177], v[56:59]
	global_load_dwordx4 v[228:231], v95, s[100:101] offset:768
	v_mfma_f32_16x16x32_bf16 v[60:63], v[248:251], v[252:255], v[60:63]
	global_load_dwordx4 v[232:235], v109, s[100:101] offset:768
	s_waitcnt lgkmcnt(0)
	s_barrier
	ds_read_b128 v[112:115], v239 offset:32768
	ds_read_b128 v[134:137], v241 offset:32768
	ds_read_b128 v[138:141], v241 offset:34816
	ds_read_b128 v[142:145], v241 offset:36864
	ds_read_b128 v[154:157], v241 offset:38912
	ds_read_b128 v[118:121], v239 offset:34816
	ds_read_b128 v[126:129], v239 offset:36864
	ds_read_b128 v[130:133], v239 offset:38912
	s_waitcnt lgkmcnt(6)
	v_mfma_f32_16x16x32_bf16 v[0:3], v[112:115], v[134:137], v[0:3]
	ds_read_b128 v[158:161], v240 offset:32768
	s_waitcnt lgkmcnt(6)
	v_mfma_f32_16x16x32_bf16 v[4:7], v[112:115], v[138:141], v[4:7]
	ds_read_b128 v[166:169], v242 offset:32768
	s_waitcnt lgkmcnt(6)
	v_mfma_f32_16x16x32_bf16 v[8:11], v[112:115], v[142:145], v[8:11]
	ds_read_b128 v[170:173], v242 offset:34816
	s_waitcnt lgkmcnt(6)
	v_mfma_f32_16x16x32_bf16 v[12:15], v[112:115], v[154:157], v[12:15]
	ds_read_b128 v[174:177], v242 offset:36864
	s_waitcnt lgkmcnt(6)
	v_mfma_f32_16x16x32_bf16 v[16:19], v[118:121], v[134:137], v[16:19]
	ds_read_b128 v[252:255], v242 offset:38912
	v_mfma_f32_16x16x32_bf16 v[20:23], v[118:121], v[138:141], v[20:23]
	ds_read_b128 v[162:165], v240 offset:34816
	v_mfma_f32_16x16x32_bf16 v[24:27], v[118:121], v[142:145], v[24:27]
	ds_read_b128 v[244:247], v240 offset:36864
	v_mfma_f32_16x16x32_bf16 v[28:31], v[118:121], v[154:157], v[28:31]
	ds_read_b128 v[248:251], v240 offset:38912
	s_waitcnt lgkmcnt(9)
	v_mfma_f32_16x16x32_bf16 v[32:35], v[126:129], v[134:137], v[32:35]
	v_mfma_f32_16x16x32_bf16 v[36:39], v[126:129], v[138:141], v[36:39]
	v_mfma_f32_16x16x32_bf16 v[40:43], v[126:129], v[142:145], v[40:43]
	v_mfma_f32_16x16x32_bf16 v[44:47], v[126:129], v[154:157], v[44:47]
	s_waitcnt lgkmcnt(8)
	v_mfma_f32_16x16x32_bf16 v[48:51], v[130:133], v[134:137], v[48:51]
	v_mfma_f32_16x16x32_bf16 v[52:55], v[130:133], v[138:141], v[52:55]
	v_mfma_f32_16x16x32_bf16 v[56:59], v[130:133], v[142:145], v[56:59]
	v_mfma_f32_16x16x32_bf16 v[60:63], v[130:133], v[154:157], v[60:63]
	s_waitcnt lgkmcnt(6)
	v_mfma_f32_16x16x32_bf16 v[0:3], v[158:161], v[166:169], v[0:3]
	s_waitcnt vmcnt(0)
	ds_write_b128 v110, v[178:181]
	s_waitcnt lgkmcnt(6)
	v_mfma_f32_16x16x32_bf16 v[4:7], v[158:161], v[170:173], v[4:7]
	ds_write_b128 v110, v[182:185] offset:4096
	s_waitcnt lgkmcnt(6)
	v_mfma_f32_16x16x32_bf16 v[8:11], v[158:161], v[174:177], v[8:11]
	ds_write_b128 v110, v[186:189] offset:8192
	s_waitcnt lgkmcnt(6)
	v_mfma_f32_16x16x32_bf16 v[12:15], v[158:161], v[252:255], v[12:15]
	ds_write_b128 v110, v[190:193] offset:12288
	s_waitcnt lgkmcnt(6)
	v_mfma_f32_16x16x32_bf16 v[16:19], v[162:165], v[166:169], v[16:19]
	ds_write_b128 v110, v[220:223] offset:16384
	v_mfma_f32_16x16x32_bf16 v[20:23], v[162:165], v[170:173], v[20:23]
	ds_write_b128 v110, v[224:227] offset:20480
	v_mfma_f32_16x16x32_bf16 v[24:27], v[162:165], v[174:177], v[24:27]
	ds_write_b128 v110, v[228:231] offset:24576
	v_mfma_f32_16x16x32_bf16 v[28:31], v[162:165], v[252:255], v[28:31]
	ds_write_b128 v110, v[232:235] offset:28672
	s_waitcnt lgkmcnt(9)
	v_mfma_f32_16x16x32_bf16 v[32:35], v[244:247], v[166:169], v[32:35]
	global_load_dwordx4 v[178:181], v93, s[98:99] offset:896
	v_mfma_f32_16x16x32_bf16 v[36:39], v[244:247], v[170:173], v[36:39]
	global_load_dwordx4 v[182:185], v94, s[98:99] offset:896
	v_mfma_f32_16x16x32_bf16 v[40:43], v[244:247], v[174:177], v[40:43]
	global_load_dwordx4 v[186:189], v95, s[98:99] offset:896
	v_mfma_f32_16x16x32_bf16 v[44:47], v[244:247], v[252:255], v[44:47]
	global_load_dwordx4 v[190:193], v109, s[98:99] offset:896
	s_waitcnt lgkmcnt(8)
	v_mfma_f32_16x16x32_bf16 v[48:51], v[248:251], v[166:169], v[48:51]
	global_load_dwordx4 v[220:223], v93, s[100:101] offset:896
	v_mfma_f32_16x16x32_bf16 v[52:55], v[248:251], v[170:173], v[52:55]
	global_load_dwordx4 v[224:227], v94, s[100:101] offset:896
	v_mfma_f32_16x16x32_bf16 v[56:59], v[248:251], v[174:177], v[56:59]
	global_load_dwordx4 v[228:231], v95, s[100:101] offset:896
	v_mfma_f32_16x16x32_bf16 v[60:63], v[248:251], v[252:255], v[60:63]
	global_load_dwordx4 v[232:235], v109, s[100:101] offset:896
	s_waitcnt lgkmcnt(0)
	s_barrier
	ds_read_b128 v[112:115], v239
	ds_read_b128 v[134:137], v241
	ds_read_b128 v[138:141], v241 offset:2048
	ds_read_b128 v[142:145], v241 offset:4096
	ds_read_b128 v[154:157], v241 offset:6144
	ds_read_b128 v[118:121], v239 offset:2048
	ds_read_b128 v[126:129], v239 offset:4096
	ds_read_b128 v[130:133], v239 offset:6144
	s_waitcnt lgkmcnt(6)
	v_mfma_f32_16x16x32_bf16 v[0:3], v[112:115], v[134:137], v[0:3]
	ds_read_b128 v[158:161], v240
	s_waitcnt lgkmcnt(6)
	v_mfma_f32_16x16x32_bf16 v[4:7], v[112:115], v[138:141], v[4:7]
	ds_read_b128 v[166:169], v242
	s_waitcnt lgkmcnt(6)
	v_mfma_f32_16x16x32_bf16 v[8:11], v[112:115], v[142:145], v[8:11]
	ds_read_b128 v[170:173], v242 offset:2048
	s_waitcnt lgkmcnt(6)
	v_mfma_f32_16x16x32_bf16 v[12:15], v[112:115], v[154:157], v[12:15]
	ds_read_b128 v[174:177], v242 offset:4096
	s_waitcnt lgkmcnt(6)
	v_mfma_f32_16x16x32_bf16 v[16:19], v[118:121], v[134:137], v[16:19]
	ds_read_b128 v[252:255], v242 offset:6144
	v_mfma_f32_16x16x32_bf16 v[20:23], v[118:121], v[138:141], v[20:23]
	ds_read_b128 v[162:165], v240 offset:2048
	v_mfma_f32_16x16x32_bf16 v[24:27], v[118:121], v[142:145], v[24:27]
	ds_read_b128 v[244:247], v240 offset:4096
	v_mfma_f32_16x16x32_bf16 v[28:31], v[118:121], v[154:157], v[28:31]
	ds_read_b128 v[248:251], v240 offset:6144
	s_waitcnt lgkmcnt(9)
	v_mfma_f32_16x16x32_bf16 v[32:35], v[126:129], v[134:137], v[32:35]
	v_mfma_f32_16x16x32_bf16 v[36:39], v[126:129], v[138:141], v[36:39]
	v_mfma_f32_16x16x32_bf16 v[40:43], v[126:129], v[142:145], v[40:43]
	v_mfma_f32_16x16x32_bf16 v[44:47], v[126:129], v[154:157], v[44:47]
	s_waitcnt lgkmcnt(8)
	v_mfma_f32_16x16x32_bf16 v[48:51], v[130:133], v[134:137], v[48:51]
	v_mfma_f32_16x16x32_bf16 v[52:55], v[130:133], v[138:141], v[52:55]
	v_mfma_f32_16x16x32_bf16 v[56:59], v[130:133], v[142:145], v[56:59]
	v_mfma_f32_16x16x32_bf16 v[60:63], v[130:133], v[154:157], v[60:63]
	s_waitcnt lgkmcnt(6)
	v_mfma_f32_16x16x32_bf16 v[0:3], v[158:161], v[166:169], v[0:3]
	s_waitcnt vmcnt(0)
	ds_write_b128 v110, v[178:181] offset:32768
	s_waitcnt lgkmcnt(6)
	v_mfma_f32_16x16x32_bf16 v[4:7], v[158:161], v[170:173], v[4:7]
	ds_write_b128 v110, v[182:185] offset:36864
	s_waitcnt lgkmcnt(6)
	v_mfma_f32_16x16x32_bf16 v[8:11], v[158:161], v[174:177], v[8:11]
	ds_write_b128 v110, v[186:189] offset:40960
	s_waitcnt lgkmcnt(6)
	v_mfma_f32_16x16x32_bf16 v[12:15], v[158:161], v[252:255], v[12:15]
	ds_write_b128 v110, v[190:193] offset:45056
	s_waitcnt lgkmcnt(6)
	v_mfma_f32_16x16x32_bf16 v[16:19], v[162:165], v[166:169], v[16:19]
	ds_write_b128 v110, v[220:223] offset:49152
	v_mfma_f32_16x16x32_bf16 v[20:23], v[162:165], v[170:173], v[20:23]
	ds_write_b128 v110, v[224:227] offset:53248
	v_mfma_f32_16x16x32_bf16 v[24:27], v[162:165], v[174:177], v[24:27]
	ds_write_b128 v110, v[228:231] offset:57344
	v_mfma_f32_16x16x32_bf16 v[28:31], v[162:165], v[252:255], v[28:31]
	ds_write_b128 v110, v[232:235] offset:61440
	s_waitcnt lgkmcnt(9)
	v_mfma_f32_16x16x32_bf16 v[32:35], v[244:247], v[166:169], v[32:35]
	global_load_dwordx4 v[178:181], v93, s[98:99] offset:1024
	v_mfma_f32_16x16x32_bf16 v[36:39], v[244:247], v[170:173], v[36:39]
	global_load_dwordx4 v[182:185], v94, s[98:99] offset:1024
	v_mfma_f32_16x16x32_bf16 v[40:43], v[244:247], v[174:177], v[40:43]
	global_load_dwordx4 v[186:189], v95, s[98:99] offset:1024
	v_mfma_f32_16x16x32_bf16 v[44:47], v[244:247], v[252:255], v[44:47]
	global_load_dwordx4 v[190:193], v109, s[98:99] offset:1024
	s_waitcnt lgkmcnt(8)
	v_mfma_f32_16x16x32_bf16 v[48:51], v[248:251], v[166:169], v[48:51]
	global_load_dwordx4 v[220:223], v93, s[100:101] offset:1024
	v_mfma_f32_16x16x32_bf16 v[52:55], v[248:251], v[170:173], v[52:55]
	global_load_dwordx4 v[224:227], v94, s[100:101] offset:1024
	v_mfma_f32_16x16x32_bf16 v[56:59], v[248:251], v[174:177], v[56:59]
	global_load_dwordx4 v[228:231], v95, s[100:101] offset:1024
	v_mfma_f32_16x16x32_bf16 v[60:63], v[248:251], v[252:255], v[60:63]
	global_load_dwordx4 v[232:235], v109, s[100:101] offset:1024
	s_waitcnt lgkmcnt(0)
	s_barrier
	ds_read_b128 v[112:115], v239 offset:32768
	ds_read_b128 v[134:137], v241 offset:32768
	ds_read_b128 v[138:141], v241 offset:34816
	ds_read_b128 v[142:145], v241 offset:36864
	ds_read_b128 v[154:157], v241 offset:38912
	ds_read_b128 v[118:121], v239 offset:34816
	ds_read_b128 v[126:129], v239 offset:36864
	ds_read_b128 v[130:133], v239 offset:38912
	s_waitcnt lgkmcnt(6)
	v_mfma_f32_16x16x32_bf16 v[0:3], v[112:115], v[134:137], v[0:3]
	ds_read_b128 v[158:161], v240 offset:32768
	s_waitcnt lgkmcnt(6)
	v_mfma_f32_16x16x32_bf16 v[4:7], v[112:115], v[138:141], v[4:7]
	ds_read_b128 v[166:169], v242 offset:32768
	s_waitcnt lgkmcnt(6)
	v_mfma_f32_16x16x32_bf16 v[8:11], v[112:115], v[142:145], v[8:11]
	ds_read_b128 v[170:173], v242 offset:34816
	s_waitcnt lgkmcnt(6)
	v_mfma_f32_16x16x32_bf16 v[12:15], v[112:115], v[154:157], v[12:15]
	ds_read_b128 v[174:177], v242 offset:36864
	s_waitcnt lgkmcnt(6)
	v_mfma_f32_16x16x32_bf16 v[16:19], v[118:121], v[134:137], v[16:19]
	ds_read_b128 v[252:255], v242 offset:38912
	v_mfma_f32_16x16x32_bf16 v[20:23], v[118:121], v[138:141], v[20:23]
	ds_read_b128 v[162:165], v240 offset:34816
	v_mfma_f32_16x16x32_bf16 v[24:27], v[118:121], v[142:145], v[24:27]
	ds_read_b128 v[244:247], v240 offset:36864
	v_mfma_f32_16x16x32_bf16 v[28:31], v[118:121], v[154:157], v[28:31]
	ds_read_b128 v[248:251], v240 offset:38912
	s_waitcnt lgkmcnt(9)
	v_mfma_f32_16x16x32_bf16 v[32:35], v[126:129], v[134:137], v[32:35]
	v_mfma_f32_16x16x32_bf16 v[36:39], v[126:129], v[138:141], v[36:39]
	v_mfma_f32_16x16x32_bf16 v[40:43], v[126:129], v[142:145], v[40:43]
	v_mfma_f32_16x16x32_bf16 v[44:47], v[126:129], v[154:157], v[44:47]
	s_waitcnt lgkmcnt(8)
	v_mfma_f32_16x16x32_bf16 v[48:51], v[130:133], v[134:137], v[48:51]
	v_mfma_f32_16x16x32_bf16 v[52:55], v[130:133], v[138:141], v[52:55]
	v_mfma_f32_16x16x32_bf16 v[56:59], v[130:133], v[142:145], v[56:59]
	v_mfma_f32_16x16x32_bf16 v[60:63], v[130:133], v[154:157], v[60:63]
	s_waitcnt lgkmcnt(6)
	v_mfma_f32_16x16x32_bf16 v[0:3], v[158:161], v[166:169], v[0:3]
	s_waitcnt vmcnt(0)
	ds_write_b128 v110, v[178:181]
	s_waitcnt lgkmcnt(6)
	v_mfma_f32_16x16x32_bf16 v[4:7], v[158:161], v[170:173], v[4:7]
	ds_write_b128 v110, v[182:185] offset:4096
	s_waitcnt lgkmcnt(6)
	v_mfma_f32_16x16x32_bf16 v[8:11], v[158:161], v[174:177], v[8:11]
	ds_write_b128 v110, v[186:189] offset:8192
	s_waitcnt lgkmcnt(6)
	v_mfma_f32_16x16x32_bf16 v[12:15], v[158:161], v[252:255], v[12:15]
	ds_write_b128 v110, v[190:193] offset:12288
	s_waitcnt lgkmcnt(6)
	v_mfma_f32_16x16x32_bf16 v[16:19], v[162:165], v[166:169], v[16:19]
	ds_write_b128 v110, v[220:223] offset:16384
	v_mfma_f32_16x16x32_bf16 v[20:23], v[162:165], v[170:173], v[20:23]
	ds_write_b128 v110, v[224:227] offset:20480
	v_mfma_f32_16x16x32_bf16 v[24:27], v[162:165], v[174:177], v[24:27]
	ds_write_b128 v110, v[228:231] offset:24576
	v_mfma_f32_16x16x32_bf16 v[28:31], v[162:165], v[252:255], v[28:31]
	ds_write_b128 v110, v[232:235] offset:28672
	s_waitcnt lgkmcnt(9)
	v_mfma_f32_16x16x32_bf16 v[32:35], v[244:247], v[166:169], v[32:35]
	global_load_dwordx4 v[178:181], v93, s[98:99] offset:1152
	v_mfma_f32_16x16x32_bf16 v[36:39], v[244:247], v[170:173], v[36:39]
	global_load_dwordx4 v[182:185], v94, s[98:99] offset:1152
	v_mfma_f32_16x16x32_bf16 v[40:43], v[244:247], v[174:177], v[40:43]
	global_load_dwordx4 v[186:189], v95, s[98:99] offset:1152
	v_mfma_f32_16x16x32_bf16 v[44:47], v[244:247], v[252:255], v[44:47]
	global_load_dwordx4 v[190:193], v109, s[98:99] offset:1152
	s_waitcnt lgkmcnt(8)
	v_mfma_f32_16x16x32_bf16 v[48:51], v[248:251], v[166:169], v[48:51]
	global_load_dwordx4 v[220:223], v93, s[100:101] offset:1152
	v_mfma_f32_16x16x32_bf16 v[52:55], v[248:251], v[170:173], v[52:55]
	global_load_dwordx4 v[224:227], v94, s[100:101] offset:1152
	v_mfma_f32_16x16x32_bf16 v[56:59], v[248:251], v[174:177], v[56:59]
	global_load_dwordx4 v[228:231], v95, s[100:101] offset:1152
	v_mfma_f32_16x16x32_bf16 v[60:63], v[248:251], v[252:255], v[60:63]
	global_load_dwordx4 v[232:235], v109, s[100:101] offset:1152
	s_waitcnt lgkmcnt(0)
	s_barrier
	ds_read_b128 v[112:115], v239
	ds_read_b128 v[134:137], v241
	ds_read_b128 v[138:141], v241 offset:2048
	ds_read_b128 v[142:145], v241 offset:4096
	ds_read_b128 v[154:157], v241 offset:6144
	ds_read_b128 v[118:121], v239 offset:2048
	ds_read_b128 v[126:129], v239 offset:4096
	ds_read_b128 v[130:133], v239 offset:6144
	s_waitcnt lgkmcnt(6)
	v_mfma_f32_16x16x32_bf16 v[0:3], v[112:115], v[134:137], v[0:3]
	ds_read_b128 v[158:161], v240
	s_waitcnt lgkmcnt(6)
	v_mfma_f32_16x16x32_bf16 v[4:7], v[112:115], v[138:141], v[4:7]
	ds_read_b128 v[166:169], v242
	s_waitcnt lgkmcnt(6)
	v_mfma_f32_16x16x32_bf16 v[8:11], v[112:115], v[142:145], v[8:11]
	ds_read_b128 v[170:173], v242 offset:2048
	s_waitcnt lgkmcnt(6)
	v_mfma_f32_16x16x32_bf16 v[12:15], v[112:115], v[154:157], v[12:15]
	ds_read_b128 v[174:177], v242 offset:4096
	s_waitcnt lgkmcnt(6)
	v_mfma_f32_16x16x32_bf16 v[16:19], v[118:121], v[134:137], v[16:19]
	ds_read_b128 v[252:255], v242 offset:6144
	v_mfma_f32_16x16x32_bf16 v[20:23], v[118:121], v[138:141], v[20:23]
	ds_read_b128 v[162:165], v240 offset:2048
	v_mfma_f32_16x16x32_bf16 v[24:27], v[118:121], v[142:145], v[24:27]
	ds_read_b128 v[244:247], v240 offset:4096
	v_mfma_f32_16x16x32_bf16 v[28:31], v[118:121], v[154:157], v[28:31]
	ds_read_b128 v[248:251], v240 offset:6144
	s_waitcnt lgkmcnt(9)
	v_mfma_f32_16x16x32_bf16 v[32:35], v[126:129], v[134:137], v[32:35]
	v_mfma_f32_16x16x32_bf16 v[36:39], v[126:129], v[138:141], v[36:39]
	v_mfma_f32_16x16x32_bf16 v[40:43], v[126:129], v[142:145], v[40:43]
	v_mfma_f32_16x16x32_bf16 v[44:47], v[126:129], v[154:157], v[44:47]
	s_waitcnt lgkmcnt(8)
	v_mfma_f32_16x16x32_bf16 v[48:51], v[130:133], v[134:137], v[48:51]
	v_mfma_f32_16x16x32_bf16 v[52:55], v[130:133], v[138:141], v[52:55]
	v_mfma_f32_16x16x32_bf16 v[56:59], v[130:133], v[142:145], v[56:59]
	v_mfma_f32_16x16x32_bf16 v[60:63], v[130:133], v[154:157], v[60:63]
	s_waitcnt lgkmcnt(6)
	v_mfma_f32_16x16x32_bf16 v[0:3], v[158:161], v[166:169], v[0:3]
	s_waitcnt vmcnt(0)
	ds_write_b128 v110, v[178:181] offset:32768
	s_waitcnt lgkmcnt(6)
	v_mfma_f32_16x16x32_bf16 v[4:7], v[158:161], v[170:173], v[4:7]
	ds_write_b128 v110, v[182:185] offset:36864
	s_waitcnt lgkmcnt(6)
	v_mfma_f32_16x16x32_bf16 v[8:11], v[158:161], v[174:177], v[8:11]
	ds_write_b128 v110, v[186:189] offset:40960
	s_waitcnt lgkmcnt(6)
	v_mfma_f32_16x16x32_bf16 v[12:15], v[158:161], v[252:255], v[12:15]
	ds_write_b128 v110, v[190:193] offset:45056
	s_waitcnt lgkmcnt(6)
	v_mfma_f32_16x16x32_bf16 v[16:19], v[162:165], v[166:169], v[16:19]
	ds_write_b128 v110, v[220:223] offset:49152
	v_mfma_f32_16x16x32_bf16 v[20:23], v[162:165], v[170:173], v[20:23]
	ds_write_b128 v110, v[224:227] offset:53248
	v_mfma_f32_16x16x32_bf16 v[24:27], v[162:165], v[174:177], v[24:27]
	ds_write_b128 v110, v[228:231] offset:57344
	v_mfma_f32_16x16x32_bf16 v[28:31], v[162:165], v[252:255], v[28:31]
	ds_write_b128 v110, v[232:235] offset:61440
	s_waitcnt lgkmcnt(9)
	v_mfma_f32_16x16x32_bf16 v[32:35], v[244:247], v[166:169], v[32:35]
	global_load_dwordx4 v[178:181], v93, s[98:99] offset:1280
	v_mfma_f32_16x16x32_bf16 v[36:39], v[244:247], v[170:173], v[36:39]
	global_load_dwordx4 v[182:185], v94, s[98:99] offset:1280
	v_mfma_f32_16x16x32_bf16 v[40:43], v[244:247], v[174:177], v[40:43]
	global_load_dwordx4 v[186:189], v95, s[98:99] offset:1280
	v_mfma_f32_16x16x32_bf16 v[44:47], v[244:247], v[252:255], v[44:47]
	global_load_dwordx4 v[190:193], v109, s[98:99] offset:1280
	s_waitcnt lgkmcnt(8)
	v_mfma_f32_16x16x32_bf16 v[48:51], v[248:251], v[166:169], v[48:51]
	global_load_dwordx4 v[220:223], v93, s[100:101] offset:1280
	v_mfma_f32_16x16x32_bf16 v[52:55], v[248:251], v[170:173], v[52:55]
	global_load_dwordx4 v[224:227], v94, s[100:101] offset:1280
	v_mfma_f32_16x16x32_bf16 v[56:59], v[248:251], v[174:177], v[56:59]
	global_load_dwordx4 v[228:231], v95, s[100:101] offset:1280
	v_mfma_f32_16x16x32_bf16 v[60:63], v[248:251], v[252:255], v[60:63]
	global_load_dwordx4 v[232:235], v109, s[100:101] offset:1280
	s_waitcnt lgkmcnt(0)
	s_barrier
	ds_read_b128 v[112:115], v239 offset:32768
	ds_read_b128 v[134:137], v241 offset:32768
	ds_read_b128 v[138:141], v241 offset:34816
	ds_read_b128 v[142:145], v241 offset:36864
	ds_read_b128 v[154:157], v241 offset:38912
	ds_read_b128 v[118:121], v239 offset:34816
	ds_read_b128 v[126:129], v239 offset:36864
	ds_read_b128 v[130:133], v239 offset:38912
	s_waitcnt lgkmcnt(6)
	v_mfma_f32_16x16x32_bf16 v[0:3], v[112:115], v[134:137], v[0:3]
	ds_read_b128 v[158:161], v240 offset:32768
	s_waitcnt lgkmcnt(6)
	v_mfma_f32_16x16x32_bf16 v[4:7], v[112:115], v[138:141], v[4:7]
	ds_read_b128 v[166:169], v242 offset:32768
	s_waitcnt lgkmcnt(6)
	v_mfma_f32_16x16x32_bf16 v[8:11], v[112:115], v[142:145], v[8:11]
	ds_read_b128 v[170:173], v242 offset:34816
	s_waitcnt lgkmcnt(6)
	v_mfma_f32_16x16x32_bf16 v[12:15], v[112:115], v[154:157], v[12:15]
	ds_read_b128 v[174:177], v242 offset:36864
	s_waitcnt lgkmcnt(6)
	v_mfma_f32_16x16x32_bf16 v[16:19], v[118:121], v[134:137], v[16:19]
	ds_read_b128 v[252:255], v242 offset:38912
	v_mfma_f32_16x16x32_bf16 v[20:23], v[118:121], v[138:141], v[20:23]
	ds_read_b128 v[162:165], v240 offset:34816
	v_mfma_f32_16x16x32_bf16 v[24:27], v[118:121], v[142:145], v[24:27]
	ds_read_b128 v[244:247], v240 offset:36864
	v_mfma_f32_16x16x32_bf16 v[28:31], v[118:121], v[154:157], v[28:31]
	ds_read_b128 v[248:251], v240 offset:38912
	s_waitcnt lgkmcnt(9)
	v_mfma_f32_16x16x32_bf16 v[32:35], v[126:129], v[134:137], v[32:35]
	v_mfma_f32_16x16x32_bf16 v[36:39], v[126:129], v[138:141], v[36:39]
	v_mfma_f32_16x16x32_bf16 v[40:43], v[126:129], v[142:145], v[40:43]
	v_mfma_f32_16x16x32_bf16 v[44:47], v[126:129], v[154:157], v[44:47]
	s_waitcnt lgkmcnt(8)
	v_mfma_f32_16x16x32_bf16 v[48:51], v[130:133], v[134:137], v[48:51]
	v_mfma_f32_16x16x32_bf16 v[52:55], v[130:133], v[138:141], v[52:55]
	v_mfma_f32_16x16x32_bf16 v[56:59], v[130:133], v[142:145], v[56:59]
	v_mfma_f32_16x16x32_bf16 v[60:63], v[130:133], v[154:157], v[60:63]
	s_waitcnt lgkmcnt(6)
	v_mfma_f32_16x16x32_bf16 v[0:3], v[158:161], v[166:169], v[0:3]
	s_waitcnt vmcnt(0)
	ds_write_b128 v110, v[178:181]
	s_waitcnt lgkmcnt(6)
	v_mfma_f32_16x16x32_bf16 v[4:7], v[158:161], v[170:173], v[4:7]
	ds_write_b128 v110, v[182:185] offset:4096
	s_waitcnt lgkmcnt(6)
	v_mfma_f32_16x16x32_bf16 v[8:11], v[158:161], v[174:177], v[8:11]
	ds_write_b128 v110, v[186:189] offset:8192
	s_waitcnt lgkmcnt(6)
	v_mfma_f32_16x16x32_bf16 v[12:15], v[158:161], v[252:255], v[12:15]
	ds_write_b128 v110, v[190:193] offset:12288
	s_waitcnt lgkmcnt(6)
	v_mfma_f32_16x16x32_bf16 v[16:19], v[162:165], v[166:169], v[16:19]
	ds_write_b128 v110, v[220:223] offset:16384
	v_mfma_f32_16x16x32_bf16 v[20:23], v[162:165], v[170:173], v[20:23]
	ds_write_b128 v110, v[224:227] offset:20480
	v_mfma_f32_16x16x32_bf16 v[24:27], v[162:165], v[174:177], v[24:27]
	ds_write_b128 v110, v[228:231] offset:24576
	v_mfma_f32_16x16x32_bf16 v[28:31], v[162:165], v[252:255], v[28:31]
	ds_write_b128 v110, v[232:235] offset:28672
	s_waitcnt lgkmcnt(9)
	v_mfma_f32_16x16x32_bf16 v[32:35], v[244:247], v[166:169], v[32:35]
	global_load_dwordx4 v[178:181], v93, s[98:99] offset:1408
	v_mfma_f32_16x16x32_bf16 v[36:39], v[244:247], v[170:173], v[36:39]
	global_load_dwordx4 v[182:185], v94, s[98:99] offset:1408
	v_mfma_f32_16x16x32_bf16 v[40:43], v[244:247], v[174:177], v[40:43]
	global_load_dwordx4 v[186:189], v95, s[98:99] offset:1408
	v_mfma_f32_16x16x32_bf16 v[44:47], v[244:247], v[252:255], v[44:47]
	global_load_dwordx4 v[190:193], v109, s[98:99] offset:1408
	s_waitcnt lgkmcnt(8)
	v_mfma_f32_16x16x32_bf16 v[48:51], v[248:251], v[166:169], v[48:51]
	global_load_dwordx4 v[220:223], v93, s[100:101] offset:1408
	v_mfma_f32_16x16x32_bf16 v[52:55], v[248:251], v[170:173], v[52:55]
	global_load_dwordx4 v[224:227], v94, s[100:101] offset:1408
	v_mfma_f32_16x16x32_bf16 v[56:59], v[248:251], v[174:177], v[56:59]
	global_load_dwordx4 v[228:231], v95, s[100:101] offset:1408
	v_mfma_f32_16x16x32_bf16 v[60:63], v[248:251], v[252:255], v[60:63]
	global_load_dwordx4 v[232:235], v109, s[100:101] offset:1408
	s_waitcnt lgkmcnt(0)
	s_barrier
	ds_read_b128 v[112:115], v239
	ds_read_b128 v[134:137], v241
	ds_read_b128 v[138:141], v241 offset:2048
	ds_read_b128 v[142:145], v241 offset:4096
	ds_read_b128 v[154:157], v241 offset:6144
	ds_read_b128 v[118:121], v239 offset:2048
	ds_read_b128 v[126:129], v239 offset:4096
	ds_read_b128 v[130:133], v239 offset:6144
	s_waitcnt lgkmcnt(6)
	v_mfma_f32_16x16x32_bf16 v[0:3], v[112:115], v[134:137], v[0:3]
	ds_read_b128 v[158:161], v240
	s_waitcnt lgkmcnt(6)
	v_mfma_f32_16x16x32_bf16 v[4:7], v[112:115], v[138:141], v[4:7]
	ds_read_b128 v[166:169], v242
	s_waitcnt lgkmcnt(6)
	v_mfma_f32_16x16x32_bf16 v[8:11], v[112:115], v[142:145], v[8:11]
	ds_read_b128 v[170:173], v242 offset:2048
	s_waitcnt lgkmcnt(6)
	v_mfma_f32_16x16x32_bf16 v[12:15], v[112:115], v[154:157], v[12:15]
	ds_read_b128 v[174:177], v242 offset:4096
	s_waitcnt lgkmcnt(6)
	v_mfma_f32_16x16x32_bf16 v[16:19], v[118:121], v[134:137], v[16:19]
	ds_read_b128 v[252:255], v242 offset:6144
	v_mfma_f32_16x16x32_bf16 v[20:23], v[118:121], v[138:141], v[20:23]
	ds_read_b128 v[162:165], v240 offset:2048
	v_mfma_f32_16x16x32_bf16 v[24:27], v[118:121], v[142:145], v[24:27]
	ds_read_b128 v[244:247], v240 offset:4096
	v_mfma_f32_16x16x32_bf16 v[28:31], v[118:121], v[154:157], v[28:31]
	ds_read_b128 v[248:251], v240 offset:6144
	s_waitcnt lgkmcnt(9)
	v_mfma_f32_16x16x32_bf16 v[32:35], v[126:129], v[134:137], v[32:35]
	v_mfma_f32_16x16x32_bf16 v[36:39], v[126:129], v[138:141], v[36:39]
	v_mfma_f32_16x16x32_bf16 v[40:43], v[126:129], v[142:145], v[40:43]
	v_mfma_f32_16x16x32_bf16 v[44:47], v[126:129], v[154:157], v[44:47]
	s_waitcnt lgkmcnt(8)
	v_mfma_f32_16x16x32_bf16 v[48:51], v[130:133], v[134:137], v[48:51]
	v_mfma_f32_16x16x32_bf16 v[52:55], v[130:133], v[138:141], v[52:55]
	v_mfma_f32_16x16x32_bf16 v[56:59], v[130:133], v[142:145], v[56:59]
	v_mfma_f32_16x16x32_bf16 v[60:63], v[130:133], v[154:157], v[60:63]
	s_waitcnt lgkmcnt(6)
	v_mfma_f32_16x16x32_bf16 v[0:3], v[158:161], v[166:169], v[0:3]
	s_waitcnt vmcnt(0)
	ds_write_b128 v110, v[178:181] offset:32768
	s_waitcnt lgkmcnt(6)
	v_mfma_f32_16x16x32_bf16 v[4:7], v[158:161], v[170:173], v[4:7]
	ds_write_b128 v110, v[182:185] offset:36864
	s_waitcnt lgkmcnt(6)
	v_mfma_f32_16x16x32_bf16 v[8:11], v[158:161], v[174:177], v[8:11]
	ds_write_b128 v110, v[186:189] offset:40960
	s_waitcnt lgkmcnt(6)
	v_mfma_f32_16x16x32_bf16 v[12:15], v[158:161], v[252:255], v[12:15]
	ds_write_b128 v110, v[190:193] offset:45056
	s_waitcnt lgkmcnt(6)
	v_mfma_f32_16x16x32_bf16 v[16:19], v[162:165], v[166:169], v[16:19]
	ds_write_b128 v110, v[220:223] offset:49152
	v_mfma_f32_16x16x32_bf16 v[20:23], v[162:165], v[170:173], v[20:23]
	ds_write_b128 v110, v[224:227] offset:53248
	v_mfma_f32_16x16x32_bf16 v[24:27], v[162:165], v[174:177], v[24:27]
	ds_write_b128 v110, v[228:231] offset:57344
	v_mfma_f32_16x16x32_bf16 v[28:31], v[162:165], v[252:255], v[28:31]
	ds_write_b128 v110, v[232:235] offset:61440
	s_waitcnt lgkmcnt(9)
	v_mfma_f32_16x16x32_bf16 v[32:35], v[244:247], v[166:169], v[32:35]
	global_load_dwordx4 v[178:181], v93, s[98:99] offset:1536
	v_mfma_f32_16x16x32_bf16 v[36:39], v[244:247], v[170:173], v[36:39]
	global_load_dwordx4 v[182:185], v94, s[98:99] offset:1536
	v_mfma_f32_16x16x32_bf16 v[40:43], v[244:247], v[174:177], v[40:43]
	global_load_dwordx4 v[186:189], v95, s[98:99] offset:1536
	v_mfma_f32_16x16x32_bf16 v[44:47], v[244:247], v[252:255], v[44:47]
	global_load_dwordx4 v[190:193], v109, s[98:99] offset:1536
	s_waitcnt lgkmcnt(8)
	v_mfma_f32_16x16x32_bf16 v[48:51], v[248:251], v[166:169], v[48:51]
	global_load_dwordx4 v[220:223], v93, s[100:101] offset:1536
	v_mfma_f32_16x16x32_bf16 v[52:55], v[248:251], v[170:173], v[52:55]
	global_load_dwordx4 v[224:227], v94, s[100:101] offset:1536
	v_mfma_f32_16x16x32_bf16 v[56:59], v[248:251], v[174:177], v[56:59]
	global_load_dwordx4 v[228:231], v95, s[100:101] offset:1536
	v_mfma_f32_16x16x32_bf16 v[60:63], v[248:251], v[252:255], v[60:63]
	global_load_dwordx4 v[232:235], v109, s[100:101] offset:1536
	s_waitcnt lgkmcnt(0)
	s_barrier
	ds_read_b128 v[112:115], v239 offset:32768
	ds_read_b128 v[134:137], v241 offset:32768
	ds_read_b128 v[138:141], v241 offset:34816
	ds_read_b128 v[142:145], v241 offset:36864
	ds_read_b128 v[154:157], v241 offset:38912
	ds_read_b128 v[118:121], v239 offset:34816
	ds_read_b128 v[126:129], v239 offset:36864
	ds_read_b128 v[130:133], v239 offset:38912
	s_waitcnt lgkmcnt(6)
	v_mfma_f32_16x16x32_bf16 v[0:3], v[112:115], v[134:137], v[0:3]
	ds_read_b128 v[158:161], v240 offset:32768
	s_waitcnt lgkmcnt(6)
	v_mfma_f32_16x16x32_bf16 v[4:7], v[112:115], v[138:141], v[4:7]
	ds_read_b128 v[166:169], v242 offset:32768
	s_waitcnt lgkmcnt(6)
	v_mfma_f32_16x16x32_bf16 v[8:11], v[112:115], v[142:145], v[8:11]
	ds_read_b128 v[170:173], v242 offset:34816
	s_waitcnt lgkmcnt(6)
	v_mfma_f32_16x16x32_bf16 v[12:15], v[112:115], v[154:157], v[12:15]
	ds_read_b128 v[174:177], v242 offset:36864
	s_waitcnt lgkmcnt(6)
	v_mfma_f32_16x16x32_bf16 v[16:19], v[118:121], v[134:137], v[16:19]
	ds_read_b128 v[252:255], v242 offset:38912
	v_mfma_f32_16x16x32_bf16 v[20:23], v[118:121], v[138:141], v[20:23]
	ds_read_b128 v[162:165], v240 offset:34816
	v_mfma_f32_16x16x32_bf16 v[24:27], v[118:121], v[142:145], v[24:27]
	ds_read_b128 v[244:247], v240 offset:36864
	v_mfma_f32_16x16x32_bf16 v[28:31], v[118:121], v[154:157], v[28:31]
	ds_read_b128 v[248:251], v240 offset:38912
	s_waitcnt lgkmcnt(9)
	v_mfma_f32_16x16x32_bf16 v[32:35], v[126:129], v[134:137], v[32:35]
	v_mfma_f32_16x16x32_bf16 v[36:39], v[126:129], v[138:141], v[36:39]
	v_mfma_f32_16x16x32_bf16 v[40:43], v[126:129], v[142:145], v[40:43]
	v_mfma_f32_16x16x32_bf16 v[44:47], v[126:129], v[154:157], v[44:47]
	s_waitcnt lgkmcnt(8)
	v_mfma_f32_16x16x32_bf16 v[48:51], v[130:133], v[134:137], v[48:51]
	v_mfma_f32_16x16x32_bf16 v[52:55], v[130:133], v[138:141], v[52:55]
	v_mfma_f32_16x16x32_bf16 v[56:59], v[130:133], v[142:145], v[56:59]
	v_mfma_f32_16x16x32_bf16 v[60:63], v[130:133], v[154:157], v[60:63]
	s_waitcnt lgkmcnt(6)
	v_mfma_f32_16x16x32_bf16 v[0:3], v[158:161], v[166:169], v[0:3]
	s_waitcnt vmcnt(0)
	ds_write_b128 v110, v[178:181]
	s_waitcnt lgkmcnt(6)
	v_mfma_f32_16x16x32_bf16 v[4:7], v[158:161], v[170:173], v[4:7]
	ds_write_b128 v110, v[182:185] offset:4096
	s_waitcnt lgkmcnt(6)
	v_mfma_f32_16x16x32_bf16 v[8:11], v[158:161], v[174:177], v[8:11]
	ds_write_b128 v110, v[186:189] offset:8192
	s_waitcnt lgkmcnt(6)
	v_mfma_f32_16x16x32_bf16 v[12:15], v[158:161], v[252:255], v[12:15]
	ds_write_b128 v110, v[190:193] offset:12288
	s_waitcnt lgkmcnt(6)
	v_mfma_f32_16x16x32_bf16 v[16:19], v[162:165], v[166:169], v[16:19]
	ds_write_b128 v110, v[220:223] offset:16384
	v_mfma_f32_16x16x32_bf16 v[20:23], v[162:165], v[170:173], v[20:23]
	ds_write_b128 v110, v[224:227] offset:20480
	v_mfma_f32_16x16x32_bf16 v[24:27], v[162:165], v[174:177], v[24:27]
	ds_write_b128 v110, v[228:231] offset:24576
	v_mfma_f32_16x16x32_bf16 v[28:31], v[162:165], v[252:255], v[28:31]
	ds_write_b128 v110, v[232:235] offset:28672
	s_waitcnt lgkmcnt(9)
	v_mfma_f32_16x16x32_bf16 v[32:35], v[244:247], v[166:169], v[32:35]
	global_load_dwordx4 v[178:181], v93, s[98:99] offset:1664
	v_mfma_f32_16x16x32_bf16 v[36:39], v[244:247], v[170:173], v[36:39]
	global_load_dwordx4 v[182:185], v94, s[98:99] offset:1664
	v_mfma_f32_16x16x32_bf16 v[40:43], v[244:247], v[174:177], v[40:43]
	global_load_dwordx4 v[186:189], v95, s[98:99] offset:1664
	v_mfma_f32_16x16x32_bf16 v[44:47], v[244:247], v[252:255], v[44:47]
	global_load_dwordx4 v[190:193], v109, s[98:99] offset:1664
	s_waitcnt lgkmcnt(8)
	v_mfma_f32_16x16x32_bf16 v[48:51], v[248:251], v[166:169], v[48:51]
	global_load_dwordx4 v[220:223], v93, s[100:101] offset:1664
	v_mfma_f32_16x16x32_bf16 v[52:55], v[248:251], v[170:173], v[52:55]
	global_load_dwordx4 v[224:227], v94, s[100:101] offset:1664
	v_mfma_f32_16x16x32_bf16 v[56:59], v[248:251], v[174:177], v[56:59]
	global_load_dwordx4 v[228:231], v95, s[100:101] offset:1664
	v_mfma_f32_16x16x32_bf16 v[60:63], v[248:251], v[252:255], v[60:63]
	global_load_dwordx4 v[232:235], v109, s[100:101] offset:1664
	s_waitcnt lgkmcnt(0)
	s_barrier
	ds_read_b128 v[112:115], v239
	ds_read_b128 v[134:137], v241
	ds_read_b128 v[138:141], v241 offset:2048
	ds_read_b128 v[142:145], v241 offset:4096
	ds_read_b128 v[154:157], v241 offset:6144
	ds_read_b128 v[118:121], v239 offset:2048
	ds_read_b128 v[126:129], v239 offset:4096
	ds_read_b128 v[130:133], v239 offset:6144
	s_waitcnt lgkmcnt(6)
	v_mfma_f32_16x16x32_bf16 v[0:3], v[112:115], v[134:137], v[0:3]
	ds_read_b128 v[158:161], v240
	s_waitcnt lgkmcnt(6)
	v_mfma_f32_16x16x32_bf16 v[4:7], v[112:115], v[138:141], v[4:7]
	ds_read_b128 v[166:169], v242
	s_waitcnt lgkmcnt(6)
	v_mfma_f32_16x16x32_bf16 v[8:11], v[112:115], v[142:145], v[8:11]
	ds_read_b128 v[170:173], v242 offset:2048
	s_waitcnt lgkmcnt(6)
	v_mfma_f32_16x16x32_bf16 v[12:15], v[112:115], v[154:157], v[12:15]
	ds_read_b128 v[174:177], v242 offset:4096
	s_waitcnt lgkmcnt(6)
	v_mfma_f32_16x16x32_bf16 v[16:19], v[118:121], v[134:137], v[16:19]
	ds_read_b128 v[252:255], v242 offset:6144
	v_mfma_f32_16x16x32_bf16 v[20:23], v[118:121], v[138:141], v[20:23]
	ds_read_b128 v[162:165], v240 offset:2048
	v_mfma_f32_16x16x32_bf16 v[24:27], v[118:121], v[142:145], v[24:27]
	ds_read_b128 v[244:247], v240 offset:4096
	v_mfma_f32_16x16x32_bf16 v[28:31], v[118:121], v[154:157], v[28:31]
	ds_read_b128 v[248:251], v240 offset:6144
	s_waitcnt lgkmcnt(9)
	v_mfma_f32_16x16x32_bf16 v[32:35], v[126:129], v[134:137], v[32:35]
	v_mfma_f32_16x16x32_bf16 v[36:39], v[126:129], v[138:141], v[36:39]
	v_mfma_f32_16x16x32_bf16 v[40:43], v[126:129], v[142:145], v[40:43]
	v_mfma_f32_16x16x32_bf16 v[44:47], v[126:129], v[154:157], v[44:47]
	s_waitcnt lgkmcnt(8)
	v_mfma_f32_16x16x32_bf16 v[48:51], v[130:133], v[134:137], v[48:51]
	v_mfma_f32_16x16x32_bf16 v[52:55], v[130:133], v[138:141], v[52:55]
	v_mfma_f32_16x16x32_bf16 v[56:59], v[130:133], v[142:145], v[56:59]
	v_mfma_f32_16x16x32_bf16 v[60:63], v[130:133], v[154:157], v[60:63]
	s_waitcnt lgkmcnt(6)
	v_mfma_f32_16x16x32_bf16 v[0:3], v[158:161], v[166:169], v[0:3]
	s_waitcnt vmcnt(0)
	ds_write_b128 v110, v[178:181] offset:32768
	s_waitcnt lgkmcnt(6)
	v_mfma_f32_16x16x32_bf16 v[4:7], v[158:161], v[170:173], v[4:7]
	ds_write_b128 v110, v[182:185] offset:36864
	s_waitcnt lgkmcnt(6)
	v_mfma_f32_16x16x32_bf16 v[8:11], v[158:161], v[174:177], v[8:11]
	ds_write_b128 v110, v[186:189] offset:40960
	s_waitcnt lgkmcnt(6)
	v_mfma_f32_16x16x32_bf16 v[12:15], v[158:161], v[252:255], v[12:15]
	ds_write_b128 v110, v[190:193] offset:45056
	s_waitcnt lgkmcnt(6)
	v_mfma_f32_16x16x32_bf16 v[16:19], v[162:165], v[166:169], v[16:19]
	ds_write_b128 v110, v[220:223] offset:49152
	v_mfma_f32_16x16x32_bf16 v[20:23], v[162:165], v[170:173], v[20:23]
	ds_write_b128 v110, v[224:227] offset:53248
	v_mfma_f32_16x16x32_bf16 v[24:27], v[162:165], v[174:177], v[24:27]
	ds_write_b128 v110, v[228:231] offset:57344
	v_mfma_f32_16x16x32_bf16 v[28:31], v[162:165], v[252:255], v[28:31]
	ds_write_b128 v110, v[232:235] offset:61440
	s_waitcnt lgkmcnt(9)
	v_mfma_f32_16x16x32_bf16 v[32:35], v[244:247], v[166:169], v[32:35]
	global_load_dwordx4 v[178:181], v93, s[98:99] offset:1792
	v_mfma_f32_16x16x32_bf16 v[36:39], v[244:247], v[170:173], v[36:39]
	global_load_dwordx4 v[182:185], v94, s[98:99] offset:1792
	v_mfma_f32_16x16x32_bf16 v[40:43], v[244:247], v[174:177], v[40:43]
	global_load_dwordx4 v[186:189], v95, s[98:99] offset:1792
	v_mfma_f32_16x16x32_bf16 v[44:47], v[244:247], v[252:255], v[44:47]
	global_load_dwordx4 v[190:193], v109, s[98:99] offset:1792
	s_waitcnt lgkmcnt(8)
	v_mfma_f32_16x16x32_bf16 v[48:51], v[248:251], v[166:169], v[48:51]
	global_load_dwordx4 v[220:223], v93, s[100:101] offset:1792
	v_mfma_f32_16x16x32_bf16 v[52:55], v[248:251], v[170:173], v[52:55]
	global_load_dwordx4 v[224:227], v94, s[100:101] offset:1792
	v_mfma_f32_16x16x32_bf16 v[56:59], v[248:251], v[174:177], v[56:59]
	global_load_dwordx4 v[228:231], v95, s[100:101] offset:1792
	v_mfma_f32_16x16x32_bf16 v[60:63], v[248:251], v[252:255], v[60:63]
	global_load_dwordx4 v[232:235], v109, s[100:101] offset:1792
	s_waitcnt lgkmcnt(0)
	s_barrier
	ds_read_b128 v[112:115], v239 offset:32768
	ds_read_b128 v[134:137], v241 offset:32768
	ds_read_b128 v[138:141], v241 offset:34816
	ds_read_b128 v[142:145], v241 offset:36864
	ds_read_b128 v[154:157], v241 offset:38912
	ds_read_b128 v[118:121], v239 offset:34816
	ds_read_b128 v[126:129], v239 offset:36864
	ds_read_b128 v[130:133], v239 offset:38912
	s_waitcnt lgkmcnt(6)
	v_mfma_f32_16x16x32_bf16 v[0:3], v[112:115], v[134:137], v[0:3]
	ds_read_b128 v[158:161], v240 offset:32768
	s_waitcnt lgkmcnt(6)
	v_mfma_f32_16x16x32_bf16 v[4:7], v[112:115], v[138:141], v[4:7]
	ds_read_b128 v[166:169], v242 offset:32768
	s_waitcnt lgkmcnt(6)
	v_mfma_f32_16x16x32_bf16 v[8:11], v[112:115], v[142:145], v[8:11]
	ds_read_b128 v[170:173], v242 offset:34816
	s_waitcnt lgkmcnt(6)
	v_mfma_f32_16x16x32_bf16 v[12:15], v[112:115], v[154:157], v[12:15]
	ds_read_b128 v[174:177], v242 offset:36864
	s_waitcnt lgkmcnt(6)
	v_mfma_f32_16x16x32_bf16 v[16:19], v[118:121], v[134:137], v[16:19]
	ds_read_b128 v[252:255], v242 offset:38912
	v_mfma_f32_16x16x32_bf16 v[20:23], v[118:121], v[138:141], v[20:23]
	ds_read_b128 v[162:165], v240 offset:34816
	v_mfma_f32_16x16x32_bf16 v[24:27], v[118:121], v[142:145], v[24:27]
	ds_read_b128 v[244:247], v240 offset:36864
	v_mfma_f32_16x16x32_bf16 v[28:31], v[118:121], v[154:157], v[28:31]
	ds_read_b128 v[248:251], v240 offset:38912
	s_waitcnt lgkmcnt(9)
	v_mfma_f32_16x16x32_bf16 v[32:35], v[126:129], v[134:137], v[32:35]
	v_mfma_f32_16x16x32_bf16 v[36:39], v[126:129], v[138:141], v[36:39]
	v_mfma_f32_16x16x32_bf16 v[40:43], v[126:129], v[142:145], v[40:43]
	v_mfma_f32_16x16x32_bf16 v[44:47], v[126:129], v[154:157], v[44:47]
	s_waitcnt lgkmcnt(8)
	v_mfma_f32_16x16x32_bf16 v[48:51], v[130:133], v[134:137], v[48:51]
	v_mfma_f32_16x16x32_bf16 v[52:55], v[130:133], v[138:141], v[52:55]
	v_mfma_f32_16x16x32_bf16 v[56:59], v[130:133], v[142:145], v[56:59]
	v_mfma_f32_16x16x32_bf16 v[60:63], v[130:133], v[154:157], v[60:63]
	s_waitcnt lgkmcnt(6)
	v_mfma_f32_16x16x32_bf16 v[0:3], v[158:161], v[166:169], v[0:3]
	s_waitcnt vmcnt(0)
	ds_write_b128 v110, v[178:181]
	s_waitcnt lgkmcnt(6)
	v_mfma_f32_16x16x32_bf16 v[4:7], v[158:161], v[170:173], v[4:7]
	ds_write_b128 v110, v[182:185] offset:4096
	s_waitcnt lgkmcnt(6)
	v_mfma_f32_16x16x32_bf16 v[8:11], v[158:161], v[174:177], v[8:11]
	ds_write_b128 v110, v[186:189] offset:8192
	s_waitcnt lgkmcnt(6)
	v_mfma_f32_16x16x32_bf16 v[12:15], v[158:161], v[252:255], v[12:15]
	ds_write_b128 v110, v[190:193] offset:12288
	s_waitcnt lgkmcnt(6)
	v_mfma_f32_16x16x32_bf16 v[16:19], v[162:165], v[166:169], v[16:19]
	ds_write_b128 v110, v[220:223] offset:16384
	v_mfma_f32_16x16x32_bf16 v[20:23], v[162:165], v[170:173], v[20:23]
	ds_write_b128 v110, v[224:227] offset:20480
	v_mfma_f32_16x16x32_bf16 v[24:27], v[162:165], v[174:177], v[24:27]
	ds_write_b128 v110, v[228:231] offset:24576
	v_mfma_f32_16x16x32_bf16 v[28:31], v[162:165], v[252:255], v[28:31]
	ds_write_b128 v110, v[232:235] offset:28672
	s_waitcnt lgkmcnt(9)
	v_mfma_f32_16x16x32_bf16 v[32:35], v[244:247], v[166:169], v[32:35]
	global_load_dwordx4 v[178:181], v93, s[98:99] offset:1920
	v_mfma_f32_16x16x32_bf16 v[36:39], v[244:247], v[170:173], v[36:39]
	global_load_dwordx4 v[182:185], v94, s[98:99] offset:1920
	v_mfma_f32_16x16x32_bf16 v[40:43], v[244:247], v[174:177], v[40:43]
	global_load_dwordx4 v[186:189], v95, s[98:99] offset:1920
	v_mfma_f32_16x16x32_bf16 v[44:47], v[244:247], v[252:255], v[44:47]
	global_load_dwordx4 v[190:193], v109, s[98:99] offset:1920
	s_waitcnt lgkmcnt(8)
	v_mfma_f32_16x16x32_bf16 v[48:51], v[248:251], v[166:169], v[48:51]
	global_load_dwordx4 v[220:223], v93, s[100:101] offset:1920
	v_mfma_f32_16x16x32_bf16 v[52:55], v[248:251], v[170:173], v[52:55]
	global_load_dwordx4 v[224:227], v94, s[100:101] offset:1920
	v_mfma_f32_16x16x32_bf16 v[56:59], v[248:251], v[174:177], v[56:59]
	global_load_dwordx4 v[228:231], v95, s[100:101] offset:1920
	v_mfma_f32_16x16x32_bf16 v[60:63], v[248:251], v[252:255], v[60:63]
	global_load_dwordx4 v[232:235], v109, s[100:101] offset:1920
	s_waitcnt lgkmcnt(0)
	s_barrier
	ds_read_b128 v[112:115], v239
	ds_read_b128 v[134:137], v241
	ds_read_b128 v[138:141], v241 offset:2048
	ds_read_b128 v[142:145], v241 offset:4096
	ds_read_b128 v[154:157], v241 offset:6144
	ds_read_b128 v[118:121], v239 offset:2048
	ds_read_b128 v[126:129], v239 offset:4096
	ds_read_b128 v[130:133], v239 offset:6144
	s_waitcnt lgkmcnt(6)
	v_mfma_f32_16x16x32_bf16 v[0:3], v[112:115], v[134:137], v[0:3]
	ds_read_b128 v[158:161], v240
	s_waitcnt lgkmcnt(6)
	v_mfma_f32_16x16x32_bf16 v[4:7], v[112:115], v[138:141], v[4:7]
	ds_read_b128 v[166:169], v242
	s_waitcnt lgkmcnt(6)
	v_mfma_f32_16x16x32_bf16 v[8:11], v[112:115], v[142:145], v[8:11]
	ds_read_b128 v[170:173], v242 offset:2048
	s_waitcnt lgkmcnt(6)
	v_mfma_f32_16x16x32_bf16 v[12:15], v[112:115], v[154:157], v[12:15]
	ds_read_b128 v[174:177], v242 offset:4096
	s_waitcnt lgkmcnt(6)
	v_mfma_f32_16x16x32_bf16 v[16:19], v[118:121], v[134:137], v[16:19]
	ds_read_b128 v[252:255], v242 offset:6144
	v_mfma_f32_16x16x32_bf16 v[20:23], v[118:121], v[138:141], v[20:23]
	ds_read_b128 v[162:165], v240 offset:2048
	v_mfma_f32_16x16x32_bf16 v[24:27], v[118:121], v[142:145], v[24:27]
	ds_read_b128 v[244:247], v240 offset:4096
	v_mfma_f32_16x16x32_bf16 v[28:31], v[118:121], v[154:157], v[28:31]
	ds_read_b128 v[248:251], v240 offset:6144
	s_waitcnt lgkmcnt(9)
	v_mfma_f32_16x16x32_bf16 v[32:35], v[126:129], v[134:137], v[32:35]
	v_mfma_f32_16x16x32_bf16 v[36:39], v[126:129], v[138:141], v[36:39]
	v_mfma_f32_16x16x32_bf16 v[40:43], v[126:129], v[142:145], v[40:43]
	v_mfma_f32_16x16x32_bf16 v[44:47], v[126:129], v[154:157], v[44:47]
	s_waitcnt lgkmcnt(8)
	v_mfma_f32_16x16x32_bf16 v[48:51], v[130:133], v[134:137], v[48:51]
	v_mfma_f32_16x16x32_bf16 v[52:55], v[130:133], v[138:141], v[52:55]
	v_mfma_f32_16x16x32_bf16 v[56:59], v[130:133], v[142:145], v[56:59]
	v_mfma_f32_16x16x32_bf16 v[60:63], v[130:133], v[154:157], v[60:63]
	s_waitcnt lgkmcnt(6)
	v_mfma_f32_16x16x32_bf16 v[0:3], v[158:161], v[166:169], v[0:3]
	s_waitcnt vmcnt(0)
	ds_write_b128 v110, v[178:181] offset:32768
	s_waitcnt lgkmcnt(6)
	v_mfma_f32_16x16x32_bf16 v[4:7], v[158:161], v[170:173], v[4:7]
	ds_write_b128 v110, v[182:185] offset:36864
	s_waitcnt lgkmcnt(6)
	v_mfma_f32_16x16x32_bf16 v[8:11], v[158:161], v[174:177], v[8:11]
	ds_write_b128 v110, v[186:189] offset:40960
	s_waitcnt lgkmcnt(6)
	v_mfma_f32_16x16x32_bf16 v[12:15], v[158:161], v[252:255], v[12:15]
	ds_write_b128 v110, v[190:193] offset:45056
	s_waitcnt lgkmcnt(6)
	v_mfma_f32_16x16x32_bf16 v[16:19], v[162:165], v[166:169], v[16:19]
	ds_write_b128 v110, v[220:223] offset:49152
	v_mfma_f32_16x16x32_bf16 v[20:23], v[162:165], v[170:173], v[20:23]
	ds_write_b128 v110, v[224:227] offset:53248
	v_mfma_f32_16x16x32_bf16 v[24:27], v[162:165], v[174:177], v[24:27]
	ds_write_b128 v110, v[228:231] offset:57344
	v_mfma_f32_16x16x32_bf16 v[28:31], v[162:165], v[252:255], v[28:31]
	ds_write_b128 v110, v[232:235] offset:61440
	s_waitcnt lgkmcnt(9)
	v_mfma_f32_16x16x32_bf16 v[32:35], v[244:247], v[166:169], v[32:35]
	v_mfma_f32_16x16x32_bf16 v[36:39], v[244:247], v[170:173], v[36:39]
	v_mfma_f32_16x16x32_bf16 v[40:43], v[244:247], v[174:177], v[40:43]
	v_mfma_f32_16x16x32_bf16 v[44:47], v[244:247], v[252:255], v[44:47]
	s_waitcnt lgkmcnt(8)
	v_mfma_f32_16x16x32_bf16 v[48:51], v[248:251], v[166:169], v[48:51]
	v_mfma_f32_16x16x32_bf16 v[52:55], v[248:251], v[170:173], v[52:55]
	v_mfma_f32_16x16x32_bf16 v[56:59], v[248:251], v[174:177], v[56:59]
	v_mfma_f32_16x16x32_bf16 v[60:63], v[248:251], v[252:255], v[60:63]
	s_waitcnt lgkmcnt(0)
	s_barrier
	ds_read_b128 v[112:115], v239 offset:32768
	ds_read_b128 v[134:137], v241 offset:32768
	ds_read_b128 v[138:141], v241 offset:34816
	ds_read_b128 v[142:145], v241 offset:36864
	ds_read_b128 v[154:157], v241 offset:38912
	ds_read_b128 v[118:121], v239 offset:34816
	ds_read_b128 v[126:129], v239 offset:36864
	ds_read_b128 v[130:133], v239 offset:38912
	s_waitcnt lgkmcnt(6)
	v_mfma_f32_16x16x32_bf16 v[0:3], v[112:115], v[134:137], v[0:3]
	ds_read_b128 v[158:161], v240 offset:32768
	s_waitcnt lgkmcnt(6)
	v_mfma_f32_16x16x32_bf16 v[4:7], v[112:115], v[138:141], v[4:7]
	ds_read_b128 v[166:169], v242 offset:32768
	s_waitcnt lgkmcnt(6)
	v_mfma_f32_16x16x32_bf16 v[8:11], v[112:115], v[142:145], v[8:11]
	ds_read_b128 v[170:173], v242 offset:34816
	s_waitcnt lgkmcnt(6)
	v_mfma_f32_16x16x32_bf16 v[12:15], v[112:115], v[154:157], v[12:15]
	ds_read_b128 v[174:177], v242 offset:36864
	s_waitcnt lgkmcnt(6)
	v_mfma_f32_16x16x32_bf16 v[16:19], v[118:121], v[134:137], v[16:19]
	ds_read_b128 v[252:255], v242 offset:38912
	v_mfma_f32_16x16x32_bf16 v[20:23], v[118:121], v[138:141], v[20:23]
	ds_read_b128 v[162:165], v240 offset:34816
	v_mfma_f32_16x16x32_bf16 v[24:27], v[118:121], v[142:145], v[24:27]
	ds_read_b128 v[244:247], v240 offset:36864
	v_mfma_f32_16x16x32_bf16 v[28:31], v[118:121], v[154:157], v[28:31]
	ds_read_b128 v[248:251], v240 offset:38912
	s_waitcnt lgkmcnt(9)
	v_mfma_f32_16x16x32_bf16 v[32:35], v[126:129], v[134:137], v[32:35]
	v_mfma_f32_16x16x32_bf16 v[36:39], v[126:129], v[138:141], v[36:39]
	v_mfma_f32_16x16x32_bf16 v[40:43], v[126:129], v[142:145], v[40:43]
	v_mfma_f32_16x16x32_bf16 v[44:47], v[126:129], v[154:157], v[44:47]
	s_waitcnt lgkmcnt(8)
	v_mfma_f32_16x16x32_bf16 v[48:51], v[130:133], v[134:137], v[48:51]
	v_mfma_f32_16x16x32_bf16 v[52:55], v[130:133], v[138:141], v[52:55]
	v_mfma_f32_16x16x32_bf16 v[56:59], v[130:133], v[142:145], v[56:59]
	v_mfma_f32_16x16x32_bf16 v[60:63], v[130:133], v[154:157], v[60:63]
	s_waitcnt lgkmcnt(6)
	v_mfma_f32_16x16x32_bf16 v[0:3], v[158:161], v[166:169], v[0:3]
	s_waitcnt lgkmcnt(5)
	v_mfma_f32_16x16x32_bf16 v[4:7], v[158:161], v[170:173], v[4:7]
	s_waitcnt lgkmcnt(4)
	v_mfma_f32_16x16x32_bf16 v[8:11], v[158:161], v[174:177], v[8:11]
	s_waitcnt lgkmcnt(3)
	v_mfma_f32_16x16x32_bf16 v[12:15], v[158:161], v[252:255], v[12:15]
	s_waitcnt lgkmcnt(2)
	v_mfma_f32_16x16x32_bf16 v[16:19], v[162:165], v[166:169], v[16:19]
	v_mfma_f32_16x16x32_bf16 v[20:23], v[162:165], v[170:173], v[20:23]
	v_mfma_f32_16x16x32_bf16 v[24:27], v[162:165], v[174:177], v[24:27]
	v_mfma_f32_16x16x32_bf16 v[28:31], v[162:165], v[252:255], v[28:31]
	s_waitcnt lgkmcnt(1)
	v_mfma_f32_16x16x32_bf16 v[32:35], v[244:247], v[166:169], v[32:35]
	v_mfma_f32_16x16x32_bf16 v[36:39], v[244:247], v[170:173], v[36:39]
	v_mfma_f32_16x16x32_bf16 v[40:43], v[244:247], v[174:177], v[40:43]
	v_mfma_f32_16x16x32_bf16 v[44:47], v[244:247], v[252:255], v[44:47]
	s_waitcnt lgkmcnt(0)
	v_mfma_f32_16x16x32_bf16 v[48:51], v[248:251], v[166:169], v[48:51]
	v_mfma_f32_16x16x32_bf16 v[52:55], v[248:251], v[170:173], v[52:55]
	v_mfma_f32_16x16x32_bf16 v[56:59], v[248:251], v[174:177], v[56:59]
	v_mfma_f32_16x16x32_bf16 v[60:63], v[248:251], v[252:255], v[60:63]
	s_waitcnt lgkmcnt(0)
	s_barrier
	s_nop 15
	ds_write_b32 v243, v0
	ds_write_b32 v243, v1 offset:528
	ds_write_b32 v243, v2 offset:1056
	ds_write_b32 v243, v3 offset:1584
	ds_write_b32 v243, v4 offset:64
	ds_write_b32 v243, v5 offset:592
	ds_write_b32 v243, v6 offset:1120
	ds_write_b32 v243, v7 offset:1648
	ds_write_b32 v243, v8 offset:128
	ds_write_b32 v243, v9 offset:656
	ds_write_b32 v243, v10 offset:1184
	ds_write_b32 v243, v11 offset:1712
	ds_write_b32 v243, v12 offset:192
	ds_write_b32 v243, v13 offset:720
	ds_write_b32 v243, v14 offset:1248
	ds_write_b32 v243, v15 offset:1776
	ds_write_b32 v243, v16 offset:8448
	ds_write_b32 v243, v17 offset:8976
	ds_write_b32 v243, v18 offset:9504
	ds_write_b32 v243, v19 offset:10032
	ds_write_b32 v243, v20 offset:8512
	ds_write_b32 v243, v21 offset:9040
	ds_write_b32 v243, v22 offset:9568
	ds_write_b32 v243, v23 offset:10096
	ds_write_b32 v243, v24 offset:8576
	ds_write_b32 v243, v25 offset:9104
	ds_write_b32 v243, v26 offset:9632
	ds_write_b32 v243, v27 offset:10160
	ds_write_b32 v243, v28 offset:8640
	ds_write_b32 v243, v29 offset:9168
	ds_write_b32 v243, v30 offset:9696
	ds_write_b32 v243, v31 offset:10224
	ds_write_b32 v243, v32 offset:16896
	ds_write_b32 v243, v33 offset:17424
	ds_write_b32 v243, v34 offset:17952
	ds_write_b32 v243, v35 offset:18480
	ds_write_b32 v243, v36 offset:16960
	ds_write_b32 v243, v37 offset:17488
	ds_write_b32 v243, v38 offset:18016
	ds_write_b32 v243, v39 offset:18544
	ds_write_b32 v243, v40 offset:17024
	ds_write_b32 v243, v41 offset:17552
	ds_write_b32 v243, v42 offset:18080
	ds_write_b32 v243, v43 offset:18608
	ds_write_b32 v243, v44 offset:17088
	ds_write_b32 v243, v45 offset:17616
	ds_write_b32 v243, v46 offset:18144
	ds_write_b32 v243, v47 offset:18672
	ds_write_b32 v243, v48 offset:25344
	ds_write_b32 v243, v49 offset:25872
	ds_write_b32 v243, v50 offset:26400
	ds_write_b32 v243, v51 offset:26928
	ds_write_b32 v243, v52 offset:25408
	ds_write_b32 v243, v53 offset:25936
	ds_write_b32 v243, v54 offset:26464
	ds_write_b32 v243, v55 offset:26992
	ds_write_b32 v243, v56 offset:25472
	ds_write_b32 v243, v57 offset:26000
	ds_write_b32 v243, v58 offset:26528
	ds_write_b32 v243, v59 offset:27056
	ds_write_b32 v243, v60 offset:25536
	ds_write_b32 v243, v61 offset:26064
	ds_write_b32 v243, v62 offset:26592
	ds_write_b32 v243, v63 offset:27120
	v_or_b32_e32 v2, s25, v74
	v_ashrrev_i32_e32 v3, 31, v2
	v_lshl_add_u64 v[0:1], v[2:3], 2, s[54:55]
	v_or_b32_e32 v4, s24, v82
	v_or_b32_e32 v5, s24, v86
	v_or_b32_e32 v6, s24, v89
	v_or_b32_e32 v7, s24, v147
	v_lshlrev_b64 v[2:3], 2, v[2:3]
	v_mov_b32_e32 v8, v84
	v_mov_b32_e32 v9, v90
	v_mov_b32_e32 v10, v87
	v_mov_b32_e32 v11, v83
	s_waitcnt lgkmcnt(0)
	s_barrier

.LBB0_922:
	s_and_b64 vcc, exec, s[10:11]
	s_cbranch_vccz .LBB0_881
	s_ashr_i32 s10, s2, 31
	s_lshr_b32 s10, s10, 29
	s_add_i32 s10, s2, s10
	s_lshl_b32 s11, s10, 4
	s_and_b32 s10, s10, 0x1fffff8
	s_sub_i32 s10, s2, s10
	s_and_b32 s20, s11, 0xffffff80
	s_lshl_b32 s10, s10, 7
	v_add_u32_e32 v0, s20, v105
	v_add_u32_e32 v16, s10, v105
	v_ashrrev_i32_e32 v1, 31, v0
	v_ashrrev_i32_e32 v17, 31, v16
	v_lshlrev_b64 v[0:1], 11, v[0:1]
	v_lshlrev_b64 v[16:17], 11, v[16:17]
	v_lshl_add_u64 v[78:79], v[68:69], 0, v[0:1]
	v_lshl_add_u64 v[80:81], v[76:77], 0, v[16:17]
	v_readfirstlane_b32 s98, v68
	v_readfirstlane_b32 s99, v69
	v_readfirstlane_b32 s100, v76
	v_readfirstlane_b32 s101, v77
	s_lshl_b32 s11, s20, 11
	s_add_u32 s98, s98, s11
	s_addc_u32 s99, s99, 0
	s_lshl_b32 s11, s10, 11
	s_add_u32 s100, s100, s11
	s_addc_u32 s101, s101, 0
	v_lshrrev_b32_e32 v246, 3, v100
	v_and_b32_e32 v247, 7, v100
	v_bfe_u32 v244, v100, 4, 3
	v_xor_b32_e32 v244, v244, v247
	v_lshlrev_b32_e32 v244, 4, v244
	v_lshl_or_b32 v124, v246, 7, v244
	v_lshlrev_b32_e32 v245, 4, v247
	v_lshl_or_b32 v115, v246, 11, v245
	v_add_u32_e32 v116, 0x10000, v115
	v_add_u32_e32 v122, 0x20000, v115
	v_add_u32_e32 v123, 0x30000, v115
	v_and_b32_e32 v244, 15, v100
	v_bfe_u32 v245, v100, 4, 2
	v_bfe_u32 v246, v100, 1, 3
	v_xor_b32_e32 v247, v245, v246
	v_lshlrev_b32_e32 v247, 4, v247
	v_lshl_or_b32 v247, v244, 7, v247
	v_bfe_u32 v246, v100, 7, 1
	v_lshl_add_u32 v239, v246, 13, v247
	v_xor_b32_e32 v240, 64, v239
	v_bfe_u32 v246, v100, 6, 1
	v_lshl_add_u32 v241, v246, 13, v247
	v_add_u32_e32 v241, 0x4000, v241
	v_xor_b32_e32 v242, 64, v241
	v_bfe_u32 v247, v100, 7, 1
	v_lshlrev_b32_e32 v247, 6, v247
	v_lshl_add_u32 v247, v245, 2, v247
	v_mul_u32_u24_e32 v247, 0x84, v247
	v_lshl_add_u32 v247, v246, 6, v247
	v_add_u32_e32 v247, v247, v244
	v_lshlrev_b32_e32 v243, 2, v247
	global_load_dwordx4 v[178:181], v115, s[98:99]
	global_load_dwordx4 v[182:185], v116, s[98:99]
	global_load_dwordx4 v[186:189], v122, s[98:99]
	global_load_dwordx4 v[190:193], v123, s[98:99]
	global_load_dwordx4 v[220:223], v115, s[100:101]
	global_load_dwordx4 v[224:227], v116, s[100:101]
	global_load_dwordx4 v[228:231], v122, s[100:101]
	global_load_dwordx4 v[232:235], v123, s[100:101]
	v_readlane_b32 s44, v238, 32
	v_readlane_b32 s56, v238, 44
	v_readlane_b32 s57, v238, 45
	v_readlane_b32 s58, v238, 46
	v_readlane_b32 s59, v238, 47
	s_mov_b64 s[24:25], s[56:57]
	v_readlane_b32 s45, v238, 33
	v_readlane_b32 s46, v238, 34
	v_readlane_b32 s47, v238, 35
	v_readlane_b32 s48, v238, 36
	v_readlane_b32 s49, v238, 37
	v_readlane_b32 s50, v238, 38
	v_readlane_b32 s51, v238, 39
	v_readlane_b32 s52, v238, 40
	v_readlane_b32 s53, v238, 41
	v_readlane_b32 s54, v238, 42
	v_readlane_b32 s55, v238, 43
	s_mov_b64 s[26:27], s[58:59]
	s_barrier
	s_waitcnt vmcnt(0)
	ds_write_b128 v124, v[178:181]
	ds_write_b128 v124, v[182:185] offset:4096
	ds_write_b128 v124, v[186:189] offset:8192
	ds_write_b128 v124, v[190:193] offset:12288
	ds_write_b128 v124, v[220:223] offset:16384
	ds_write_b128 v124, v[224:227] offset:20480
	ds_write_b128 v124, v[228:231] offset:24576
	ds_write_b128 v124, v[232:235] offset:28672
	global_load_dwordx4 v[178:181], v115, s[98:99] offset:128
	global_load_dwordx4 v[182:185], v116, s[98:99] offset:128
	global_load_dwordx4 v[186:189], v122, s[98:99] offset:128
	global_load_dwordx4 v[190:193], v123, s[98:99] offset:128
	global_load_dwordx4 v[220:223], v115, s[100:101] offset:128
	global_load_dwordx4 v[224:227], v116, s[100:101] offset:128
	global_load_dwordx4 v[228:231], v122, s[100:101] offset:128
	global_load_dwordx4 v[232:235], v123, s[100:101] offset:128
	s_waitcnt lgkmcnt(0)
	s_barrier
	ds_read_b128 v[118:121], v239
	ds_read_b128 v[138:141], v241
	ds_read_b128 v[142:145], v241 offset:2048
	ds_read_b128 v[148:151], v241 offset:4096
	ds_read_b128 v[154:157], v241 offset:6144
	ds_read_b128 v[126:129], v239 offset:2048
	ds_read_b128 v[130:133], v239 offset:4096
	ds_read_b128 v[134:137], v239 offset:6144
	s_waitcnt lgkmcnt(6)
	v_mfma_f32_16x16x32_bf16 v[0:3], v[118:121], v[138:141], 0
	ds_read_b128 v[158:161], v240
	s_waitcnt lgkmcnt(6)
	v_mfma_f32_16x16x32_bf16 v[4:7], v[118:121], v[142:145], 0
	ds_read_b128 v[166:169], v242
	s_waitcnt lgkmcnt(6)
	v_mfma_f32_16x16x32_bf16 v[8:11], v[118:121], v[148:151], 0
	ds_read_b128 v[170:173], v242 offset:2048
	s_waitcnt lgkmcnt(6)
	v_mfma_f32_16x16x32_bf16 v[12:15], v[118:121], v[154:157], 0
	ds_read_b128 v[174:177], v242 offset:4096
	s_waitcnt lgkmcnt(6)
	v_mfma_f32_16x16x32_bf16 v[16:19], v[126:129], v[138:141], 0
	ds_read_b128 v[252:255], v242 offset:6144
	v_mfma_f32_16x16x32_bf16 v[20:23], v[126:129], v[142:145], 0
	ds_read_b128 v[162:165], v240 offset:2048
	v_mfma_f32_16x16x32_bf16 v[24:27], v[126:129], v[148:151], 0
	ds_read_b128 v[244:247], v240 offset:4096
	v_mfma_f32_16x16x32_bf16 v[28:31], v[126:129], v[154:157], 0
	ds_read_b128 v[248:251], v240 offset:6144
	s_waitcnt lgkmcnt(9)
	v_mfma_f32_16x16x32_bf16 v[32:35], v[130:133], v[138:141], 0
	v_mfma_f32_16x16x32_bf16 v[36:39], v[130:133], v[142:145], 0
	v_mfma_f32_16x16x32_bf16 v[40:43], v[130:133], v[148:151], 0
	v_mfma_f32_16x16x32_bf16 v[44:47], v[130:133], v[154:157], 0
	s_waitcnt lgkmcnt(8)
	v_mfma_f32_16x16x32_bf16 v[48:51], v[134:137], v[138:141], 0
	v_mfma_f32_16x16x32_bf16 v[52:55], v[134:137], v[142:145], 0
	v_mfma_f32_16x16x32_bf16 v[56:59], v[134:137], v[148:151], 0
	v_mfma_f32_16x16x32_bf16 v[60:63], v[134:137], v[154:157], 0
	s_waitcnt lgkmcnt(6)
	v_mfma_f32_16x16x32_bf16 v[0:3], v[158:161], v[166:169], v[0:3]
	s_waitcnt vmcnt(0)
	ds_write_b128 v124, v[178:181] offset:32768
	s_waitcnt lgkmcnt(6)
	v_mfma_f32_16x16x32_bf16 v[4:7], v[158:161], v[170:173], v[4:7]
	ds_write_b128 v124, v[182:185] offset:36864
	s_waitcnt lgkmcnt(6)
	v_mfma_f32_16x16x32_bf16 v[8:11], v[158:161], v[174:177], v[8:11]
	ds_write_b128 v124, v[186:189] offset:40960
	s_waitcnt lgkmcnt(6)
	v_mfma_f32_16x16x32_bf16 v[12:15], v[158:161], v[252:255], v[12:15]
	ds_write_b128 v124, v[190:193] offset:45056
	s_waitcnt lgkmcnt(6)
	v_mfma_f32_16x16x32_bf16 v[16:19], v[162:165], v[166:169], v[16:19]
	ds_write_b128 v124, v[220:223] offset:49152
	v_mfma_f32_16x16x32_bf16 v[20:23], v[162:165], v[170:173], v[20:23]
	ds_write_b128 v124, v[224:227] offset:53248
	v_mfma_f32_16x16x32_bf16 v[24:27], v[162:165], v[174:177], v[24:27]
	ds_write_b128 v124, v[228:231] offset:57344
	v_mfma_f32_16x16x32_bf16 v[28:31], v[162:165], v[252:255], v[28:31]
	ds_write_b128 v124, v[232:235] offset:61440
	s_waitcnt lgkmcnt(9)
	v_mfma_f32_16x16x32_bf16 v[32:35], v[244:247], v[166:169], v[32:35]
	global_load_dwordx4 v[178:181], v115, s[98:99] offset:256
	v_mfma_f32_16x16x32_bf16 v[36:39], v[244:247], v[170:173], v[36:39]
	global_load_dwordx4 v[182:185], v116, s[98:99] offset:256
	v_mfma_f32_16x16x32_bf16 v[40:43], v[244:247], v[174:177], v[40:43]
	global_load_dwordx4 v[186:189], v122, s[98:99] offset:256
	v_mfma_f32_16x16x32_bf16 v[44:47], v[244:247], v[252:255], v[44:47]
	global_load_dwordx4 v[190:193], v123, s[98:99] offset:256
	s_waitcnt lgkmcnt(8)
	v_mfma_f32_16x16x32_bf16 v[48:51], v[248:251], v[166:169], v[48:51]
	global_load_dwordx4 v[220:223], v115, s[100:101] offset:256
	v_mfma_f32_16x16x32_bf16 v[52:55], v[248:251], v[170:173], v[52:55]
	global_load_dwordx4 v[224:227], v116, s[100:101] offset:256
	v_mfma_f32_16x16x32_bf16 v[56:59], v[248:251], v[174:177], v[56:59]
	global_load_dwordx4 v[228:231], v122, s[100:101] offset:256
	v_mfma_f32_16x16x32_bf16 v[60:63], v[248:251], v[252:255], v[60:63]
	global_load_dwordx4 v[232:235], v123, s[100:101] offset:256
	s_waitcnt lgkmcnt(0)
	s_barrier
	ds_read_b128 v[118:121], v239 offset:32768
	ds_read_b128 v[138:141], v241 offset:32768
	ds_read_b128 v[142:145], v241 offset:34816
	ds_read_b128 v[148:151], v241 offset:36864
	ds_read_b128 v[154:157], v241 offset:38912
	ds_read_b128 v[126:129], v239 offset:34816
	ds_read_b128 v[130:133], v239 offset:36864
	ds_read_b128 v[134:137], v239 offset:38912
	s_waitcnt lgkmcnt(6)
	v_mfma_f32_16x16x32_bf16 v[0:3], v[118:121], v[138:141], v[0:3]
	ds_read_b128 v[158:161], v240 offset:32768
	s_waitcnt lgkmcnt(6)
	v_mfma_f32_16x16x32_bf16 v[4:7], v[118:121], v[142:145], v[4:7]
	ds_read_b128 v[166:169], v242 offset:32768
	s_waitcnt lgkmcnt(6)
	v_mfma_f32_16x16x32_bf16 v[8:11], v[118:121], v[148:151], v[8:11]
	ds_read_b128 v[170:173], v242 offset:34816
	s_waitcnt lgkmcnt(6)
	v_mfma_f32_16x16x32_bf16 v[12:15], v[118:121], v[154:157], v[12:15]
	ds_read_b128 v[174:177], v242 offset:36864
	s_waitcnt lgkmcnt(6)
	v_mfma_f32_16x16x32_bf16 v[16:19], v[126:129], v[138:141], v[16:19]
	ds_read_b128 v[252:255], v242 offset:38912
	v_mfma_f32_16x16x32_bf16 v[20:23], v[126:129], v[142:145], v[20:23]
	ds_read_b128 v[162:165], v240 offset:34816
	v_mfma_f32_16x16x32_bf16 v[24:27], v[126:129], v[148:151], v[24:27]
	ds_read_b128 v[244:247], v240 offset:36864
	v_mfma_f32_16x16x32_bf16 v[28:31], v[126:129], v[154:157], v[28:31]
	ds_read_b128 v[248:251], v240 offset:38912
	s_waitcnt lgkmcnt(9)
	v_mfma_f32_16x16x32_bf16 v[32:35], v[130:133], v[138:141], v[32:35]
	v_mfma_f32_16x16x32_bf16 v[36:39], v[130:133], v[142:145], v[36:39]
	v_mfma_f32_16x16x32_bf16 v[40:43], v[130:133], v[148:151], v[40:43]
	v_mfma_f32_16x16x32_bf16 v[44:47], v[130:133], v[154:157], v[44:47]
	s_waitcnt lgkmcnt(8)
	v_mfma_f32_16x16x32_bf16 v[48:51], v[134:137], v[138:141], v[48:51]
	v_mfma_f32_16x16x32_bf16 v[52:55], v[134:137], v[142:145], v[52:55]
	v_mfma_f32_16x16x32_bf16 v[56:59], v[134:137], v[148:151], v[56:59]
	v_mfma_f32_16x16x32_bf16 v[60:63], v[134:137], v[154:157], v[60:63]
	s_waitcnt lgkmcnt(6)
	v_mfma_f32_16x16x32_bf16 v[0:3], v[158:161], v[166:169], v[0:3]
	s_waitcnt vmcnt(0)
	ds_write_b128 v124, v[178:181]
	s_waitcnt lgkmcnt(6)
	v_mfma_f32_16x16x32_bf16 v[4:7], v[158:161], v[170:173], v[4:7]
	ds_write_b128 v124, v[182:185] offset:4096
	s_waitcnt lgkmcnt(6)
	v_mfma_f32_16x16x32_bf16 v[8:11], v[158:161], v[174:177], v[8:11]
	ds_write_b128 v124, v[186:189] offset:8192
	s_waitcnt lgkmcnt(6)
	v_mfma_f32_16x16x32_bf16 v[12:15], v[158:161], v[252:255], v[12:15]
	ds_write_b128 v124, v[190:193] offset:12288
	s_waitcnt lgkmcnt(6)
	v_mfma_f32_16x16x32_bf16 v[16:19], v[162:165], v[166:169], v[16:19]
	ds_write_b128 v124, v[220:223] offset:16384
	v_mfma_f32_16x16x32_bf16 v[20:23], v[162:165], v[170:173], v[20:23]
	ds_write_b128 v124, v[224:227] offset:20480
	v_mfma_f32_16x16x32_bf16 v[24:27], v[162:165], v[174:177], v[24:27]
	ds_write_b128 v124, v[228:231] offset:24576
	v_mfma_f32_16x16x32_bf16 v[28:31], v[162:165], v[252:255], v[28:31]
	ds_write_b128 v124, v[232:235] offset:28672
	s_waitcnt lgkmcnt(9)
	v_mfma_f32_16x16x32_bf16 v[32:35], v[244:247], v[166:169], v[32:35]
	global_load_dwordx4 v[178:181], v115, s[98:99] offset:384
	v_mfma_f32_16x16x32_bf16 v[36:39], v[244:247], v[170:173], v[36:39]
	global_load_dwordx4 v[182:185], v116, s[98:99] offset:384
	v_mfma_f32_16x16x32_bf16 v[40:43], v[244:247], v[174:177], v[40:43]
	global_load_dwordx4 v[186:189], v122, s[98:99] offset:384
	v_mfma_f32_16x16x32_bf16 v[44:47], v[244:247], v[252:255], v[44:47]
	global_load_dwordx4 v[190:193], v123, s[98:99] offset:384
	s_waitcnt lgkmcnt(8)
	v_mfma_f32_16x16x32_bf16 v[48:51], v[248:251], v[166:169], v[48:51]
	global_load_dwordx4 v[220:223], v115, s[100:101] offset:384
	v_mfma_f32_16x16x32_bf16 v[52:55], v[248:251], v[170:173], v[52:55]
	global_load_dwordx4 v[224:227], v116, s[100:101] offset:384
	v_mfma_f32_16x16x32_bf16 v[56:59], v[248:251], v[174:177], v[56:59]
	global_load_dwordx4 v[228:231], v122, s[100:101] offset:384
	v_mfma_f32_16x16x32_bf16 v[60:63], v[248:251], v[252:255], v[60:63]
	global_load_dwordx4 v[232:235], v123, s[100:101] offset:384
	s_waitcnt lgkmcnt(0)
	s_barrier
	ds_read_b128 v[118:121], v239
	ds_read_b128 v[138:141], v241
	ds_read_b128 v[142:145], v241 offset:2048
	ds_read_b128 v[148:151], v241 offset:4096
	ds_read_b128 v[154:157], v241 offset:6144
	ds_read_b128 v[126:129], v239 offset:2048
	ds_read_b128 v[130:133], v239 offset:4096
	ds_read_b128 v[134:137], v239 offset:6144
	s_waitcnt lgkmcnt(6)
	v_mfma_f32_16x16x32_bf16 v[0:3], v[118:121], v[138:141], v[0:3]
	ds_read_b128 v[158:161], v240
	s_waitcnt lgkmcnt(6)
	v_mfma_f32_16x16x32_bf16 v[4:7], v[118:121], v[142:145], v[4:7]
	ds_read_b128 v[166:169], v242
	s_waitcnt lgkmcnt(6)
	v_mfma_f32_16x16x32_bf16 v[8:11], v[118:121], v[148:151], v[8:11]
	ds_read_b128 v[170:173], v242 offset:2048
	s_waitcnt lgkmcnt(6)
	v_mfma_f32_16x16x32_bf16 v[12:15], v[118:121], v[154:157], v[12:15]
	ds_read_b128 v[174:177], v242 offset:4096
	s_waitcnt lgkmcnt(6)
	v_mfma_f32_16x16x32_bf16 v[16:19], v[126:129], v[138:141], v[16:19]
	ds_read_b128 v[252:255], v242 offset:6144
	v_mfma_f32_16x16x32_bf16 v[20:23], v[126:129], v[142:145], v[20:23]
	ds_read_b128 v[162:165], v240 offset:2048
	v_mfma_f32_16x16x32_bf16 v[24:27], v[126:129], v[148:151], v[24:27]
	ds_read_b128 v[244:247], v240 offset:4096
	v_mfma_f32_16x16x32_bf16 v[28:31], v[126:129], v[154:157], v[28:31]
	ds_read_b128 v[248:251], v240 offset:6144
	s_waitcnt lgkmcnt(9)
	v_mfma_f32_16x16x32_bf16 v[32:35], v[130:133], v[138:141], v[32:35]
	v_mfma_f32_16x16x32_bf16 v[36:39], v[130:133], v[142:145], v[36:39]
	v_mfma_f32_16x16x32_bf16 v[40:43], v[130:133], v[148:151], v[40:43]
	v_mfma_f32_16x16x32_bf16 v[44:47], v[130:133], v[154:157], v[44:47]
	s_waitcnt lgkmcnt(8)
	v_mfma_f32_16x16x32_bf16 v[48:51], v[134:137], v[138:141], v[48:51]
	v_mfma_f32_16x16x32_bf16 v[52:55], v[134:137], v[142:145], v[52:55]
	v_mfma_f32_16x16x32_bf16 v[56:59], v[134:137], v[148:151], v[56:59]
	v_mfma_f32_16x16x32_bf16 v[60:63], v[134:137], v[154:157], v[60:63]
	s_waitcnt lgkmcnt(6)
	v_mfma_f32_16x16x32_bf16 v[0:3], v[158:161], v[166:169], v[0:3]
	s_waitcnt vmcnt(0)
	ds_write_b128 v124, v[178:181] offset:32768
	s_waitcnt lgkmcnt(6)
	v_mfma_f32_16x16x32_bf16 v[4:7], v[158:161], v[170:173], v[4:7]
	ds_write_b128 v124, v[182:185] offset:36864
	s_waitcnt lgkmcnt(6)
	v_mfma_f32_16x16x32_bf16 v[8:11], v[158:161], v[174:177], v[8:11]
	ds_write_b128 v124, v[186:189] offset:40960
	s_waitcnt lgkmcnt(6)
	v_mfma_f32_16x16x32_bf16 v[12:15], v[158:161], v[252:255], v[12:15]
	ds_write_b128 v124, v[190:193] offset:45056
	s_waitcnt lgkmcnt(6)
	v_mfma_f32_16x16x32_bf16 v[16:19], v[162:165], v[166:169], v[16:19]
	ds_write_b128 v124, v[220:223] offset:49152
	v_mfma_f32_16x16x32_bf16 v[20:23], v[162:165], v[170:173], v[20:23]
	ds_write_b128 v124, v[224:227] offset:53248
	v_mfma_f32_16x16x32_bf16 v[24:27], v[162:165], v[174:177], v[24:27]
	ds_write_b128 v124, v[228:231] offset:57344
	v_mfma_f32_16x16x32_bf16 v[28:31], v[162:165], v[252:255], v[28:31]
	ds_write_b128 v124, v[232:235] offset:61440
	s_waitcnt lgkmcnt(9)
	v_mfma_f32_16x16x32_bf16 v[32:35], v[244:247], v[166:169], v[32:35]
	global_load_dwordx4 v[178:181], v115, s[98:99] offset:512
	v_mfma_f32_16x16x32_bf16 v[36:39], v[244:247], v[170:173], v[36:39]
	global_load_dwordx4 v[182:185], v116, s[98:99] offset:512
	v_mfma_f32_16x16x32_bf16 v[40:43], v[244:247], v[174:177], v[40:43]
	global_load_dwordx4 v[186:189], v122, s[98:99] offset:512
	v_mfma_f32_16x16x32_bf16 v[44:47], v[244:247], v[252:255], v[44:47]
	global_load_dwordx4 v[190:193], v123, s[98:99] offset:512
	s_waitcnt lgkmcnt(8)
	v_mfma_f32_16x16x32_bf16 v[48:51], v[248:251], v[166:169], v[48:51]
	global_load_dwordx4 v[220:223], v115, s[100:101] offset:512
	v_mfma_f32_16x16x32_bf16 v[52:55], v[248:251], v[170:173], v[52:55]
	global_load_dwordx4 v[224:227], v116, s[100:101] offset:512
	v_mfma_f32_16x16x32_bf16 v[56:59], v[248:251], v[174:177], v[56:59]
	global_load_dwordx4 v[228:231], v122, s[100:101] offset:512
	v_mfma_f32_16x16x32_bf16 v[60:63], v[248:251], v[252:255], v[60:63]
	global_load_dwordx4 v[232:235], v123, s[100:101] offset:512
	s_waitcnt lgkmcnt(0)
	s_barrier
	ds_read_b128 v[118:121], v239 offset:32768
	ds_read_b128 v[138:141], v241 offset:32768
	ds_read_b128 v[142:145], v241 offset:34816
	ds_read_b128 v[148:151], v241 offset:36864
	ds_read_b128 v[154:157], v241 offset:38912
	ds_read_b128 v[126:129], v239 offset:34816
	ds_read_b128 v[130:133], v239 offset:36864
	ds_read_b128 v[134:137], v239 offset:38912
	s_waitcnt lgkmcnt(6)
	v_mfma_f32_16x16x32_bf16 v[0:3], v[118:121], v[138:141], v[0:3]
	ds_read_b128 v[158:161], v240 offset:32768
	s_waitcnt lgkmcnt(6)
	v_mfma_f32_16x16x32_bf16 v[4:7], v[118:121], v[142:145], v[4:7]
	ds_read_b128 v[166:169], v242 offset:32768
	s_waitcnt lgkmcnt(6)
	v_mfma_f32_16x16x32_bf16 v[8:11], v[118:121], v[148:151], v[8:11]
	ds_read_b128 v[170:173], v242 offset:34816
	s_waitcnt lgkmcnt(6)
	v_mfma_f32_16x16x32_bf16 v[12:15], v[118:121], v[154:157], v[12:15]
	ds_read_b128 v[174:177], v242 offset:36864
	s_waitcnt lgkmcnt(6)
	v_mfma_f32_16x16x32_bf16 v[16:19], v[126:129], v[138:141], v[16:19]
	ds_read_b128 v[252:255], v242 offset:38912
	v_mfma_f32_16x16x32_bf16 v[20:23], v[126:129], v[142:145], v[20:23]
	ds_read_b128 v[162:165], v240 offset:34816
	v_mfma_f32_16x16x32_bf16 v[24:27], v[126:129], v[148:151], v[24:27]
	ds_read_b128 v[244:247], v240 offset:36864
	v_mfma_f32_16x16x32_bf16 v[28:31], v[126:129], v[154:157], v[28:31]
	ds_read_b128 v[248:251], v240 offset:38912
	s_waitcnt lgkmcnt(9)
	v_mfma_f32_16x16x32_bf16 v[32:35], v[130:133], v[138:141], v[32:35]
	v_mfma_f32_16x16x32_bf16 v[36:39], v[130:133], v[142:145], v[36:39]
	v_mfma_f32_16x16x32_bf16 v[40:43], v[130:133], v[148:151], v[40:43]
	v_mfma_f32_16x16x32_bf16 v[44:47], v[130:133], v[154:157], v[44:47]
	s_waitcnt lgkmcnt(8)
	v_mfma_f32_16x16x32_bf16 v[48:51], v[134:137], v[138:141], v[48:51]
	v_mfma_f32_16x16x32_bf16 v[52:55], v[134:137], v[142:145], v[52:55]
	v_mfma_f32_16x16x32_bf16 v[56:59], v[134:137], v[148:151], v[56:59]
	v_mfma_f32_16x16x32_bf16 v[60:63], v[134:137], v[154:157], v[60:63]
	s_waitcnt lgkmcnt(6)
	v_mfma_f32_16x16x32_bf16 v[0:3], v[158:161], v[166:169], v[0:3]
	s_waitcnt vmcnt(0)
	ds_write_b128 v124, v[178:181]
	s_waitcnt lgkmcnt(6)
	v_mfma_f32_16x16x32_bf16 v[4:7], v[158:161], v[170:173], v[4:7]
	ds_write_b128 v124, v[182:185] offset:4096
	s_waitcnt lgkmcnt(6)
	v_mfma_f32_16x16x32_bf16 v[8:11], v[158:161], v[174:177], v[8:11]
	ds_write_b128 v124, v[186:189] offset:8192
	s_waitcnt lgkmcnt(6)
	v_mfma_f32_16x16x32_bf16 v[12:15], v[158:161], v[252:255], v[12:15]
	ds_write_b128 v124, v[190:193] offset:12288
	s_waitcnt lgkmcnt(6)
	v_mfma_f32_16x16x32_bf16 v[16:19], v[162:165], v[166:169], v[16:19]
	ds_write_b128 v124, v[220:223] offset:16384
	v_mfma_f32_16x16x32_bf16 v[20:23], v[162:165], v[170:173], v[20:23]
	ds_write_b128 v124, v[224:227] offset:20480
	v_mfma_f32_16x16x32_bf16 v[24:27], v[162:165], v[174:177], v[24:27]
	ds_write_b128 v124, v[228:231] offset:24576
	v_mfma_f32_16x16x32_bf16 v[28:31], v[162:165], v[252:255], v[28:31]
	ds_write_b128 v124, v[232:235] offset:28672
	s_waitcnt lgkmcnt(9)
	v_mfma_f32_16x16x32_bf16 v[32:35], v[244:247], v[166:169], v[32:35]
	global_load_dwordx4 v[178:181], v115, s[98:99] offset:640
	v_mfma_f32_16x16x32_bf16 v[36:39], v[244:247], v[170:173], v[36:39]
	global_load_dwordx4 v[182:185], v116, s[98:99] offset:640
	v_mfma_f32_16x16x32_bf16 v[40:43], v[244:247], v[174:177], v[40:43]
	global_load_dwordx4 v[186:189], v122, s[98:99] offset:640
	v_mfma_f32_16x16x32_bf16 v[44:47], v[244:247], v[252:255], v[44:47]
	global_load_dwordx4 v[190:193], v123, s[98:99] offset:640
	s_waitcnt lgkmcnt(8)
	v_mfma_f32_16x16x32_bf16 v[48:51], v[248:251], v[166:169], v[48:51]
	global_load_dwordx4 v[220:223], v115, s[100:101] offset:640
	v_mfma_f32_16x16x32_bf16 v[52:55], v[248:251], v[170:173], v[52:55]
	global_load_dwordx4 v[224:227], v116, s[100:101] offset:640
	v_mfma_f32_16x16x32_bf16 v[56:59], v[248:251], v[174:177], v[56:59]
	global_load_dwordx4 v[228:231], v122, s[100:101] offset:640
	v_mfma_f32_16x16x32_bf16 v[60:63], v[248:251], v[252:255], v[60:63]
	global_load_dwordx4 v[232:235], v123, s[100:101] offset:640
	s_waitcnt lgkmcnt(0)
	s_barrier
	ds_read_b128 v[118:121], v239
	ds_read_b128 v[138:141], v241
	ds_read_b128 v[142:145], v241 offset:2048
	ds_read_b128 v[148:151], v241 offset:4096
	ds_read_b128 v[154:157], v241 offset:6144
	ds_read_b128 v[126:129], v239 offset:2048
	ds_read_b128 v[130:133], v239 offset:4096
	ds_read_b128 v[134:137], v239 offset:6144
	s_waitcnt lgkmcnt(6)
	v_mfma_f32_16x16x32_bf16 v[0:3], v[118:121], v[138:141], v[0:3]
	ds_read_b128 v[158:161], v240
	s_waitcnt lgkmcnt(6)
	v_mfma_f32_16x16x32_bf16 v[4:7], v[118:121], v[142:145], v[4:7]
	ds_read_b128 v[166:169], v242
	s_waitcnt lgkmcnt(6)
	v_mfma_f32_16x16x32_bf16 v[8:11], v[118:121], v[148:151], v[8:11]
	ds_read_b128 v[170:173], v242 offset:2048
	s_waitcnt lgkmcnt(6)
	v_mfma_f32_16x16x32_bf16 v[12:15], v[118:121], v[154:157], v[12:15]
	ds_read_b128 v[174:177], v242 offset:4096
	s_waitcnt lgkmcnt(6)
	v_mfma_f32_16x16x32_bf16 v[16:19], v[126:129], v[138:141], v[16:19]
	ds_read_b128 v[252:255], v242 offset:6144
	v_mfma_f32_16x16x32_bf16 v[20:23], v[126:129], v[142:145], v[20:23]
	ds_read_b128 v[162:165], v240 offset:2048
	v_mfma_f32_16x16x32_bf16 v[24:27], v[126:129], v[148:151], v[24:27]
	ds_read_b128 v[244:247], v240 offset:4096
	v_mfma_f32_16x16x32_bf16 v[28:31], v[126:129], v[154:157], v[28:31]
	ds_read_b128 v[248:251], v240 offset:6144
	s_waitcnt lgkmcnt(9)
	v_mfma_f32_16x16x32_bf16 v[32:35], v[130:133], v[138:141], v[32:35]
	v_mfma_f32_16x16x32_bf16 v[36:39], v[130:133], v[142:145], v[36:39]
	v_mfma_f32_16x16x32_bf16 v[40:43], v[130:133], v[148:151], v[40:43]
	v_mfma_f32_16x16x32_bf16 v[44:47], v[130:133], v[154:157], v[44:47]
	s_waitcnt lgkmcnt(8)
	v_mfma_f32_16x16x32_bf16 v[48:51], v[134:137], v[138:141], v[48:51]
	v_mfma_f32_16x16x32_bf16 v[52:55], v[134:137], v[142:145], v[52:55]
	v_mfma_f32_16x16x32_bf16 v[56:59], v[134:137], v[148:151], v[56:59]
	v_mfma_f32_16x16x32_bf16 v[60:63], v[134:137], v[154:157], v[60:63]
	s_waitcnt lgkmcnt(6)
	v_mfma_f32_16x16x32_bf16 v[0:3], v[158:161], v[166:169], v[0:3]
	s_waitcnt vmcnt(0)
	ds_write_b128 v124, v[178:181] offset:32768
	s_waitcnt lgkmcnt(6)
	v_mfma_f32_16x16x32_bf16 v[4:7], v[158:161], v[170:173], v[4:7]
	ds_write_b128 v124, v[182:185] offset:36864
	s_waitcnt lgkmcnt(6)
	v_mfma_f32_16x16x32_bf16 v[8:11], v[158:161], v[174:177], v[8:11]
	ds_write_b128 v124, v[186:189] offset:40960
	s_waitcnt lgkmcnt(6)
	v_mfma_f32_16x16x32_bf16 v[12:15], v[158:161], v[252:255], v[12:15]
	ds_write_b128 v124, v[190:193] offset:45056
	s_waitcnt lgkmcnt(6)
	v_mfma_f32_16x16x32_bf16 v[16:19], v[162:165], v[166:169], v[16:19]
	ds_write_b128 v124, v[220:223] offset:49152
	v_mfma_f32_16x16x32_bf16 v[20:23], v[162:165], v[170:173], v[20:23]
	ds_write_b128 v124, v[224:227] offset:53248
	v_mfma_f32_16x16x32_bf16 v[24:27], v[162:165], v[174:177], v[24:27]
	ds_write_b128 v124, v[228:231] offset:57344
	v_mfma_f32_16x16x32_bf16 v[28:31], v[162:165], v[252:255], v[28:31]
	ds_write_b128 v124, v[232:235] offset:61440
	s_waitcnt lgkmcnt(9)
	v_mfma_f32_16x16x32_bf16 v[32:35], v[244:247], v[166:169], v[32:35]
	global_load_dwordx4 v[178:181], v115, s[98:99] offset:768
	v_mfma_f32_16x16x32_bf16 v[36:39], v[244:247], v[170:173], v[36:39]
	global_load_dwordx4 v[182:185], v116, s[98:99] offset:768
	v_mfma_f32_16x16x32_bf16 v[40:43], v[244:247], v[174:177], v[40:43]
	global_load_dwordx4 v[186:189], v122, s[98:99] offset:768
	v_mfma_f32_16x16x32_bf16 v[44:47], v[244:247], v[252:255], v[44:47]
	global_load_dwordx4 v[190:193], v123, s[98:99] offset:768
	s_waitcnt lgkmcnt(8)
	v_mfma_f32_16x16x32_bf16 v[48:51], v[248:251], v[166:169], v[48:51]
	global_load_dwordx4 v[220:223], v115, s[100:101] offset:768
	v_mfma_f32_16x16x32_bf16 v[52:55], v[248:251], v[170:173], v[52:55]
	global_load_dwordx4 v[224:227], v116, s[100:101] offset:768
	v_mfma_f32_16x16x32_bf16 v[56:59], v[248:251], v[174:177], v[56:59]
	global_load_dwordx4 v[228:231], v122, s[100:101] offset:768
	v_mfma_f32_16x16x32_bf16 v[60:63], v[248:251], v[252:255], v[60:63]
	global_load_dwordx4 v[232:235], v123, s[100:101] offset:768
	s_waitcnt lgkmcnt(0)
	s_barrier
	ds_read_b128 v[118:121], v239 offset:32768
	ds_read_b128 v[138:141], v241 offset:32768
	ds_read_b128 v[142:145], v241 offset:34816
	ds_read_b128 v[148:151], v241 offset:36864
	ds_read_b128 v[154:157], v241 offset:38912
	ds_read_b128 v[126:129], v239 offset:34816
	ds_read_b128 v[130:133], v239 offset:36864
	ds_read_b128 v[134:137], v239 offset:38912
	s_waitcnt lgkmcnt(6)
	v_mfma_f32_16x16x32_bf16 v[0:3], v[118:121], v[138:141], v[0:3]
	ds_read_b128 v[158:161], v240 offset:32768
	s_waitcnt lgkmcnt(6)
	v_mfma_f32_16x16x32_bf16 v[4:7], v[118:121], v[142:145], v[4:7]
	ds_read_b128 v[166:169], v242 offset:32768
	s_waitcnt lgkmcnt(6)
	v_mfma_f32_16x16x32_bf16 v[8:11], v[118:121], v[148:151], v[8:11]
	ds_read_b128 v[170:173], v242 offset:34816
	s_waitcnt lgkmcnt(6)
	v_mfma_f32_16x16x32_bf16 v[12:15], v[118:121], v[154:157], v[12:15]
	ds_read_b128 v[174:177], v242 offset:36864
	s_waitcnt lgkmcnt(6)
	v_mfma_f32_16x16x32_bf16 v[16:19], v[126:129], v[138:141], v[16:19]
	ds_read_b128 v[252:255], v242 offset:38912
	v_mfma_f32_16x16x32_bf16 v[20:23], v[126:129], v[142:145], v[20:23]
	ds_read_b128 v[162:165], v240 offset:34816
	v_mfma_f32_16x16x32_bf16 v[24:27], v[126:129], v[148:151], v[24:27]
	ds_read_b128 v[244:247], v240 offset:36864
	v_mfma_f32_16x16x32_bf16 v[28:31], v[126:129], v[154:157], v[28:31]
	ds_read_b128 v[248:251], v240 offset:38912
	s_waitcnt lgkmcnt(9)
	v_mfma_f32_16x16x32_bf16 v[32:35], v[130:133], v[138:141], v[32:35]
	v_mfma_f32_16x16x32_bf16 v[36:39], v[130:133], v[142:145], v[36:39]
	v_mfma_f32_16x16x32_bf16 v[40:43], v[130:133], v[148:151], v[40:43]
	v_mfma_f32_16x16x32_bf16 v[44:47], v[130:133], v[154:157], v[44:47]
	s_waitcnt lgkmcnt(8)
	v_mfma_f32_16x16x32_bf16 v[48:51], v[134:137], v[138:141], v[48:51]
	v_mfma_f32_16x16x32_bf16 v[52:55], v[134:137], v[142:145], v[52:55]
	v_mfma_f32_16x16x32_bf16 v[56:59], v[134:137], v[148:151], v[56:59]
	v_mfma_f32_16x16x32_bf16 v[60:63], v[134:137], v[154:157], v[60:63]
	s_waitcnt lgkmcnt(6)
	v_mfma_f32_16x16x32_bf16 v[0:3], v[158:161], v[166:169], v[0:3]
	s_waitcnt vmcnt(0)
	ds_write_b128 v124, v[178:181]
	s_waitcnt lgkmcnt(6)
	v_mfma_f32_16x16x32_bf16 v[4:7], v[158:161], v[170:173], v[4:7]
	ds_write_b128 v124, v[182:185] offset:4096
	s_waitcnt lgkmcnt(6)
	v_mfma_f32_16x16x32_bf16 v[8:11], v[158:161], v[174:177], v[8:11]
	ds_write_b128 v124, v[186:189] offset:8192
	s_waitcnt lgkmcnt(6)
	v_mfma_f32_16x16x32_bf16 v[12:15], v[158:161], v[252:255], v[12:15]
	ds_write_b128 v124, v[190:193] offset:12288
	s_waitcnt lgkmcnt(6)
	v_mfma_f32_16x16x32_bf16 v[16:19], v[162:165], v[166:169], v[16:19]
	ds_write_b128 v124, v[220:223] offset:16384
	v_mfma_f32_16x16x32_bf16 v[20:23], v[162:165], v[170:173], v[20:23]
	ds_write_b128 v124, v[224:227] offset:20480
	v_mfma_f32_16x16x32_bf16 v[24:27], v[162:165], v[174:177], v[24:27]
	ds_write_b128 v124, v[228:231] offset:24576
	v_mfma_f32_16x16x32_bf16 v[28:31], v[162:165], v[252:255], v[28:31]
	ds_write_b128 v124, v[232:235] offset:28672
	s_waitcnt lgkmcnt(9)
	v_mfma_f32_16x16x32_bf16 v[32:35], v[244:247], v[166:169], v[32:35]
	global_load_dwordx4 v[178:181], v115, s[98:99] offset:896
	v_mfma_f32_16x16x32_bf16 v[36:39], v[244:247], v[170:173], v[36:39]
	global_load_dwordx4 v[182:185], v116, s[98:99] offset:896
	v_mfma_f32_16x16x32_bf16 v[40:43], v[244:247], v[174:177], v[40:43]
	global_load_dwordx4 v[186:189], v122, s[98:99] offset:896
	v_mfma_f32_16x16x32_bf16 v[44:47], v[244:247], v[252:255], v[44:47]
	global_load_dwordx4 v[190:193], v123, s[98:99] offset:896
	s_waitcnt lgkmcnt(8)
	v_mfma_f32_16x16x32_bf16 v[48:51], v[248:251], v[166:169], v[48:51]
	global_load_dwordx4 v[220:223], v115, s[100:101] offset:896
	v_mfma_f32_16x16x32_bf16 v[52:55], v[248:251], v[170:173], v[52:55]
	global_load_dwordx4 v[224:227], v116, s[100:101] offset:896
	v_mfma_f32_16x16x32_bf16 v[56:59], v[248:251], v[174:177], v[56:59]
	global_load_dwordx4 v[228:231], v122, s[100:101] offset:896
	v_mfma_f32_16x16x32_bf16 v[60:63], v[248:251], v[252:255], v[60:63]
	global_load_dwordx4 v[232:235], v123, s[100:101] offset:896
	s_waitcnt lgkmcnt(0)
	s_barrier
	ds_read_b128 v[118:121], v239
	ds_read_b128 v[138:141], v241
	ds_read_b128 v[142:145], v241 offset:2048
	ds_read_b128 v[148:151], v241 offset:4096
	ds_read_b128 v[154:157], v241 offset:6144
	ds_read_b128 v[126:129], v239 offset:2048
	ds_read_b128 v[130:133], v239 offset:4096
	ds_read_b128 v[134:137], v239 offset:6144
	s_waitcnt lgkmcnt(6)
	v_mfma_f32_16x16x32_bf16 v[0:3], v[118:121], v[138:141], v[0:3]
	ds_read_b128 v[158:161], v240
	s_waitcnt lgkmcnt(6)
	v_mfma_f32_16x16x32_bf16 v[4:7], v[118:121], v[142:145], v[4:7]
	ds_read_b128 v[166:169], v242
	s_waitcnt lgkmcnt(6)
	v_mfma_f32_16x16x32_bf16 v[8:11], v[118:121], v[148:151], v[8:11]
	ds_read_b128 v[170:173], v242 offset:2048
	s_waitcnt lgkmcnt(6)
	v_mfma_f32_16x16x32_bf16 v[12:15], v[118:121], v[154:157], v[12:15]
	ds_read_b128 v[174:177], v242 offset:4096
	s_waitcnt lgkmcnt(6)
	v_mfma_f32_16x16x32_bf16 v[16:19], v[126:129], v[138:141], v[16:19]
	ds_read_b128 v[252:255], v242 offset:6144
	v_mfma_f32_16x16x32_bf16 v[20:23], v[126:129], v[142:145], v[20:23]
	ds_read_b128 v[162:165], v240 offset:2048
	v_mfma_f32_16x16x32_bf16 v[24:27], v[126:129], v[148:151], v[24:27]
	ds_read_b128 v[244:247], v240 offset:4096
	v_mfma_f32_16x16x32_bf16 v[28:31], v[126:129], v[154:157], v[28:31]
	ds_read_b128 v[248:251], v240 offset:6144
	s_waitcnt lgkmcnt(9)
	v_mfma_f32_16x16x32_bf16 v[32:35], v[130:133], v[138:141], v[32:35]
	v_mfma_f32_16x16x32_bf16 v[36:39], v[130:133], v[142:145], v[36:39]
	v_mfma_f32_16x16x32_bf16 v[40:43], v[130:133], v[148:151], v[40:43]
	v_mfma_f32_16x16x32_bf16 v[44:47], v[130:133], v[154:157], v[44:47]
	s_waitcnt lgkmcnt(8)
	v_mfma_f32_16x16x32_bf16 v[48:51], v[134:137], v[138:141], v[48:51]
	v_mfma_f32_16x16x32_bf16 v[52:55], v[134:137], v[142:145], v[52:55]
	v_mfma_f32_16x16x32_bf16 v[56:59], v[134:137], v[148:151], v[56:59]
	v_mfma_f32_16x16x32_bf16 v[60:63], v[134:137], v[154:157], v[60:63]
	s_waitcnt lgkmcnt(6)
	v_mfma_f32_16x16x32_bf16 v[0:3], v[158:161], v[166:169], v[0:3]
	s_waitcnt vmcnt(0)
	ds_write_b128 v124, v[178:181] offset:32768
	s_waitcnt lgkmcnt(6)
	v_mfma_f32_16x16x32_bf16 v[4:7], v[158:161], v[170:173], v[4:7]
	ds_write_b128 v124, v[182:185] offset:36864
	s_waitcnt lgkmcnt(6)
	v_mfma_f32_16x16x32_bf16 v[8:11], v[158:161], v[174:177], v[8:11]
	ds_write_b128 v124, v[186:189] offset:40960
	s_waitcnt lgkmcnt(6)
	v_mfma_f32_16x16x32_bf16 v[12:15], v[158:161], v[252:255], v[12:15]
	ds_write_b128 v124, v[190:193] offset:45056
	s_waitcnt lgkmcnt(6)
	v_mfma_f32_16x16x32_bf16 v[16:19], v[162:165], v[166:169], v[16:19]
	ds_write_b128 v124, v[220:223] offset:49152
	v_mfma_f32_16x16x32_bf16 v[20:23], v[162:165], v[170:173], v[20:23]
	ds_write_b128 v124, v[224:227] offset:53248
	v_mfma_f32_16x16x32_bf16 v[24:27], v[162:165], v[174:177], v[24:27]
	ds_write_b128 v124, v[228:231] offset:57344
	v_mfma_f32_16x16x32_bf16 v[28:31], v[162:165], v[252:255], v[28:31]
	ds_write_b128 v124, v[232:235] offset:61440
	s_waitcnt lgkmcnt(9)
	v_mfma_f32_16x16x32_bf16 v[32:35], v[244:247], v[166:169], v[32:35]
	global_load_dwordx4 v[178:181], v115, s[98:99] offset:1024
	v_mfma_f32_16x16x32_bf16 v[36:39], v[244:247], v[170:173], v[36:39]
	global_load_dwordx4 v[182:185], v116, s[98:99] offset:1024
	v_mfma_f32_16x16x32_bf16 v[40:43], v[244:247], v[174:177], v[40:43]
	global_load_dwordx4 v[186:189], v122, s[98:99] offset:1024
	v_mfma_f32_16x16x32_bf16 v[44:47], v[244:247], v[252:255], v[44:47]
	global_load_dwordx4 v[190:193], v123, s[98:99] offset:1024
	s_waitcnt lgkmcnt(8)
	v_mfma_f32_16x16x32_bf16 v[48:51], v[248:251], v[166:169], v[48:51]
	global_load_dwordx4 v[220:223], v115, s[100:101] offset:1024
	v_mfma_f32_16x16x32_bf16 v[52:55], v[248:251], v[170:173], v[52:55]
	global_load_dwordx4 v[224:227], v116, s[100:101] offset:1024
	v_mfma_f32_16x16x32_bf16 v[56:59], v[248:251], v[174:177], v[56:59]
	global_load_dwordx4 v[228:231], v122, s[100:101] offset:1024
	v_mfma_f32_16x16x32_bf16 v[60:63], v[248:251], v[252:255], v[60:63]
	global_load_dwordx4 v[232:235], v123, s[100:101] offset:1024
	s_waitcnt lgkmcnt(0)
	s_barrier
	ds_read_b128 v[118:121], v239 offset:32768
	ds_read_b128 v[138:141], v241 offset:32768
	ds_read_b128 v[142:145], v241 offset:34816
	ds_read_b128 v[148:151], v241 offset:36864
	ds_read_b128 v[154:157], v241 offset:38912
	ds_read_b128 v[126:129], v239 offset:34816
	ds_read_b128 v[130:133], v239 offset:36864
	ds_read_b128 v[134:137], v239 offset:38912
	s_waitcnt lgkmcnt(6)
	v_mfma_f32_16x16x32_bf16 v[0:3], v[118:121], v[138:141], v[0:3]
	ds_read_b128 v[158:161], v240 offset:32768
	s_waitcnt lgkmcnt(6)
	v_mfma_f32_16x16x32_bf16 v[4:7], v[118:121], v[142:145], v[4:7]
	ds_read_b128 v[166:169], v242 offset:32768
	s_waitcnt lgkmcnt(6)
	v_mfma_f32_16x16x32_bf16 v[8:11], v[118:121], v[148:151], v[8:11]
	ds_read_b128 v[170:173], v242 offset:34816
	s_waitcnt lgkmcnt(6)
	v_mfma_f32_16x16x32_bf16 v[12:15], v[118:121], v[154:157], v[12:15]
	ds_read_b128 v[174:177], v242 offset:36864
	s_waitcnt lgkmcnt(6)
	v_mfma_f32_16x16x32_bf16 v[16:19], v[126:129], v[138:141], v[16:19]
	ds_read_b128 v[252:255], v242 offset:38912
	v_mfma_f32_16x16x32_bf16 v[20:23], v[126:129], v[142:145], v[20:23]
	ds_read_b128 v[162:165], v240 offset:34816
	v_mfma_f32_16x16x32_bf16 v[24:27], v[126:129], v[148:151], v[24:27]
	ds_read_b128 v[244:247], v240 offset:36864
	v_mfma_f32_16x16x32_bf16 v[28:31], v[126:129], v[154:157], v[28:31]
	ds_read_b128 v[248:251], v240 offset:38912
	s_waitcnt lgkmcnt(9)
	v_mfma_f32_16x16x32_bf16 v[32:35], v[130:133], v[138:141], v[32:35]
	v_mfma_f32_16x16x32_bf16 v[36:39], v[130:133], v[142:145], v[36:39]
	v_mfma_f32_16x16x32_bf16 v[40:43], v[130:133], v[148:151], v[40:43]
	v_mfma_f32_16x16x32_bf16 v[44:47], v[130:133], v[154:157], v[44:47]
	s_waitcnt lgkmcnt(8)
	v_mfma_f32_16x16x32_bf16 v[48:51], v[134:137], v[138:141], v[48:51]
	v_mfma_f32_16x16x32_bf16 v[52:55], v[134:137], v[142:145], v[52:55]
	v_mfma_f32_16x16x32_bf16 v[56:59], v[134:137], v[148:151], v[56:59]
	v_mfma_f32_16x16x32_bf16 v[60:63], v[134:137], v[154:157], v[60:63]
	s_waitcnt lgkmcnt(6)
	v_mfma_f32_16x16x32_bf16 v[0:3], v[158:161], v[166:169], v[0:3]
	s_waitcnt vmcnt(0)
	ds_write_b128 v124, v[178:181]
	s_waitcnt lgkmcnt(6)
	v_mfma_f32_16x16x32_bf16 v[4:7], v[158:161], v[170:173], v[4:7]
	ds_write_b128 v124, v[182:185] offset:4096
	s_waitcnt lgkmcnt(6)
	v_mfma_f32_16x16x32_bf16 v[8:11], v[158:161], v[174:177], v[8:11]
	ds_write_b128 v124, v[186:189] offset:8192
	s_waitcnt lgkmcnt(6)
	v_mfma_f32_16x16x32_bf16 v[12:15], v[158:161], v[252:255], v[12:15]
	ds_write_b128 v124, v[190:193] offset:12288
	s_waitcnt lgkmcnt(6)
	v_mfma_f32_16x16x32_bf16 v[16:19], v[162:165], v[166:169], v[16:19]
	ds_write_b128 v124, v[220:223] offset:16384
	v_mfma_f32_16x16x32_bf16 v[20:23], v[162:165], v[170:173], v[20:23]
	ds_write_b128 v124, v[224:227] offset:20480
	v_mfma_f32_16x16x32_bf16 v[24:27], v[162:165], v[174:177], v[24:27]
	ds_write_b128 v124, v[228:231] offset:24576
	v_mfma_f32_16x16x32_bf16 v[28:31], v[162:165], v[252:255], v[28:31]
	ds_write_b128 v124, v[232:235] offset:28672
	s_waitcnt lgkmcnt(9)
	v_mfma_f32_16x16x32_bf16 v[32:35], v[244:247], v[166:169], v[32:35]
	global_load_dwordx4 v[178:181], v115, s[98:99] offset:1152
	v_mfma_f32_16x16x32_bf16 v[36:39], v[244:247], v[170:173], v[36:39]
	global_load_dwordx4 v[182:185], v116, s[98:99] offset:1152
	v_mfma_f32_16x16x32_bf16 v[40:43], v[244:247], v[174:177], v[40:43]
	global_load_dwordx4 v[186:189], v122, s[98:99] offset:1152
	v_mfma_f32_16x16x32_bf16 v[44:47], v[244:247], v[252:255], v[44:47]
	global_load_dwordx4 v[190:193], v123, s[98:99] offset:1152
	s_waitcnt lgkmcnt(8)
	v_mfma_f32_16x16x32_bf16 v[48:51], v[248:251], v[166:169], v[48:51]
	global_load_dwordx4 v[220:223], v115, s[100:101] offset:1152
	v_mfma_f32_16x16x32_bf16 v[52:55], v[248:251], v[170:173], v[52:55]
	global_load_dwordx4 v[224:227], v116, s[100:101] offset:1152
	v_mfma_f32_16x16x32_bf16 v[56:59], v[248:251], v[174:177], v[56:59]
	global_load_dwordx4 v[228:231], v122, s[100:101] offset:1152
	v_mfma_f32_16x16x32_bf16 v[60:63], v[248:251], v[252:255], v[60:63]
	global_load_dwordx4 v[232:235], v123, s[100:101] offset:1152
	s_waitcnt lgkmcnt(0)
	s_barrier
	ds_read_b128 v[118:121], v239
	ds_read_b128 v[138:141], v241
	ds_read_b128 v[142:145], v241 offset:2048
	ds_read_b128 v[148:151], v241 offset:4096
	ds_read_b128 v[154:157], v241 offset:6144
	ds_read_b128 v[126:129], v239 offset:2048
	ds_read_b128 v[130:133], v239 offset:4096
	ds_read_b128 v[134:137], v239 offset:6144
	s_waitcnt lgkmcnt(6)
	v_mfma_f32_16x16x32_bf16 v[0:3], v[118:121], v[138:141], v[0:3]
	ds_read_b128 v[158:161], v240
	s_waitcnt lgkmcnt(6)
	v_mfma_f32_16x16x32_bf16 v[4:7], v[118:121], v[142:145], v[4:7]
	ds_read_b128 v[166:169], v242
	s_waitcnt lgkmcnt(6)
	v_mfma_f32_16x16x32_bf16 v[8:11], v[118:121], v[148:151], v[8:11]
	ds_read_b128 v[170:173], v242 offset:2048
	s_waitcnt lgkmcnt(6)
	v_mfma_f32_16x16x32_bf16 v[12:15], v[118:121], v[154:157], v[12:15]
	ds_read_b128 v[174:177], v242 offset:4096
	s_waitcnt lgkmcnt(6)
	v_mfma_f32_16x16x32_bf16 v[16:19], v[126:129], v[138:141], v[16:19]
	ds_read_b128 v[252:255], v242 offset:6144
	v_mfma_f32_16x16x32_bf16 v[20:23], v[126:129], v[142:145], v[20:23]
	ds_read_b128 v[162:165], v240 offset:2048
	v_mfma_f32_16x16x32_bf16 v[24:27], v[126:129], v[148:151], v[24:27]
	ds_read_b128 v[244:247], v240 offset:4096
	v_mfma_f32_16x16x32_bf16 v[28:31], v[126:129], v[154:157], v[28:31]
	ds_read_b128 v[248:251], v240 offset:6144
	s_waitcnt lgkmcnt(9)
	v_mfma_f32_16x16x32_bf16 v[32:35], v[130:133], v[138:141], v[32:35]
	v_mfma_f32_16x16x32_bf16 v[36:39], v[130:133], v[142:145], v[36:39]
	v_mfma_f32_16x16x32_bf16 v[40:43], v[130:133], v[148:151], v[40:43]
	v_mfma_f32_16x16x32_bf16 v[44:47], v[130:133], v[154:157], v[44:47]
	s_waitcnt lgkmcnt(8)
	v_mfma_f32_16x16x32_bf16 v[48:51], v[134:137], v[138:141], v[48:51]
	v_mfma_f32_16x16x32_bf16 v[52:55], v[134:137], v[142:145], v[52:55]
	v_mfma_f32_16x16x32_bf16 v[56:59], v[134:137], v[148:151], v[56:59]
	v_mfma_f32_16x16x32_bf16 v[60:63], v[134:137], v[154:157], v[60:63]
	s_waitcnt lgkmcnt(6)
	v_mfma_f32_16x16x32_bf16 v[0:3], v[158:161], v[166:169], v[0:3]
	s_waitcnt vmcnt(0)
	ds_write_b128 v124, v[178:181] offset:32768
	s_waitcnt lgkmcnt(6)
	v_mfma_f32_16x16x32_bf16 v[4:7], v[158:161], v[170:173], v[4:7]
	ds_write_b128 v124, v[182:185] offset:36864
	s_waitcnt lgkmcnt(6)
	v_mfma_f32_16x16x32_bf16 v[8:11], v[158:161], v[174:177], v[8:11]
	ds_write_b128 v124, v[186:189] offset:40960
	s_waitcnt lgkmcnt(6)
	v_mfma_f32_16x16x32_bf16 v[12:15], v[158:161], v[252:255], v[12:15]
	ds_write_b128 v124, v[190:193] offset:45056
	s_waitcnt lgkmcnt(6)
	v_mfma_f32_16x16x32_bf16 v[16:19], v[162:165], v[166:169], v[16:19]
	ds_write_b128 v124, v[220:223] offset:49152
	v_mfma_f32_16x16x32_bf16 v[20:23], v[162:165], v[170:173], v[20:23]
	ds_write_b128 v124, v[224:227] offset:53248
	v_mfma_f32_16x16x32_bf16 v[24:27], v[162:165], v[174:177], v[24:27]
	ds_write_b128 v124, v[228:231] offset:57344
	v_mfma_f32_16x16x32_bf16 v[28:31], v[162:165], v[252:255], v[28:31]
	ds_write_b128 v124, v[232:235] offset:61440
	s_waitcnt lgkmcnt(9)
	v_mfma_f32_16x16x32_bf16 v[32:35], v[244:247], v[166:169], v[32:35]
	global_load_dwordx4 v[178:181], v115, s[98:99] offset:1280
	v_mfma_f32_16x16x32_bf16 v[36:39], v[244:247], v[170:173], v[36:39]
	global_load_dwordx4 v[182:185], v116, s[98:99] offset:1280
	v_mfma_f32_16x16x32_bf16 v[40:43], v[244:247], v[174:177], v[40:43]
	global_load_dwordx4 v[186:189], v122, s[98:99] offset:1280
	v_mfma_f32_16x16x32_bf16 v[44:47], v[244:247], v[252:255], v[44:47]
	global_load_dwordx4 v[190:193], v123, s[98:99] offset:1280
	s_waitcnt lgkmcnt(8)
	v_mfma_f32_16x16x32_bf16 v[48:51], v[248:251], v[166:169], v[48:51]
	global_load_dwordx4 v[220:223], v115, s[100:101] offset:1280
	v_mfma_f32_16x16x32_bf16 v[52:55], v[248:251], v[170:173], v[52:55]
	global_load_dwordx4 v[224:227], v116, s[100:101] offset:1280
	v_mfma_f32_16x16x32_bf16 v[56:59], v[248:251], v[174:177], v[56:59]
	global_load_dwordx4 v[228:231], v122, s[100:101] offset:1280
	v_mfma_f32_16x16x32_bf16 v[60:63], v[248:251], v[252:255], v[60:63]
	global_load_dwordx4 v[232:235], v123, s[100:101] offset:1280
	s_waitcnt lgkmcnt(0)
	s_barrier
	ds_read_b128 v[118:121], v239 offset:32768
	ds_read_b128 v[138:141], v241 offset:32768
	ds_read_b128 v[142:145], v241 offset:34816
	ds_read_b128 v[148:151], v241 offset:36864
	ds_read_b128 v[154:157], v241 offset:38912
	ds_read_b128 v[126:129], v239 offset:34816
	ds_read_b128 v[130:133], v239 offset:36864
	ds_read_b128 v[134:137], v239 offset:38912
	s_waitcnt lgkmcnt(6)
	v_mfma_f32_16x16x32_bf16 v[0:3], v[118:121], v[138:141], v[0:3]
	ds_read_b128 v[158:161], v240 offset:32768
	s_waitcnt lgkmcnt(6)
	v_mfma_f32_16x16x32_bf16 v[4:7], v[118:121], v[142:145], v[4:7]
	ds_read_b128 v[166:169], v242 offset:32768
	s_waitcnt lgkmcnt(6)
	v_mfma_f32_16x16x32_bf16 v[8:11], v[118:121], v[148:151], v[8:11]
	ds_read_b128 v[170:173], v242 offset:34816
	s_waitcnt lgkmcnt(6)
	v_mfma_f32_16x16x32_bf16 v[12:15], v[118:121], v[154:157], v[12:15]
	ds_read_b128 v[174:177], v242 offset:36864
	s_waitcnt lgkmcnt(6)
	v_mfma_f32_16x16x32_bf16 v[16:19], v[126:129], v[138:141], v[16:19]
	ds_read_b128 v[252:255], v242 offset:38912
	v_mfma_f32_16x16x32_bf16 v[20:23], v[126:129], v[142:145], v[20:23]
	ds_read_b128 v[162:165], v240 offset:34816
	v_mfma_f32_16x16x32_bf16 v[24:27], v[126:129], v[148:151], v[24:27]
	ds_read_b128 v[244:247], v240 offset:36864
	v_mfma_f32_16x16x32_bf16 v[28:31], v[126:129], v[154:157], v[28:31]
	ds_read_b128 v[248:251], v240 offset:38912
	s_waitcnt lgkmcnt(9)
	v_mfma_f32_16x16x32_bf16 v[32:35], v[130:133], v[138:141], v[32:35]
	v_mfma_f32_16x16x32_bf16 v[36:39], v[130:133], v[142:145], v[36:39]
	v_mfma_f32_16x16x32_bf16 v[40:43], v[130:133], v[148:151], v[40:43]
	v_mfma_f32_16x16x32_bf16 v[44:47], v[130:133], v[154:157], v[44:47]
	s_waitcnt lgkmcnt(8)
	v_mfma_f32_16x16x32_bf16 v[48:51], v[134:137], v[138:141], v[48:51]
	v_mfma_f32_16x16x32_bf16 v[52:55], v[134:137], v[142:145], v[52:55]
	v_mfma_f32_16x16x32_bf16 v[56:59], v[134:137], v[148:151], v[56:59]
	v_mfma_f32_16x16x32_bf16 v[60:63], v[134:137], v[154:157], v[60:63]
	s_waitcnt lgkmcnt(6)
	v_mfma_f32_16x16x32_bf16 v[0:3], v[158:161], v[166:169], v[0:3]
	s_waitcnt vmcnt(0)
	ds_write_b128 v124, v[178:181]
	s_waitcnt lgkmcnt(6)
	v_mfma_f32_16x16x32_bf16 v[4:7], v[158:161], v[170:173], v[4:7]
	ds_write_b128 v124, v[182:185] offset:4096
	s_waitcnt lgkmcnt(6)
	v_mfma_f32_16x16x32_bf16 v[8:11], v[158:161], v[174:177], v[8:11]
	ds_write_b128 v124, v[186:189] offset:8192
	s_waitcnt lgkmcnt(6)
	v_mfma_f32_16x16x32_bf16 v[12:15], v[158:161], v[252:255], v[12:15]
	ds_write_b128 v124, v[190:193] offset:12288
	s_waitcnt lgkmcnt(6)
	v_mfma_f32_16x16x32_bf16 v[16:19], v[162:165], v[166:169], v[16:19]
	ds_write_b128 v124, v[220:223] offset:16384
	v_mfma_f32_16x16x32_bf16 v[20:23], v[162:165], v[170:173], v[20:23]
	ds_write_b128 v124, v[224:227] offset:20480
	v_mfma_f32_16x16x32_bf16 v[24:27], v[162:165], v[174:177], v[24:27]
	ds_write_b128 v124, v[228:231] offset:24576
	v_mfma_f32_16x16x32_bf16 v[28:31], v[162:165], v[252:255], v[28:31]
	ds_write_b128 v124, v[232:235] offset:28672
	s_waitcnt lgkmcnt(9)
	v_mfma_f32_16x16x32_bf16 v[32:35], v[244:247], v[166:169], v[32:35]
	global_load_dwordx4 v[178:181], v115, s[98:99] offset:1408
	v_mfma_f32_16x16x32_bf16 v[36:39], v[244:247], v[170:173], v[36:39]
	global_load_dwordx4 v[182:185], v116, s[98:99] offset:1408
	v_mfma_f32_16x16x32_bf16 v[40:43], v[244:247], v[174:177], v[40:43]
	global_load_dwordx4 v[186:189], v122, s[98:99] offset:1408
	v_mfma_f32_16x16x32_bf16 v[44:47], v[244:247], v[252:255], v[44:47]
	global_load_dwordx4 v[190:193], v123, s[98:99] offset:1408
	s_waitcnt lgkmcnt(8)
	v_mfma_f32_16x16x32_bf16 v[48:51], v[248:251], v[166:169], v[48:51]
	global_load_dwordx4 v[220:223], v115, s[100:101] offset:1408
	v_mfma_f32_16x16x32_bf16 v[52:55], v[248:251], v[170:173], v[52:55]
	global_load_dwordx4 v[224:227], v116, s[100:101] offset:1408
	v_mfma_f32_16x16x32_bf16 v[56:59], v[248:251], v[174:177], v[56:59]
	global_load_dwordx4 v[228:231], v122, s[100:101] offset:1408
	v_mfma_f32_16x16x32_bf16 v[60:63], v[248:251], v[252:255], v[60:63]
	global_load_dwordx4 v[232:235], v123, s[100:101] offset:1408
	s_waitcnt lgkmcnt(0)
	s_barrier
	ds_read_b128 v[118:121], v239
	ds_read_b128 v[138:141], v241
	ds_read_b128 v[142:145], v241 offset:2048
	ds_read_b128 v[148:151], v241 offset:4096
	ds_read_b128 v[154:157], v241 offset:6144
	ds_read_b128 v[126:129], v239 offset:2048
	ds_read_b128 v[130:133], v239 offset:4096
	ds_read_b128 v[134:137], v239 offset:6144
	s_waitcnt lgkmcnt(6)
	v_mfma_f32_16x16x32_bf16 v[0:3], v[118:121], v[138:141], v[0:3]
	ds_read_b128 v[158:161], v240
	s_waitcnt lgkmcnt(6)
	v_mfma_f32_16x16x32_bf16 v[4:7], v[118:121], v[142:145], v[4:7]
	ds_read_b128 v[166:169], v242
	s_waitcnt lgkmcnt(6)
	v_mfma_f32_16x16x32_bf16 v[8:11], v[118:121], v[148:151], v[8:11]
	ds_read_b128 v[170:173], v242 offset:2048
	s_waitcnt lgkmcnt(6)
	v_mfma_f32_16x16x32_bf16 v[12:15], v[118:121], v[154:157], v[12:15]
	ds_read_b128 v[174:177], v242 offset:4096
	s_waitcnt lgkmcnt(6)
	v_mfma_f32_16x16x32_bf16 v[16:19], v[126:129], v[138:141], v[16:19]
	ds_read_b128 v[252:255], v242 offset:6144
	v_mfma_f32_16x16x32_bf16 v[20:23], v[126:129], v[142:145], v[20:23]
	ds_read_b128 v[162:165], v240 offset:2048
	v_mfma_f32_16x16x32_bf16 v[24:27], v[126:129], v[148:151], v[24:27]
	ds_read_b128 v[244:247], v240 offset:4096
	v_mfma_f32_16x16x32_bf16 v[28:31], v[126:129], v[154:157], v[28:31]
	ds_read_b128 v[248:251], v240 offset:6144
	s_waitcnt lgkmcnt(9)
	v_mfma_f32_16x16x32_bf16 v[32:35], v[130:133], v[138:141], v[32:35]
	v_mfma_f32_16x16x32_bf16 v[36:39], v[130:133], v[142:145], v[36:39]
	v_mfma_f32_16x16x32_bf16 v[40:43], v[130:133], v[148:151], v[40:43]
	v_mfma_f32_16x16x32_bf16 v[44:47], v[130:133], v[154:157], v[44:47]
	s_waitcnt lgkmcnt(8)
	v_mfma_f32_16x16x32_bf16 v[48:51], v[134:137], v[138:141], v[48:51]
	v_mfma_f32_16x16x32_bf16 v[52:55], v[134:137], v[142:145], v[52:55]
	v_mfma_f32_16x16x32_bf16 v[56:59], v[134:137], v[148:151], v[56:59]
	v_mfma_f32_16x16x32_bf16 v[60:63], v[134:137], v[154:157], v[60:63]
	s_waitcnt lgkmcnt(6)
	v_mfma_f32_16x16x32_bf16 v[0:3], v[158:161], v[166:169], v[0:3]
	s_waitcnt vmcnt(0)
	ds_write_b128 v124, v[178:181] offset:32768
	s_waitcnt lgkmcnt(6)
	v_mfma_f32_16x16x32_bf16 v[4:7], v[158:161], v[170:173], v[4:7]
	ds_write_b128 v124, v[182:185] offset:36864
	s_waitcnt lgkmcnt(6)
	v_mfma_f32_16x16x32_bf16 v[8:11], v[158:161], v[174:177], v[8:11]
	ds_write_b128 v124, v[186:189] offset:40960
	s_waitcnt lgkmcnt(6)
	v_mfma_f32_16x16x32_bf16 v[12:15], v[158:161], v[252:255], v[12:15]
	ds_write_b128 v124, v[190:193] offset:45056
	s_waitcnt lgkmcnt(6)
	v_mfma_f32_16x16x32_bf16 v[16:19], v[162:165], v[166:169], v[16:19]
	ds_write_b128 v124, v[220:223] offset:49152
	v_mfma_f32_16x16x32_bf16 v[20:23], v[162:165], v[170:173], v[20:23]
	ds_write_b128 v124, v[224:227] offset:53248
	v_mfma_f32_16x16x32_bf16 v[24:27], v[162:165], v[174:177], v[24:27]
	ds_write_b128 v124, v[228:231] offset:57344
	v_mfma_f32_16x16x32_bf16 v[28:31], v[162:165], v[252:255], v[28:31]
	ds_write_b128 v124, v[232:235] offset:61440
	s_waitcnt lgkmcnt(9)
	v_mfma_f32_16x16x32_bf16 v[32:35], v[244:247], v[166:169], v[32:35]
	global_load_dwordx4 v[178:181], v115, s[98:99] offset:1536
	v_mfma_f32_16x16x32_bf16 v[36:39], v[244:247], v[170:173], v[36:39]
	global_load_dwordx4 v[182:185], v116, s[98:99] offset:1536
	v_mfma_f32_16x16x32_bf16 v[40:43], v[244:247], v[174:177], v[40:43]
	global_load_dwordx4 v[186:189], v122, s[98:99] offset:1536
	v_mfma_f32_16x16x32_bf16 v[44:47], v[244:247], v[252:255], v[44:47]
	global_load_dwordx4 v[190:193], v123, s[98:99] offset:1536
	s_waitcnt lgkmcnt(8)
	v_mfma_f32_16x16x32_bf16 v[48:51], v[248:251], v[166:169], v[48:51]
	global_load_dwordx4 v[220:223], v115, s[100:101] offset:1536
	v_mfma_f32_16x16x32_bf16 v[52:55], v[248:251], v[170:173], v[52:55]
	global_load_dwordx4 v[224:227], v116, s[100:101] offset:1536
	v_mfma_f32_16x16x32_bf16 v[56:59], v[248:251], v[174:177], v[56:59]
	global_load_dwordx4 v[228:231], v122, s[100:101] offset:1536
	v_mfma_f32_16x16x32_bf16 v[60:63], v[248:251], v[252:255], v[60:63]
	global_load_dwordx4 v[232:235], v123, s[100:101] offset:1536
	s_waitcnt lgkmcnt(0)
	s_barrier
	ds_read_b128 v[118:121], v239 offset:32768
	ds_read_b128 v[138:141], v241 offset:32768
	ds_read_b128 v[142:145], v241 offset:34816
	ds_read_b128 v[148:151], v241 offset:36864
	ds_read_b128 v[154:157], v241 offset:38912
	ds_read_b128 v[126:129], v239 offset:34816
	ds_read_b128 v[130:133], v239 offset:36864
	ds_read_b128 v[134:137], v239 offset:38912
	s_waitcnt lgkmcnt(6)
	v_mfma_f32_16x16x32_bf16 v[0:3], v[118:121], v[138:141], v[0:3]
	ds_read_b128 v[158:161], v240 offset:32768
	s_waitcnt lgkmcnt(6)
	v_mfma_f32_16x16x32_bf16 v[4:7], v[118:121], v[142:145], v[4:7]
	ds_read_b128 v[166:169], v242 offset:32768
	s_waitcnt lgkmcnt(6)
	v_mfma_f32_16x16x32_bf16 v[8:11], v[118:121], v[148:151], v[8:11]
	ds_read_b128 v[170:173], v242 offset:34816
	s_waitcnt lgkmcnt(6)
	v_mfma_f32_16x16x32_bf16 v[12:15], v[118:121], v[154:157], v[12:15]
	ds_read_b128 v[174:177], v242 offset:36864
	s_waitcnt lgkmcnt(6)
	v_mfma_f32_16x16x32_bf16 v[16:19], v[126:129], v[138:141], v[16:19]
	ds_read_b128 v[252:255], v242 offset:38912
	v_mfma_f32_16x16x32_bf16 v[20:23], v[126:129], v[142:145], v[20:23]
	ds_read_b128 v[162:165], v240 offset:34816
	v_mfma_f32_16x16x32_bf16 v[24:27], v[126:129], v[148:151], v[24:27]
	ds_read_b128 v[244:247], v240 offset:36864
	v_mfma_f32_16x16x32_bf16 v[28:31], v[126:129], v[154:157], v[28:31]
	ds_read_b128 v[248:251], v240 offset:38912
	s_waitcnt lgkmcnt(9)
	v_mfma_f32_16x16x32_bf16 v[32:35], v[130:133], v[138:141], v[32:35]
	v_mfma_f32_16x16x32_bf16 v[36:39], v[130:133], v[142:145], v[36:39]
	v_mfma_f32_16x16x32_bf16 v[40:43], v[130:133], v[148:151], v[40:43]
	v_mfma_f32_16x16x32_bf16 v[44:47], v[130:133], v[154:157], v[44:47]
	s_waitcnt lgkmcnt(8)
	v_mfma_f32_16x16x32_bf16 v[48:51], v[134:137], v[138:141], v[48:51]
	v_mfma_f32_16x16x32_bf16 v[52:55], v[134:137], v[142:145], v[52:55]
	v_mfma_f32_16x16x32_bf16 v[56:59], v[134:137], v[148:151], v[56:59]
	v_mfma_f32_16x16x32_bf16 v[60:63], v[134:137], v[154:157], v[60:63]
	s_waitcnt lgkmcnt(6)
	v_mfma_f32_16x16x32_bf16 v[0:3], v[158:161], v[166:169], v[0:3]
	s_waitcnt vmcnt(0)
	ds_write_b128 v124, v[178:181]
	s_waitcnt lgkmcnt(6)
	v_mfma_f32_16x16x32_bf16 v[4:7], v[158:161], v[170:173], v[4:7]
	ds_write_b128 v124, v[182:185] offset:4096
	s_waitcnt lgkmcnt(6)
	v_mfma_f32_16x16x32_bf16 v[8:11], v[158:161], v[174:177], v[8:11]
	ds_write_b128 v124, v[186:189] offset:8192
	s_waitcnt lgkmcnt(6)
	v_mfma_f32_16x16x32_bf16 v[12:15], v[158:161], v[252:255], v[12:15]
	ds_write_b128 v124, v[190:193] offset:12288
	s_waitcnt lgkmcnt(6)
	v_mfma_f32_16x16x32_bf16 v[16:19], v[162:165], v[166:169], v[16:19]
	ds_write_b128 v124, v[220:223] offset:16384
	v_mfma_f32_16x16x32_bf16 v[20:23], v[162:165], v[170:173], v[20:23]
	ds_write_b128 v124, v[224:227] offset:20480
	v_mfma_f32_16x16x32_bf16 v[24:27], v[162:165], v[174:177], v[24:27]
	ds_write_b128 v124, v[228:231] offset:24576
	v_mfma_f32_16x16x32_bf16 v[28:31], v[162:165], v[252:255], v[28:31]
	ds_write_b128 v124, v[232:235] offset:28672
	s_waitcnt lgkmcnt(9)
	v_mfma_f32_16x16x32_bf16 v[32:35], v[244:247], v[166:169], v[32:35]
	global_load_dwordx4 v[178:181], v115, s[98:99] offset:1664
	v_mfma_f32_16x16x32_bf16 v[36:39], v[244:247], v[170:173], v[36:39]
	global_load_dwordx4 v[182:185], v116, s[98:99] offset:1664
	v_mfma_f32_16x16x32_bf16 v[40:43], v[244:247], v[174:177], v[40:43]
	global_load_dwordx4 v[186:189], v122, s[98:99] offset:1664
	v_mfma_f32_16x16x32_bf16 v[44:47], v[244:247], v[252:255], v[44:47]
	global_load_dwordx4 v[190:193], v123, s[98:99] offset:1664
	s_waitcnt lgkmcnt(8)
	v_mfma_f32_16x16x32_bf16 v[48:51], v[248:251], v[166:169], v[48:51]
	global_load_dwordx4 v[220:223], v115, s[100:101] offset:1664
	v_mfma_f32_16x16x32_bf16 v[52:55], v[248:251], v[170:173], v[52:55]
	global_load_dwordx4 v[224:227], v116, s[100:101] offset:1664
	v_mfma_f32_16x16x32_bf16 v[56:59], v[248:251], v[174:177], v[56:59]
	global_load_dwordx4 v[228:231], v122, s[100:101] offset:1664
	v_mfma_f32_16x16x32_bf16 v[60:63], v[248:251], v[252:255], v[60:63]
	global_load_dwordx4 v[232:235], v123, s[100:101] offset:1664
	s_waitcnt lgkmcnt(0)
	s_barrier
	ds_read_b128 v[118:121], v239
	ds_read_b128 v[138:141], v241
	ds_read_b128 v[142:145], v241 offset:2048
	ds_read_b128 v[148:151], v241 offset:4096
	ds_read_b128 v[154:157], v241 offset:6144
	ds_read_b128 v[126:129], v239 offset:2048
	ds_read_b128 v[130:133], v239 offset:4096
	ds_read_b128 v[134:137], v239 offset:6144
	s_waitcnt lgkmcnt(6)
	v_mfma_f32_16x16x32_bf16 v[0:3], v[118:121], v[138:141], v[0:3]
	ds_read_b128 v[158:161], v240
	s_waitcnt lgkmcnt(6)
	v_mfma_f32_16x16x32_bf16 v[4:7], v[118:121], v[142:145], v[4:7]
	ds_read_b128 v[166:169], v242
	s_waitcnt lgkmcnt(6)
	v_mfma_f32_16x16x32_bf16 v[8:11], v[118:121], v[148:151], v[8:11]
	ds_read_b128 v[170:173], v242 offset:2048
	s_waitcnt lgkmcnt(6)
	v_mfma_f32_16x16x32_bf16 v[12:15], v[118:121], v[154:157], v[12:15]
	ds_read_b128 v[174:177], v242 offset:4096
	s_waitcnt lgkmcnt(6)
	v_mfma_f32_16x16x32_bf16 v[16:19], v[126:129], v[138:141], v[16:19]
	ds_read_b128 v[252:255], v242 offset:6144
	v_mfma_f32_16x16x32_bf16 v[20:23], v[126:129], v[142:145], v[20:23]
	ds_read_b128 v[162:165], v240 offset:2048
	v_mfma_f32_16x16x32_bf16 v[24:27], v[126:129], v[148:151], v[24:27]
	ds_read_b128 v[244:247], v240 offset:4096
	v_mfma_f32_16x16x32_bf16 v[28:31], v[126:129], v[154:157], v[28:31]
	ds_read_b128 v[248:251], v240 offset:6144
	s_waitcnt lgkmcnt(9)
	v_mfma_f32_16x16x32_bf16 v[32:35], v[130:133], v[138:141], v[32:35]
	v_mfma_f32_16x16x32_bf16 v[36:39], v[130:133], v[142:145], v[36:39]
	v_mfma_f32_16x16x32_bf16 v[40:43], v[130:133], v[148:151], v[40:43]
	v_mfma_f32_16x16x32_bf16 v[44:47], v[130:133], v[154:157], v[44:47]
	s_waitcnt lgkmcnt(8)
	v_mfma_f32_16x16x32_bf16 v[48:51], v[134:137], v[138:141], v[48:51]
	v_mfma_f32_16x16x32_bf16 v[52:55], v[134:137], v[142:145], v[52:55]
	v_mfma_f32_16x16x32_bf16 v[56:59], v[134:137], v[148:151], v[56:59]
	v_mfma_f32_16x16x32_bf16 v[60:63], v[134:137], v[154:157], v[60:63]
	s_waitcnt lgkmcnt(6)
	v_mfma_f32_16x16x32_bf16 v[0:3], v[158:161], v[166:169], v[0:3]
	s_waitcnt vmcnt(0)
	ds_write_b128 v124, v[178:181] offset:32768
	s_waitcnt lgkmcnt(6)
	v_mfma_f32_16x16x32_bf16 v[4:7], v[158:161], v[170:173], v[4:7]
	ds_write_b128 v124, v[182:185] offset:36864
	s_waitcnt lgkmcnt(6)
	v_mfma_f32_16x16x32_bf16 v[8:11], v[158:161], v[174:177], v[8:11]
	ds_write_b128 v124, v[186:189] offset:40960
	s_waitcnt lgkmcnt(6)
	v_mfma_f32_16x16x32_bf16 v[12:15], v[158:161], v[252:255], v[12:15]
	ds_write_b128 v124, v[190:193] offset:45056
	s_waitcnt lgkmcnt(6)
	v_mfma_f32_16x16x32_bf16 v[16:19], v[162:165], v[166:169], v[16:19]
	ds_write_b128 v124, v[220:223] offset:49152
	v_mfma_f32_16x16x32_bf16 v[20:23], v[162:165], v[170:173], v[20:23]
	ds_write_b128 v124, v[224:227] offset:53248
	v_mfma_f32_16x16x32_bf16 v[24:27], v[162:165], v[174:177], v[24:27]
	ds_write_b128 v124, v[228:231] offset:57344
	v_mfma_f32_16x16x32_bf16 v[28:31], v[162:165], v[252:255], v[28:31]
	ds_write_b128 v124, v[232:235] offset:61440
	s_waitcnt lgkmcnt(9)
	v_mfma_f32_16x16x32_bf16 v[32:35], v[244:247], v[166:169], v[32:35]
	global_load_dwordx4 v[178:181], v115, s[98:99] offset:1792
	v_mfma_f32_16x16x32_bf16 v[36:39], v[244:247], v[170:173], v[36:39]
	global_load_dwordx4 v[182:185], v116, s[98:99] offset:1792
	v_mfma_f32_16x16x32_bf16 v[40:43], v[244:247], v[174:177], v[40:43]
	global_load_dwordx4 v[186:189], v122, s[98:99] offset:1792
	v_mfma_f32_16x16x32_bf16 v[44:47], v[244:247], v[252:255], v[44:47]
	global_load_dwordx4 v[190:193], v123, s[98:99] offset:1792
	s_waitcnt lgkmcnt(8)
	v_mfma_f32_16x16x32_bf16 v[48:51], v[248:251], v[166:169], v[48:51]
	global_load_dwordx4 v[220:223], v115, s[100:101] offset:1792
	v_mfma_f32_16x16x32_bf16 v[52:55], v[248:251], v[170:173], v[52:55]
	global_load_dwordx4 v[224:227], v116, s[100:101] offset:1792
	v_mfma_f32_16x16x32_bf16 v[56:59], v[248:251], v[174:177], v[56:59]
	global_load_dwordx4 v[228:231], v122, s[100:101] offset:1792
	v_mfma_f32_16x16x32_bf16 v[60:63], v[248:251], v[252:255], v[60:63]
	global_load_dwordx4 v[232:235], v123, s[100:101] offset:1792
	s_waitcnt lgkmcnt(0)
	s_barrier
	ds_read_b128 v[118:121], v239 offset:32768
	ds_read_b128 v[138:141], v241 offset:32768
	ds_read_b128 v[142:145], v241 offset:34816
	ds_read_b128 v[148:151], v241 offset:36864
	ds_read_b128 v[154:157], v241 offset:38912
	ds_read_b128 v[126:129], v239 offset:34816
	ds_read_b128 v[130:133], v239 offset:36864
	ds_read_b128 v[134:137], v239 offset:38912
	s_waitcnt lgkmcnt(6)
	v_mfma_f32_16x16x32_bf16 v[0:3], v[118:121], v[138:141], v[0:3]
	ds_read_b128 v[158:161], v240 offset:32768
	s_waitcnt lgkmcnt(6)
	v_mfma_f32_16x16x32_bf16 v[4:7], v[118:121], v[142:145], v[4:7]
	ds_read_b128 v[166:169], v242 offset:32768
	s_waitcnt lgkmcnt(6)
	v_mfma_f32_16x16x32_bf16 v[8:11], v[118:121], v[148:151], v[8:11]
	ds_read_b128 v[170:173], v242 offset:34816
	s_waitcnt lgkmcnt(6)
	v_mfma_f32_16x16x32_bf16 v[12:15], v[118:121], v[154:157], v[12:15]
	ds_read_b128 v[174:177], v242 offset:36864
	s_waitcnt lgkmcnt(6)
	v_mfma_f32_16x16x32_bf16 v[16:19], v[126:129], v[138:141], v[16:19]
	ds_read_b128 v[252:255], v242 offset:38912
	v_mfma_f32_16x16x32_bf16 v[20:23], v[126:129], v[142:145], v[20:23]
	ds_read_b128 v[162:165], v240 offset:34816
	v_mfma_f32_16x16x32_bf16 v[24:27], v[126:129], v[148:151], v[24:27]
	ds_read_b128 v[244:247], v240 offset:36864
	v_mfma_f32_16x16x32_bf16 v[28:31], v[126:129], v[154:157], v[28:31]
	ds_read_b128 v[248:251], v240 offset:38912
	s_waitcnt lgkmcnt(9)
	v_mfma_f32_16x16x32_bf16 v[32:35], v[130:133], v[138:141], v[32:35]
	v_mfma_f32_16x16x32_bf16 v[36:39], v[130:133], v[142:145], v[36:39]
	v_mfma_f32_16x16x32_bf16 v[40:43], v[130:133], v[148:151], v[40:43]
	v_mfma_f32_16x16x32_bf16 v[44:47], v[130:133], v[154:157], v[44:47]
	s_waitcnt lgkmcnt(8)
	v_mfma_f32_16x16x32_bf16 v[48:51], v[134:137], v[138:141], v[48:51]
	v_mfma_f32_16x16x32_bf16 v[52:55], v[134:137], v[142:145], v[52:55]
	v_mfma_f32_16x16x32_bf16 v[56:59], v[134:137], v[148:151], v[56:59]
	v_mfma_f32_16x16x32_bf16 v[60:63], v[134:137], v[154:157], v[60:63]
	s_waitcnt lgkmcnt(6)
	v_mfma_f32_16x16x32_bf16 v[0:3], v[158:161], v[166:169], v[0:3]
	s_waitcnt vmcnt(0)
	ds_write_b128 v124, v[178:181]
	s_waitcnt lgkmcnt(6)
	v_mfma_f32_16x16x32_bf16 v[4:7], v[158:161], v[170:173], v[4:7]
	ds_write_b128 v124, v[182:185] offset:4096
	s_waitcnt lgkmcnt(6)
	v_mfma_f32_16x16x32_bf16 v[8:11], v[158:161], v[174:177], v[8:11]
	ds_write_b128 v124, v[186:189] offset:8192
	s_waitcnt lgkmcnt(6)
	v_mfma_f32_16x16x32_bf16 v[12:15], v[158:161], v[252:255], v[12:15]
	ds_write_b128 v124, v[190:193] offset:12288
	s_waitcnt lgkmcnt(6)
	v_mfma_f32_16x16x32_bf16 v[16:19], v[162:165], v[166:169], v[16:19]
	ds_write_b128 v124, v[220:223] offset:16384
	v_mfma_f32_16x16x32_bf16 v[20:23], v[162:165], v[170:173], v[20:23]
	ds_write_b128 v124, v[224:227] offset:20480
	v_mfma_f32_16x16x32_bf16 v[24:27], v[162:165], v[174:177], v[24:27]
	ds_write_b128 v124, v[228:231] offset:24576
	v_mfma_f32_16x16x32_bf16 v[28:31], v[162:165], v[252:255], v[28:31]
	ds_write_b128 v124, v[232:235] offset:28672
	s_waitcnt lgkmcnt(9)
	v_mfma_f32_16x16x32_bf16 v[32:35], v[244:247], v[166:169], v[32:35]
	global_load_dwordx4 v[178:181], v115, s[98:99] offset:1920
	v_mfma_f32_16x16x32_bf16 v[36:39], v[244:247], v[170:173], v[36:39]
	global_load_dwordx4 v[182:185], v116, s[98:99] offset:1920
	v_mfma_f32_16x16x32_bf16 v[40:43], v[244:247], v[174:177], v[40:43]
	global_load_dwordx4 v[186:189], v122, s[98:99] offset:1920
	v_mfma_f32_16x16x32_bf16 v[44:47], v[244:247], v[252:255], v[44:47]
	global_load_dwordx4 v[190:193], v123, s[98:99] offset:1920
	s_waitcnt lgkmcnt(8)
	v_mfma_f32_16x16x32_bf16 v[48:51], v[248:251], v[166:169], v[48:51]
	global_load_dwordx4 v[220:223], v115, s[100:101] offset:1920
	v_mfma_f32_16x16x32_bf16 v[52:55], v[248:251], v[170:173], v[52:55]
	global_load_dwordx4 v[224:227], v116, s[100:101] offset:1920
	v_mfma_f32_16x16x32_bf16 v[56:59], v[248:251], v[174:177], v[56:59]
	global_load_dwordx4 v[228:231], v122, s[100:101] offset:1920
	v_mfma_f32_16x16x32_bf16 v[60:63], v[248:251], v[252:255], v[60:63]
	global_load_dwordx4 v[232:235], v123, s[100:101] offset:1920
	s_waitcnt lgkmcnt(0)
	s_barrier
	ds_read_b128 v[118:121], v239
	ds_read_b128 v[138:141], v241
	ds_read_b128 v[142:145], v241 offset:2048
	ds_read_b128 v[148:151], v241 offset:4096
	ds_read_b128 v[154:157], v241 offset:6144
	ds_read_b128 v[126:129], v239 offset:2048
	ds_read_b128 v[130:133], v239 offset:4096
	ds_read_b128 v[134:137], v239 offset:6144
	s_waitcnt lgkmcnt(6)
	v_mfma_f32_16x16x32_bf16 v[0:3], v[118:121], v[138:141], v[0:3]
	ds_read_b128 v[158:161], v240
	s_waitcnt lgkmcnt(6)
	v_mfma_f32_16x16x32_bf16 v[4:7], v[118:121], v[142:145], v[4:7]
	ds_read_b128 v[166:169], v242
	s_waitcnt lgkmcnt(6)
	v_mfma_f32_16x16x32_bf16 v[8:11], v[118:121], v[148:151], v[8:11]
	ds_read_b128 v[170:173], v242 offset:2048
	s_waitcnt lgkmcnt(6)
	v_mfma_f32_16x16x32_bf16 v[12:15], v[118:121], v[154:157], v[12:15]
	ds_read_b128 v[174:177], v242 offset:4096
	s_waitcnt lgkmcnt(6)
	v_mfma_f32_16x16x32_bf16 v[16:19], v[126:129], v[138:141], v[16:19]
	ds_read_b128 v[252:255], v242 offset:6144
	v_mfma_f32_16x16x32_bf16 v[20:23], v[126:129], v[142:145], v[20:23]
	ds_read_b128 v[162:165], v240 offset:2048
	v_mfma_f32_16x16x32_bf16 v[24:27], v[126:129], v[148:151], v[24:27]
	ds_read_b128 v[244:247], v240 offset:4096
	v_mfma_f32_16x16x32_bf16 v[28:31], v[126:129], v[154:157], v[28:31]
	ds_read_b128 v[248:251], v240 offset:6144
	s_waitcnt lgkmcnt(9)
	v_mfma_f32_16x16x32_bf16 v[32:35], v[130:133], v[138:141], v[32:35]
	v_mfma_f32_16x16x32_bf16 v[36:39], v[130:133], v[142:145], v[36:39]
	v_mfma_f32_16x16x32_bf16 v[40:43], v[130:133], v[148:151], v[40:43]
	v_mfma_f32_16x16x32_bf16 v[44:47], v[130:133], v[154:157], v[44:47]
	s_waitcnt lgkmcnt(8)
	v_mfma_f32_16x16x32_bf16 v[48:51], v[134:137], v[138:141], v[48:51]
	v_mfma_f32_16x16x32_bf16 v[52:55], v[134:137], v[142:145], v[52:55]
	v_mfma_f32_16x16x32_bf16 v[56:59], v[134:137], v[148:151], v[56:59]
	v_mfma_f32_16x16x32_bf16 v[60:63], v[134:137], v[154:157], v[60:63]
	s_waitcnt lgkmcnt(6)
	v_mfma_f32_16x16x32_bf16 v[0:3], v[158:161], v[166:169], v[0:3]
	s_waitcnt vmcnt(0)
	ds_write_b128 v124, v[178:181] offset:32768
	s_waitcnt lgkmcnt(6)
	v_mfma_f32_16x16x32_bf16 v[4:7], v[158:161], v[170:173], v[4:7]
	ds_write_b128 v124, v[182:185] offset:36864
	s_waitcnt lgkmcnt(6)
	v_mfma_f32_16x16x32_bf16 v[8:11], v[158:161], v[174:177], v[8:11]
	ds_write_b128 v124, v[186:189] offset:40960
	s_waitcnt lgkmcnt(6)
	v_mfma_f32_16x16x32_bf16 v[12:15], v[158:161], v[252:255], v[12:15]
	ds_write_b128 v124, v[190:193] offset:45056
	s_waitcnt lgkmcnt(6)
	v_mfma_f32_16x16x32_bf16 v[16:19], v[162:165], v[166:169], v[16:19]
	ds_write_b128 v124, v[220:223] offset:49152
	v_mfma_f32_16x16x32_bf16 v[20:23], v[162:165], v[170:173], v[20:23]
	ds_write_b128 v124, v[224:227] offset:53248
	v_mfma_f32_16x16x32_bf16 v[24:27], v[162:165], v[174:177], v[24:27]
	ds_write_b128 v124, v[228:231] offset:57344
	v_mfma_f32_16x16x32_bf16 v[28:31], v[162:165], v[252:255], v[28:31]
	ds_write_b128 v124, v[232:235] offset:61440
	s_waitcnt lgkmcnt(9)
	v_mfma_f32_16x16x32_bf16 v[32:35], v[244:247], v[166:169], v[32:35]
	v_mfma_f32_16x16x32_bf16 v[36:39], v[244:247], v[170:173], v[36:39]
	v_mfma_f32_16x16x32_bf16 v[40:43], v[244:247], v[174:177], v[40:43]
	v_mfma_f32_16x16x32_bf16 v[44:47], v[244:247], v[252:255], v[44:47]
	s_waitcnt lgkmcnt(8)
	v_mfma_f32_16x16x32_bf16 v[48:51], v[248:251], v[166:169], v[48:51]
	v_mfma_f32_16x16x32_bf16 v[52:55], v[248:251], v[170:173], v[52:55]
	v_mfma_f32_16x16x32_bf16 v[56:59], v[248:251], v[174:177], v[56:59]
	v_mfma_f32_16x16x32_bf16 v[60:63], v[248:251], v[252:255], v[60:63]
	s_waitcnt lgkmcnt(0)
	s_barrier
	ds_read_b128 v[118:121], v239 offset:32768
	ds_read_b128 v[138:141], v241 offset:32768
	ds_read_b128 v[142:145], v241 offset:34816
	ds_read_b128 v[148:151], v241 offset:36864
	ds_read_b128 v[154:157], v241 offset:38912
	ds_read_b128 v[126:129], v239 offset:34816
	ds_read_b128 v[130:133], v239 offset:36864
	ds_read_b128 v[134:137], v239 offset:38912
	s_waitcnt lgkmcnt(6)
	v_mfma_f32_16x16x32_bf16 v[0:3], v[118:121], v[138:141], v[0:3]
	ds_read_b128 v[158:161], v240 offset:32768
	s_waitcnt lgkmcnt(6)
	v_mfma_f32_16x16x32_bf16 v[4:7], v[118:121], v[142:145], v[4:7]
	ds_read_b128 v[166:169], v242 offset:32768
	s_waitcnt lgkmcnt(6)
	v_mfma_f32_16x16x32_bf16 v[8:11], v[118:121], v[148:151], v[8:11]
	ds_read_b128 v[170:173], v242 offset:34816
	s_waitcnt lgkmcnt(6)
	v_mfma_f32_16x16x32_bf16 v[12:15], v[118:121], v[154:157], v[12:15]
	ds_read_b128 v[174:177], v242 offset:36864
	s_waitcnt lgkmcnt(6)
	v_mfma_f32_16x16x32_bf16 v[16:19], v[126:129], v[138:141], v[16:19]
	ds_read_b128 v[252:255], v242 offset:38912
	v_mfma_f32_16x16x32_bf16 v[20:23], v[126:129], v[142:145], v[20:23]
	ds_read_b128 v[162:165], v240 offset:34816
	v_mfma_f32_16x16x32_bf16 v[24:27], v[126:129], v[148:151], v[24:27]
	ds_read_b128 v[244:247], v240 offset:36864
	v_mfma_f32_16x16x32_bf16 v[28:31], v[126:129], v[154:157], v[28:31]
	ds_read_b128 v[248:251], v240 offset:38912
	s_waitcnt lgkmcnt(9)
	v_mfma_f32_16x16x32_bf16 v[32:35], v[130:133], v[138:141], v[32:35]
	v_mfma_f32_16x16x32_bf16 v[36:39], v[130:133], v[142:145], v[36:39]
	v_mfma_f32_16x16x32_bf16 v[40:43], v[130:133], v[148:151], v[40:43]
	v_mfma_f32_16x16x32_bf16 v[44:47], v[130:133], v[154:157], v[44:47]
	s_waitcnt lgkmcnt(8)
	v_mfma_f32_16x16x32_bf16 v[48:51], v[134:137], v[138:141], v[48:51]
	v_mfma_f32_16x16x32_bf16 v[52:55], v[134:137], v[142:145], v[52:55]
	v_mfma_f32_16x16x32_bf16 v[56:59], v[134:137], v[148:151], v[56:59]
	v_mfma_f32_16x16x32_bf16 v[60:63], v[134:137], v[154:157], v[60:63]
	s_waitcnt lgkmcnt(6)
	v_mfma_f32_16x16x32_bf16 v[0:3], v[158:161], v[166:169], v[0:3]
	s_waitcnt lgkmcnt(5)
	v_mfma_f32_16x16x32_bf16 v[4:7], v[158:161], v[170:173], v[4:7]
	s_waitcnt lgkmcnt(4)
	v_mfma_f32_16x16x32_bf16 v[8:11], v[158:161], v[174:177], v[8:11]
	s_waitcnt lgkmcnt(3)
	v_mfma_f32_16x16x32_bf16 v[12:15], v[158:161], v[252:255], v[12:15]
	s_waitcnt lgkmcnt(2)
	v_mfma_f32_16x16x32_bf16 v[16:19], v[162:165], v[166:169], v[16:19]
	v_mfma_f32_16x16x32_bf16 v[20:23], v[162:165], v[170:173], v[20:23]
	v_mfma_f32_16x16x32_bf16 v[24:27], v[162:165], v[174:177], v[24:27]
	v_mfma_f32_16x16x32_bf16 v[28:31], v[162:165], v[252:255], v[28:31]
	s_waitcnt lgkmcnt(1)
	v_mfma_f32_16x16x32_bf16 v[32:35], v[244:247], v[166:169], v[32:35]
	v_mfma_f32_16x16x32_bf16 v[36:39], v[244:247], v[170:173], v[36:39]
	v_mfma_f32_16x16x32_bf16 v[40:43], v[244:247], v[174:177], v[40:43]
	v_mfma_f32_16x16x32_bf16 v[44:47], v[244:247], v[252:255], v[44:47]
	s_waitcnt lgkmcnt(0)
	v_mfma_f32_16x16x32_bf16 v[48:51], v[248:251], v[166:169], v[48:51]
	v_mfma_f32_16x16x32_bf16 v[52:55], v[248:251], v[170:173], v[52:55]
	v_mfma_f32_16x16x32_bf16 v[56:59], v[248:251], v[174:177], v[56:59]
	v_mfma_f32_16x16x32_bf16 v[60:63], v[248:251], v[252:255], v[60:63]
	s_waitcnt lgkmcnt(0)
	s_barrier
	s_nop 15
	ds_write_b32 v243, v0
	ds_write_b32 v243, v1 offset:528
	ds_write_b32 v243, v2 offset:1056
	ds_write_b32 v243, v3 offset:1584
	ds_write_b32 v243, v4 offset:64
	ds_write_b32 v243, v5 offset:592
	ds_write_b32 v243, v6 offset:1120
	ds_write_b32 v243, v7 offset:1648
	ds_write_b32 v243, v8 offset:128
	ds_write_b32 v243, v9 offset:656
	ds_write_b32 v243, v10 offset:1184
	ds_write_b32 v243, v11 offset:1712
	ds_write_b32 v243, v12 offset:192
	ds_write_b32 v243, v13 offset:720
	ds_write_b32 v243, v14 offset:1248
	ds_write_b32 v243, v15 offset:1776
	ds_write_b32 v243, v16 offset:8448
	ds_write_b32 v243, v17 offset:8976
	ds_write_b32 v243, v18 offset:9504
	ds_write_b32 v243, v19 offset:10032
	ds_write_b32 v243, v20 offset:8512
	ds_write_b32 v243, v21 offset:9040
	ds_write_b32 v243, v22 offset:9568
	ds_write_b32 v243, v23 offset:10096
	ds_write_b32 v243, v24 offset:8576
	ds_write_b32 v243, v25 offset:9104
	ds_write_b32 v243, v26 offset:9632
	ds_write_b32 v243, v27 offset:10160
	ds_write_b32 v243, v28 offset:8640
	ds_write_b32 v243, v29 offset:9168
	ds_write_b32 v243, v30 offset:9696
	ds_write_b32 v243, v31 offset:10224
	ds_write_b32 v243, v32 offset:16896
	ds_write_b32 v243, v33 offset:17424
	ds_write_b32 v243, v34 offset:17952
	ds_write_b32 v243, v35 offset:18480
	ds_write_b32 v243, v36 offset:16960
	ds_write_b32 v243, v37 offset:17488
	ds_write_b32 v243, v38 offset:18016
	ds_write_b32 v243, v39 offset:18544
	ds_write_b32 v243, v40 offset:17024
	ds_write_b32 v243, v41 offset:17552
	ds_write_b32 v243, v42 offset:18080
	ds_write_b32 v243, v43 offset:18608
	ds_write_b32 v243, v44 offset:17088
	ds_write_b32 v243, v45 offset:17616
	ds_write_b32 v243, v46 offset:18144
	ds_write_b32 v243, v47 offset:18672
	ds_write_b32 v243, v48 offset:25344
	ds_write_b32 v243, v49 offset:25872
	ds_write_b32 v243, v50 offset:26400
	ds_write_b32 v243, v51 offset:26928
	ds_write_b32 v243, v52 offset:25408
	ds_write_b32 v243, v53 offset:25936
	ds_write_b32 v243, v54 offset:26464
	ds_write_b32 v243, v55 offset:26992
	ds_write_b32 v243, v56 offset:25472
	ds_write_b32 v243, v57 offset:26000
	ds_write_b32 v243, v58 offset:26528
	ds_write_b32 v243, v59 offset:27056
	ds_write_b32 v243, v60 offset:25536
	ds_write_b32 v243, v61 offset:26064
	ds_write_b32 v243, v62 offset:26592
	ds_write_b32 v243, v63 offset:27120
	v_or_b32_e32 v4, s20, v147
	v_or_b32_e32 v0, s10, v82
	v_ashrrev_i32_e32 v5, 31, v4
	v_ashrrev_i32_e32 v1, 31, v0
	v_cmp_gt_i32_e32 vcc, s17, v4
	v_lshlrev_b64 v[4:5], 11, v[4:5]
	v_lshlrev_b64 v[2:3], 1, v[0:1]
	v_lshl_add_u64 v[4:5], s[24:25], 0, v[4:5]
	v_lshl_add_u64 v[0:1], s[24:25], 0, v[2:3]
	v_lshl_add_u64 v[2:3], v[4:5], 0, v[2:3]
	v_lshl_add_u64 v[4:5], v[2:3], 0, s[12:13]
	v_cmp_ge_u64_e64 s[10:11], v[4:5], v[2:3]
	s_and_b64 s[10:11], vcc, s[10:11]
	s_waitcnt lgkmcnt(0)
	s_barrier
	s_and_saveexec_b64 s[14:15], s[10:11]
	s_xor_b64 s[10:11], exec, s[14:15]
	s_cbranch_execz .LBB0_926
	s_mov_b32 s14, s20
	s_mov_b32 s15, 1
	s_mov_b32 s21, 0
	s_mov_b32 s22, 16
